# speedup vs baseline: 1.0031x; 1.0031x over previous
; #define PG8_STAGE(bufoff, gbase, voff) do { _Pragma("unroll") for (int _i = 0; _i < 2; ++_i) \
;         __builtin_amdgcn_global_load_lds((const unsigned*)((const char*)(gbase) + (voff)[_i]), (PG8_LAS unsigned*)(lds + (bufoff) + ldsw + _i * 8192), 16, 0, 0); } while (0)
; #define PG8_LDA(dst, b, h) do { _Pragma("unroll") for (int m = 0; m < 4; ++m) _Pragma("unroll") for (int k = 0; k < 2; ++k) dst[m][k] = *(const PG8_LAS bf16x8*)(lds + PG8_SA(b, h) + aoff + m * 2048 + k * 1024); } while (0)
; #define PG8_LDB(dst, b, h) do { _Pragma("unroll") for (int n = 0; n < 2; ++n) _Pragma("unroll") for (int k = 0; k < 2; ++k) dst[n][k] = *(const PG8_LAS bf16x8*)(lds + PG8_SB(b, h) + boff + n * 2048 + k * 1024); } while (0)
; #define PG8_WAIT_V(n) asm volatile("s_waitcnt vmcnt(" #n ")" ::: "memory")
; #define PG8_WAIT_L(n) asm volatile("s_waitcnt lgkmcnt(" #n ")" ::: "memory")
; #define PG8_BAR __builtin_amdgcn_s_barrier()
; #define PG8_SCHED __builtin_amdgcn_sched_barrier(0)
; template <class Epi, class Sched, bool ALIGN_EPI = false, bool SP2 = false>
; __device__ __forceinline__ void gemm_phase(PG8_LAS unsigned char* lds, const Gemm g, const Sched& S, const Epi& E, const int tid) {
;     ...
;         const bool has_next = S.next(ui + 1, nxt);
;         const char* nA = has_next ? (const char*)g.A + (size_t)nxt.pm * tstep : cA; const char* nB = has_next ? (const char*)g.Bt + (size_t)nxt.pn * tstep : cB;
;         for (int t = 0; t < nt; t += 2) {
;             const bool last = (t == nt - 2);
;             const char* a1 = cA + (size_t)(t + 1) * kstep;
;             const char* a2 = last ? nA : cA + (size_t)(t + 2) * kstep; const char* b2 = last ? nB : cB + (size_t)(t + 2) * kstep;
;             const char* a3 = a2 + kstep; const char* b3 = b2 + kstep;
;             if (last && has_next) S.a_ready(nxt);
;             if constexpr (SP2) {
;             PG8_LDB(B0, 0, 0); PG8_LDB(B1, 0, 1); PG8_SCHED; PG8_LDA(At, 0, 0); PG8_STAGE(PG8_SA(1, 1), a1 + hstep, voffA);
;             PG8_WAIT_V(8); PG8_WAIT_L(0); PG8_BAR; PG8_MMA(0, 0, At, B0); PG8_MMA(0, 1, At, B1); PG8_BAR; PG8_SCHED;
;             PG8_LDA(At, 0, 1); PG8_STAGE(PG8_SB(0, 0), b2, voffB); PG8_STAGE(PG8_SB(0, 1), b2 + hstep, voffB); PG8_STAGE(PG8_SA(0, 0), a2, voffA);
;             PG8_WAIT_V(8); PG8_WAIT_L(0); PG8_BAR; PG8_MMA(1, 0, At, B0); PG8_MMA(1, 1, At, B1); PG8_BAR; PG8_SCHED;
.LBB0_59:
	s_add_u32 s26, s26, 0x80
	s_addc_u32 s27, s27, 0
	s_add_u32 s36, s30, 0x100
	s_addc_u32 s37, s31, 0
	s_mov_b32 s30, 0
	s_add_i32 s44, s30, 2
	s_add_u32 s45, s26, 0x80
	s_addc_u32 s31, s27, 0
	s_add_i32 s63, 0, 0x10000
	s_cmp_eq_u32 s58, s30
	s_cselect_b32 s31, s21, s31
	s_cselect_b32 s30, s20, s45
	s_cselect_b32 s65, s23, s37
	s_cselect_b32 s64, s22, s36
	s_add_i32 s45, 0, 0x14000
	v_add_u32_e32 v154, s63, v143
	v_add_u32_e32 v158, s45, v143
	ds_read_b128 v[138:141], v154
	ds_read_b128 v[146:149], v154 offset:1024
	ds_read_b128 v[150:153], v154 offset:2048
	ds_read_b128 v[154:157], v154 offset:3072
	ds_read_b128 v[162:165], v158
	ds_read_b128 v[166:169], v158 offset:1024
	ds_read_b128 v[170:173], v158 offset:2048
	ds_read_b128 v[184:187], v158 offset:3072
	v_lshl_add_u64 v[158:159], s[26:27], 0, v[134:135]
	s_add_i32 m0, s47, 0xc000
	ds_read_b128 v[188:191], v145
	ds_read_b128 v[192:195], v145 offset:1024
	ds_read_b128 v[208:211], v145 offset:2048
	ds_read_b128 v[214:217], v145 offset:3072
	ds_read_b128 v[218:221], v145 offset:4096
	ds_read_b128 v[222:225], v145 offset:5120
	ds_read_b128 v[226:229], v145 offset:6144
	ds_read_b128 v[230:233], v145 offset:7168
	global_load_lds_dwordx4 v[158:159], off
	v_lshl_add_u64 v[158:159], s[26:27], 0, v[136:137]
	s_add_i32 m0, s47, 0xe000
	s_nop 0
	global_load_lds_dwordx4 v[158:159], off
	s_waitcnt vmcnt(24)
	s_waitcnt lgkmcnt(0)
	s_setprio 1
	s_barrier
	v_mfma_f32_16x16x32_bf16 v[124:127], v[138:141], v[188:191], 0
	v_mfma_f32_16x16x32_bf16 v[120:123], v[150:153], v[188:191], 0
	v_mfma_f32_16x16x32_bf16 v[108:111], v[138:141], v[208:211], 0
	v_mfma_f32_16x16x32_bf16 v[104:107], v[150:153], v[208:211], 0
	v_mfma_f32_16x16x32_bf16 v[92:95], v[138:141], v[218:221], 0
	v_mfma_f32_16x16x32_bf16 v[88:91], v[150:153], v[218:221], 0
	v_mfma_f32_16x16x32_bf16 v[76:79], v[138:141], v[226:229], 0
	v_mfma_f32_16x16x32_bf16 v[72:75], v[150:153], v[226:229], 0
	v_mfma_f32_16x16x32_bf16 v[124:127], v[146:149], v[192:195], v[124:127]
	v_mfma_f32_16x16x32_bf16 v[120:123], v[154:157], v[192:195], v[120:123]
	v_mfma_f32_16x16x32_bf16 v[108:111], v[146:149], v[214:217], v[108:111]
	v_mfma_f32_16x16x32_bf16 v[104:107], v[154:157], v[214:217], v[104:107]
	v_mfma_f32_16x16x32_bf16 v[92:95], v[146:149], v[222:225], v[92:95]
	v_mfma_f32_16x16x32_bf16 v[88:91], v[154:157], v[222:225], v[88:91]
	v_mfma_f32_16x16x32_bf16 v[76:79], v[146:149], v[230:233], v[76:79]
	v_mfma_f32_16x16x32_bf16 v[72:75], v[154:157], v[230:233], v[72:75]
	s_setprio 0
	s_setprio 1
	v_mfma_f32_16x16x32_bf16 v[116:119], v[162:165], v[188:191], 0
	v_mfma_f32_16x16x32_bf16 v[112:115], v[170:173], v[188:191], 0
	v_mfma_f32_16x16x32_bf16 v[100:103], v[162:165], v[208:211], 0
	v_mfma_f32_16x16x32_bf16 v[96:99], v[170:173], v[208:211], 0
	v_mfma_f32_16x16x32_bf16 v[84:87], v[162:165], v[218:221], 0
	v_mfma_f32_16x16x32_bf16 v[80:83], v[170:173], v[218:221], 0
	v_mfma_f32_16x16x32_bf16 v[68:71], v[162:165], v[226:229], 0
	v_mfma_f32_16x16x32_bf16 v[64:67], v[170:173], v[226:229], 0
	v_mfma_f32_16x16x32_bf16 v[116:119], v[166:169], v[192:195], v[116:119]
	v_mfma_f32_16x16x32_bf16 v[112:115], v[184:187], v[192:195], v[112:115]
	v_mfma_f32_16x16x32_bf16 v[100:103], v[166:169], v[214:217], v[100:103]
	v_mfma_f32_16x16x32_bf16 v[96:99], v[184:187], v[214:217], v[96:99]
	v_mfma_f32_16x16x32_bf16 v[84:87], v[166:169], v[222:225], v[84:87]
	v_mfma_f32_16x16x32_bf16 v[80:83], v[184:187], v[222:225], v[80:83]
	v_mfma_f32_16x16x32_bf16 v[68:71], v[166:169], v[230:233], v[68:71]
	v_mfma_f32_16x16x32_bf16 v[64:67], v[184:187], v[230:233], v[64:67]
	s_setprio 0
	s_barrier
	s_add_i32 s63, s63, s46
	v_lshl_add_u64 v[158:159], s[64:65], 0, v[160:161]
	s_mov_b32 m0, s63
	ds_read_b128 v[188:191], v145 offset:16384
	ds_read_b128 v[192:195], v145 offset:17408
	ds_read_b128 v[208:211], v145 offset:18432
	ds_read_b128 v[214:217], v145 offset:19456
	ds_read_b128 v[218:221], v145 offset:20480
	ds_read_b128 v[222:225], v145 offset:21504
	ds_read_b128 v[226:229], v145 offset:22528
	ds_read_b128 v[230:233], v145 offset:23552
	global_load_lds_dwordx4 v[158:159], off
	s_add_i32 m0, s63, 0x2000
	v_lshl_add_u64 v[174:175], s[64:65], 0, v[132:133]
	s_add_u32 s64, s64, s12
	s_addc_u32 s65, s65, 0
	s_add_i32 s45, s45, s46
	global_load_lds_dwordx4 v[174:175], off
	v_lshl_add_u64 v[178:179], s[64:65], 0, v[160:161]
	s_mov_b32 m0, s45
	v_lshl_add_u64 v[180:181], s[64:65], 0, v[132:133]
	global_load_lds_dwordx4 v[178:179], off
	s_add_i32 m0, s45, 0x2000
	v_lshl_add_u64 v[196:197], s[30:31], 0, v[128:129]
	global_load_lds_dwordx4 v[180:181], off
	s_mov_b32 m0, s47
	v_lshl_add_u64 v[198:199], s[30:31], 0, v[130:131]
	global_load_lds_dwordx4 v[196:197], off
	s_mov_b32 m0, s48
	s_nop 0
	global_load_lds_dwordx4 v[198:199], off
	s_cmp_lt_u32 s59, 2
	s_cbranch_scc1 .Lmy_w8_0
	s_waitcnt vmcnt(24)
	s_branch .Lmy_wj_0

; #define PG8_STAGE(bufoff, gbase, voff) do { _Pragma("unroll") for (int _i = 0; _i < 2; ++_i) \
;         __builtin_amdgcn_global_load_lds((const unsigned*)((const char*)(gbase) + (voff)[_i]), (PG8_LAS unsigned*)(lds + (bufoff) + ldsw + _i * 8192), 16, 0, 0); } while (0)
; #define PG8_LDA(dst, b, h) do { _Pragma("unroll") for (int m = 0; m < 4; ++m) _Pragma("unroll") for (int k = 0; k < 2; ++k) dst[m][k] = *(const PG8_LAS bf16x8*)(lds + PG8_SA(b, h) + aoff + m * 2048 + k * 1024); } while (0)
; #define PG8_LDB(dst, b, h) do { _Pragma("unroll") for (int n = 0; n < 2; ++n) _Pragma("unroll") for (int k = 0; k < 2; ++k) dst[n][k] = *(const PG8_LAS bf16x8*)(lds + PG8_SB(b, h) + boff + n * 2048 + k * 1024); } while (0)
; #define PG8_MMA(ai, bj, At, Bt) do { __builtin_amdgcn_s_setprio(1); _Pragma("unroll") for (int m = 0; m < 4; ++m) _Pragma("unroll") for (int n = 0; n < 2; ++n) _Pragma("unroll") for (int k = 0; k < 2; ++k) \
;         acc[ai][bj][m][n] = __builtin_amdgcn_mfma_f32_16x16x32_bf16(Bt[n][k], At[m][k], acc[ai][bj][m][n], 0, 0, 0); __builtin_amdgcn_s_setprio(0); } while (0)
; #define PG8_WAIT_V(n) asm volatile("s_waitcnt vmcnt(" #n ")" ::: "memory")
; #define PG8_WAIT_L(n) asm volatile("s_waitcnt lgkmcnt(" #n ")" ::: "memory")
; #define PG8_BAR __builtin_amdgcn_s_barrier()
; #define PG8_SCHED __builtin_amdgcn_sched_barrier(0)
; template <class Epi, class Sched, bool ALIGN_EPI = false, bool SP2 = false>
; __device__ __forceinline__ void gemm_phase(PG8_LAS unsigned char* lds, const Gemm g, const Sched& S, const Epi& E, const int tid) {
;     ...
;             PG8_WAIT_V(8); PG8_WAIT_L(0); PG8_BAR; PG8_MMA(1, 0, At, B0); PG8_MMA(1, 1, At, B1); PG8_BAR; PG8_SCHED;
;             PG8_LDB(B0, 1, 0); PG8_LDB(B1, 1, 1); PG8_SCHED; PG8_LDA(At, 1, 0); PG8_STAGE(PG8_SA(0, 1), a2 + hstep, voffA);
;             PG8_WAIT_V(8); PG8_WAIT_L(0); PG8_BAR; PG8_MMA(0, 0, At, B0); PG8_MMA(0, 1, At, B1); PG8_BAR; PG8_SCHED;
.Lmy_wj_0:
	s_waitcnt lgkmcnt(0)
	s_setprio 1
	s_barrier
	v_mfma_f32_16x16x32_bf16 v[60:63], v[138:141], v[188:191], 0
	v_mfma_f32_16x16x32_bf16 v[56:59], v[150:153], v[188:191], 0
	v_mfma_f32_16x16x32_bf16 v[44:47], v[138:141], v[208:211], 0
	v_mfma_f32_16x16x32_bf16 v[40:43], v[150:153], v[208:211], 0
	v_mfma_f32_16x16x32_bf16 v[28:31], v[138:141], v[218:221], 0
	v_mfma_f32_16x16x32_bf16 v[24:27], v[150:153], v[218:221], 0
	v_mfma_f32_16x16x32_bf16 v[12:15], v[138:141], v[226:229], 0
	v_mfma_f32_16x16x32_bf16 v[8:11], v[150:153], v[226:229], 0
	v_mfma_f32_16x16x32_bf16 v[60:63], v[146:149], v[192:195], v[60:63]
	v_mfma_f32_16x16x32_bf16 v[56:59], v[154:157], v[192:195], v[56:59]
	v_mfma_f32_16x16x32_bf16 v[44:47], v[146:149], v[214:217], v[44:47]
	v_mfma_f32_16x16x32_bf16 v[40:43], v[154:157], v[214:217], v[40:43]
	v_mfma_f32_16x16x32_bf16 v[28:31], v[146:149], v[222:225], v[28:31]
	v_mfma_f32_16x16x32_bf16 v[24:27], v[154:157], v[222:225], v[24:27]
	v_mfma_f32_16x16x32_bf16 v[12:15], v[146:149], v[230:233], v[12:15]
	v_mfma_f32_16x16x32_bf16 v[8:11], v[154:157], v[230:233], v[8:11]
	s_setprio 0
	s_setprio 1
	v_mfma_f32_16x16x32_bf16 v[52:55], v[162:165], v[188:191], 0
	v_mfma_f32_16x16x32_bf16 v[48:51], v[170:173], v[188:191], 0
	v_mfma_f32_16x16x32_bf16 v[36:39], v[162:165], v[208:211], 0
	v_mfma_f32_16x16x32_bf16 v[32:35], v[170:173], v[208:211], 0
	v_mfma_f32_16x16x32_bf16 v[20:23], v[162:165], v[218:221], 0
	v_mfma_f32_16x16x32_bf16 v[16:19], v[170:173], v[218:221], 0
	v_mfma_f32_16x16x32_bf16 v[4:7], v[162:165], v[226:229], 0
	v_mfma_f32_16x16x32_bf16 v[0:3], v[170:173], v[226:229], 0
	v_mfma_f32_16x16x32_bf16 v[52:55], v[166:169], v[192:195], v[52:55]
	v_mfma_f32_16x16x32_bf16 v[48:51], v[184:187], v[192:195], v[48:51]
	v_mfma_f32_16x16x32_bf16 v[36:39], v[166:169], v[214:217], v[36:39]
	v_mfma_f32_16x16x32_bf16 v[32:35], v[184:187], v[214:217], v[32:35]
	v_mfma_f32_16x16x32_bf16 v[20:23], v[166:169], v[222:225], v[20:23]
	v_mfma_f32_16x16x32_bf16 v[16:19], v[184:187], v[222:225], v[16:19]
	v_mfma_f32_16x16x32_bf16 v[4:7], v[166:169], v[230:233], v[4:7]
	v_mfma_f32_16x16x32_bf16 v[0:3], v[184:187], v[230:233], v[0:3]
	s_setprio 0
	s_barrier
	s_add_i32 s45, 0, 0x18000
	s_add_i32 s63, 0, 0x1c000
	v_add_u32_e32 v154, s45, v143
	v_add_u32_e32 v183, s63, v143
	ds_read_b128 v[138:141], v154
	ds_read_b128 v[146:149], v154 offset:1024
	ds_read_b128 v[150:153], v154 offset:2048
	ds_read_b128 v[154:157], v154 offset:3072
	ds_read_b128 v[162:165], v183
	ds_read_b128 v[166:169], v183 offset:1024
	ds_read_b128 v[170:173], v183 offset:2048
	ds_read_b128 v[184:187], v183 offset:3072
	s_add_u32 s30, s30, s12
	s_addc_u32 s31, s31, 0
	s_mov_b32 m0, s49
	v_lshl_add_u64 v[204:205], s[30:31], 0, v[128:129]
	ds_read_b128 v[188:191], v145 offset:32768
	ds_read_b128 v[192:195], v145 offset:33792
	ds_read_b128 v[208:211], v145 offset:34816
	ds_read_b128 v[214:217], v145 offset:35840
	ds_read_b128 v[218:221], v145 offset:36864
	ds_read_b128 v[222:225], v145 offset:37888
	ds_read_b128 v[226:229], v145 offset:38912
	ds_read_b128 v[230:233], v145 offset:39936
	global_load_lds_dwordx4 v[204:205], off
	v_lshl_add_u64 v[204:205], s[30:31], 0, v[130:131]
	s_mov_b32 m0, s50
	s_nop 0
	global_load_lds_dwordx4 v[204:205], off
	s_waitcnt vmcnt(8)
	s_waitcnt lgkmcnt(0)
	s_setprio 1
	s_barrier
	v_mfma_f32_16x16x32_bf16 v[124:127], v[138:141], v[188:191], v[124:127]
	v_mfma_f32_16x16x32_bf16 v[120:123], v[150:153], v[188:191], v[120:123]
	v_mfma_f32_16x16x32_bf16 v[108:111], v[138:141], v[208:211], v[108:111]
	v_mfma_f32_16x16x32_bf16 v[104:107], v[150:153], v[208:211], v[104:107]
	v_mfma_f32_16x16x32_bf16 v[92:95], v[138:141], v[218:221], v[92:95]
	v_mfma_f32_16x16x32_bf16 v[88:91], v[150:153], v[218:221], v[88:91]
	v_mfma_f32_16x16x32_bf16 v[76:79], v[138:141], v[226:229], v[76:79]
	v_mfma_f32_16x16x32_bf16 v[72:75], v[150:153], v[226:229], v[72:75]
	v_mfma_f32_16x16x32_bf16 v[124:127], v[146:149], v[192:195], v[124:127]
	v_mfma_f32_16x16x32_bf16 v[120:123], v[154:157], v[192:195], v[120:123]
	v_mfma_f32_16x16x32_bf16 v[108:111], v[146:149], v[214:217], v[108:111]
	v_mfma_f32_16x16x32_bf16 v[104:107], v[154:157], v[214:217], v[104:107]
	v_mfma_f32_16x16x32_bf16 v[92:95], v[146:149], v[222:225], v[92:95]
	v_mfma_f32_16x16x32_bf16 v[88:91], v[154:157], v[222:225], v[88:91]
	v_mfma_f32_16x16x32_bf16 v[76:79], v[146:149], v[230:233], v[76:79]
	v_mfma_f32_16x16x32_bf16 v[72:75], v[154:157], v[230:233], v[72:75]
	s_setprio 0
	s_setprio 1
	v_mfma_f32_16x16x32_bf16 v[116:119], v[162:165], v[188:191], v[116:119]
	v_mfma_f32_16x16x32_bf16 v[112:115], v[170:173], v[188:191], v[112:115]
	v_mfma_f32_16x16x32_bf16 v[100:103], v[162:165], v[208:211], v[100:103]
	v_mfma_f32_16x16x32_bf16 v[96:99], v[170:173], v[208:211], v[96:99]
	v_mfma_f32_16x16x32_bf16 v[84:87], v[162:165], v[218:221], v[84:87]
	v_mfma_f32_16x16x32_bf16 v[80:83], v[170:173], v[218:221], v[80:83]
	v_mfma_f32_16x16x32_bf16 v[68:71], v[162:165], v[226:229], v[68:71]
	v_mfma_f32_16x16x32_bf16 v[64:67], v[170:173], v[226:229], v[64:67]
	v_mfma_f32_16x16x32_bf16 v[116:119], v[166:169], v[192:195], v[116:119]
	v_mfma_f32_16x16x32_bf16 v[112:115], v[184:187], v[192:195], v[112:115]
	v_mfma_f32_16x16x32_bf16 v[100:103], v[166:169], v[214:217], v[100:103]
	v_mfma_f32_16x16x32_bf16 v[96:99], v[184:187], v[214:217], v[96:99]
	v_mfma_f32_16x16x32_bf16 v[84:87], v[166:169], v[222:225], v[84:87]
	v_mfma_f32_16x16x32_bf16 v[80:83], v[184:187], v[222:225], v[80:83]
	v_mfma_f32_16x16x32_bf16 v[68:71], v[166:169], v[230:233], v[68:71]
	v_mfma_f32_16x16x32_bf16 v[64:67], v[184:187], v[230:233], v[64:67]
	s_setprio 0
	s_barrier
; #define PG8_STAGE(bufoff, gbase, voff) do { _Pragma("unroll") for (int _i = 0; _i < 2; ++_i) \
;         __builtin_amdgcn_global_load_lds((const unsigned*)((const char*)(gbase) + (voff)[_i]), (PG8_LAS unsigned*)(lds + (bufoff) + ldsw + _i * 8192), 16, 0, 0); } while (0)
; #define PG8_LDA(dst, b, h) do { _Pragma("unroll") for (int m = 0; m < 4; ++m) _Pragma("unroll") for (int k = 0; k < 2; ++k) dst[m][k] = *(const PG8_LAS bf16x8*)(lds + PG8_SA(b, h) + aoff + m * 2048 + k * 1024); } while (0)
; #define PG8_WAIT_V(n) asm volatile("s_waitcnt vmcnt(" #n ")" ::: "memory")
; #define PG8_WAIT_L(n) asm volatile("s_waitcnt lgkmcnt(" #n ")" ::: "memory")
; #define PG8_BAR __builtin_amdgcn_s_barrier()
; template <class Epi, class Sched, bool ALIGN_EPI = false, bool SP2 = false>
; __device__ __forceinline__ void gemm_phase(PG8_LAS unsigned char* lds, const Gemm g, const Sched& S, const Epi& E, const int tid) {
;     ...
;         for (int t = 0; t < nt; t += 2) {
;             const bool last = (t == nt - 2);
;             const char* a1 = cA + (size_t)(t + 1) * kstep;
;             const char* a2 = last ? nA : cA + (size_t)(t + 2) * kstep; const char* b2 = last ? nB : cB + (size_t)(t + 2) * kstep;
;             const char* a3 = a2 + kstep; const char* b3 = b2 + kstep;
;             if (last && has_next) S.a_ready(nxt);
;             if constexpr (SP2) {
;             PG8_LDB(B0, 0, 0); PG8_LDB(B1, 0, 1); PG8_SCHED; PG8_LDA(At, 0, 0); PG8_STAGE(PG8_SA(1, 1), a1 + hstep, voffA);
;             PG8_WAIT_V(8); PG8_WAIT_L(0); PG8_BAR; PG8_MMA(0, 0, At, B0); PG8_MMA(0, 1, At, B1); PG8_BAR; PG8_SCHED;
;             PG8_LDA(At, 0, 1); PG8_STAGE(PG8_SB(0, 0), b2, voffB); PG8_STAGE(PG8_SB(0, 1), b2 + hstep, voffB); PG8_STAGE(PG8_SA(0, 0), a2, voffA);
;             PG8_WAIT_V(8); PG8_WAIT_L(0); PG8_BAR; PG8_MMA(1, 0, At, B0); PG8_MMA(1, 1, At, B1); PG8_BAR; PG8_SCHED;
;             PG8_LDB(B0, 1, 0); PG8_LDB(B1, 1, 1); PG8_SCHED; PG8_LDA(At, 1, 0); PG8_STAGE(PG8_SA(0, 1), a2 + hstep, voffA);
;             PG8_WAIT_V(8); PG8_WAIT_L(0); PG8_BAR; PG8_MMA(0, 0, At, B0); PG8_MMA(0, 1, At, B1); PG8_BAR; PG8_SCHED;
;             PG8_LDA(At, 1, 1); PG8_STAGE(PG8_SB(1, 0), b3, voffB); PG8_STAGE(PG8_SB(1, 1), b3 + hstep, voffB); PG8_STAGE(PG8_SA(1, 0), a3, voffA);
;             PG8_WAIT_V(8); PG8_WAIT_L(0); PG8_BAR; PG8_MMA(1, 0, At, B0); PG8_MMA(1, 1, At, B1); PG8_BAR; PG8_SCHED;
	s_add_i32 s30, s45, s46
	v_lshl_add_u64 v[158:159], v[158:159], 0, s[28:29]
	s_mov_b32 m0, s30
	ds_read_b128 v[188:191], v145 offset:49152
	ds_read_b128 v[192:195], v145 offset:50176
	ds_read_b128 v[208:211], v145 offset:51200
	ds_read_b128 v[214:217], v145 offset:52224
	ds_read_b128 v[218:221], v145 offset:53248
	ds_read_b128 v[222:225], v145 offset:54272
	ds_read_b128 v[226:229], v145 offset:55296
	ds_read_b128 v[230:233], v145 offset:56320
	global_load_lds_dwordx4 v[158:159], off
	v_lshl_add_u64 v[158:159], v[174:175], 0, s[28:29]
	s_add_i32 m0, s30, 0x2000
	s_add_i32 s30, s63, s46
	global_load_lds_dwordx4 v[158:159], off
	v_lshl_add_u64 v[158:159], v[178:179], 0, s[28:29]
	s_mov_b32 m0, s30
	s_nop 0
	global_load_lds_dwordx4 v[158:159], off
	v_lshl_add_u64 v[158:159], v[180:181], 0, s[28:29]
	s_add_i32 m0, s30, 0x2000
	s_nop 0
	global_load_lds_dwordx4 v[158:159], off
	v_lshl_add_u64 v[158:159], v[196:197], 0, s[28:29]
	s_mov_b32 m0, s51
	s_nop 0
	global_load_lds_dwordx4 v[158:159], off
	v_lshl_add_u64 v[158:159], v[198:199], 0, s[28:29]
	s_mov_b32 m0, s52
	s_nop 0
	global_load_lds_dwordx4 v[158:159], off
	s_waitcnt vmcnt(8)
	s_waitcnt lgkmcnt(0)
	s_setprio 1
	s_barrier
	v_mfma_f32_16x16x32_bf16 v[60:63], v[138:141], v[188:191], v[60:63]
	v_mfma_f32_16x16x32_bf16 v[56:59], v[150:153], v[188:191], v[56:59]
	v_mfma_f32_16x16x32_bf16 v[44:47], v[138:141], v[208:211], v[44:47]
	v_mfma_f32_16x16x32_bf16 v[40:43], v[150:153], v[208:211], v[40:43]
	v_mfma_f32_16x16x32_bf16 v[28:31], v[138:141], v[218:221], v[28:31]
	v_mfma_f32_16x16x32_bf16 v[24:27], v[150:153], v[218:221], v[24:27]
	v_mfma_f32_16x16x32_bf16 v[12:15], v[138:141], v[226:229], v[12:15]
	v_mfma_f32_16x16x32_bf16 v[8:11], v[150:153], v[226:229], v[8:11]
	v_mfma_f32_16x16x32_bf16 v[60:63], v[146:149], v[192:195], v[60:63]
	v_mfma_f32_16x16x32_bf16 v[56:59], v[154:157], v[192:195], v[56:59]
	v_mfma_f32_16x16x32_bf16 v[44:47], v[146:149], v[214:217], v[44:47]
	v_mfma_f32_16x16x32_bf16 v[40:43], v[154:157], v[214:217], v[40:43]
	v_mfma_f32_16x16x32_bf16 v[28:31], v[146:149], v[222:225], v[28:31]
	v_mfma_f32_16x16x32_bf16 v[24:27], v[154:157], v[222:225], v[24:27]
	v_mfma_f32_16x16x32_bf16 v[12:15], v[146:149], v[230:233], v[12:15]
	v_mfma_f32_16x16x32_bf16 v[8:11], v[154:157], v[230:233], v[8:11]
	s_setprio 0
	s_setprio 1
	v_mfma_f32_16x16x32_bf16 v[52:55], v[162:165], v[188:191], v[52:55]
	v_mfma_f32_16x16x32_bf16 v[48:51], v[170:173], v[188:191], v[48:51]
	v_mfma_f32_16x16x32_bf16 v[36:39], v[162:165], v[208:211], v[36:39]
	v_mfma_f32_16x16x32_bf16 v[32:35], v[170:173], v[208:211], v[32:35]
	v_mfma_f32_16x16x32_bf16 v[20:23], v[162:165], v[218:221], v[20:23]
	v_mfma_f32_16x16x32_bf16 v[16:19], v[170:173], v[218:221], v[16:19]
	v_mfma_f32_16x16x32_bf16 v[4:7], v[162:165], v[226:229], v[4:7]
	v_mfma_f32_16x16x32_bf16 v[0:3], v[170:173], v[226:229], v[0:3]
	v_mfma_f32_16x16x32_bf16 v[52:55], v[166:169], v[192:195], v[52:55]
	v_mfma_f32_16x16x32_bf16 v[48:51], v[184:187], v[192:195], v[48:51]
	v_mfma_f32_16x16x32_bf16 v[36:39], v[166:169], v[214:217], v[36:39]
	v_mfma_f32_16x16x32_bf16 v[32:35], v[184:187], v[214:217], v[32:35]
	v_mfma_f32_16x16x32_bf16 v[20:23], v[166:169], v[222:225], v[20:23]
	v_mfma_f32_16x16x32_bf16 v[16:19], v[184:187], v[222:225], v[16:19]
	v_mfma_f32_16x16x32_bf16 v[4:7], v[166:169], v[230:233], v[4:7]
	v_mfma_f32_16x16x32_bf16 v[0:3], v[184:187], v[230:233], v[0:3]
	s_setprio 0
	s_barrier
	s_add_u32 s26, s26, 0x100
	s_addc_u32 s27, s27, 0
	s_add_u32 s36, s36, 0x100
	s_addc_u32 s37, s37, 0
	s_cmp_ge_u32 s44, s57
	s_mov_b32 s30, s44
	s_cbranch_scc1 .Lmy_kdone_0
.LBB0_60:
	s_add_i32 s44, s30, 2
	s_add_u32 s45, s26, 0x80
	s_addc_u32 s31, s27, 0
	s_add_i32 s63, 0, 0x10000
	s_cmp_eq_u32 s58, s30
	s_cselect_b32 s31, s21, s31
	s_cselect_b32 s30, s20, s45
	s_cselect_b32 s65, s23, s37
	s_cselect_b32 s64, s22, s36
	s_add_i32 s45, 0, 0x14000
	v_add_u32_e32 v154, s63, v143
	v_add_u32_e32 v158, s45, v143
	ds_read_b128 v[138:141], v154
	ds_read_b128 v[146:149], v154 offset:1024
	ds_read_b128 v[150:153], v154 offset:2048
	ds_read_b128 v[154:157], v154 offset:3072
	ds_read_b128 v[162:165], v158
	ds_read_b128 v[166:169], v158 offset:1024
	ds_read_b128 v[170:173], v158 offset:2048
	ds_read_b128 v[184:187], v158 offset:3072
	v_lshl_add_u64 v[158:159], s[26:27], 0, v[134:135]
	s_add_i32 m0, s47, 0xc000
	ds_read_b128 v[188:191], v145
	ds_read_b128 v[192:195], v145 offset:1024
	ds_read_b128 v[208:211], v145 offset:2048
	ds_read_b128 v[214:217], v145 offset:3072
	ds_read_b128 v[218:221], v145 offset:4096
	ds_read_b128 v[222:225], v145 offset:5120
	ds_read_b128 v[226:229], v145 offset:6144
	ds_read_b128 v[230:233], v145 offset:7168
	global_load_lds_dwordx4 v[158:159], off
	v_lshl_add_u64 v[158:159], s[26:27], 0, v[136:137]
	s_add_i32 m0, s47, 0xe000
	s_nop 0
	global_load_lds_dwordx4 v[158:159], off
	s_waitcnt vmcnt(8)
	s_waitcnt lgkmcnt(0)
	s_setprio 1
	s_barrier
; #define PG8_STAGE(bufoff, gbase, voff) do { _Pragma("unroll") for (int _i = 0; _i < 2; ++_i) \
;         __builtin_amdgcn_global_load_lds((const unsigned*)((const char*)(gbase) + (voff)[_i]), (PG8_LAS unsigned*)(lds + (bufoff) + ldsw + _i * 8192), 16, 0, 0); } while (0)
; #define PG8_LDA(dst, b, h) do { _Pragma("unroll") for (int m = 0; m < 4; ++m) _Pragma("unroll") for (int k = 0; k < 2; ++k) dst[m][k] = *(const PG8_LAS bf16x8*)(lds + PG8_SA(b, h) + aoff + m * 2048 + k * 1024); } while (0)
; #define PG8_MMA(ai, bj, At, Bt) do { __builtin_amdgcn_s_setprio(1); _Pragma("unroll") for (int m = 0; m < 4; ++m) _Pragma("unroll") for (int n = 0; n < 2; ++n) _Pragma("unroll") for (int k = 0; k < 2; ++k) \
;         acc[ai][bj][m][n] = __builtin_amdgcn_mfma_f32_16x16x32_bf16(Bt[n][k], At[m][k], acc[ai][bj][m][n], 0, 0, 0); __builtin_amdgcn_s_setprio(0); } while (0)
; #define PG8_WAIT_V(n) asm volatile("s_waitcnt vmcnt(" #n ")" ::: "memory")
; #define PG8_WAIT_L(n) asm volatile("s_waitcnt lgkmcnt(" #n ")" ::: "memory")
; #define PG8_BAR __builtin_amdgcn_s_barrier()
; #define PG8_SCHED __builtin_amdgcn_sched_barrier(0)
; template <class Epi, class Sched, bool ALIGN_EPI = false, bool SP2 = false>
; __device__ __forceinline__ void gemm_phase(PG8_LAS unsigned char* lds, const Gemm g, const Sched& S, const Epi& E, const int tid) {
;     ...
;             PG8_WAIT_V(8); PG8_WAIT_L(0); PG8_BAR; PG8_MMA(0, 0, At, B0); PG8_MMA(0, 1, At, B1); PG8_BAR; PG8_SCHED;
;             PG8_LDA(At, 0, 1); PG8_STAGE(PG8_SB(0, 0), b2, voffB); PG8_STAGE(PG8_SB(0, 1), b2 + hstep, voffB); PG8_STAGE(PG8_SA(0, 0), a2, voffA);
;             PG8_WAIT_V(8); PG8_WAIT_L(0); PG8_BAR; PG8_MMA(1, 0, At, B0); PG8_MMA(1, 1, At, B1); PG8_BAR; PG8_SCHED;
	v_mfma_f32_16x16x32_bf16 v[124:127], v[138:141], v[188:191], v[124:127]
	v_mfma_f32_16x16x32_bf16 v[120:123], v[150:153], v[188:191], v[120:123]
	v_mfma_f32_16x16x32_bf16 v[108:111], v[138:141], v[208:211], v[108:111]
	v_mfma_f32_16x16x32_bf16 v[104:107], v[150:153], v[208:211], v[104:107]
	v_mfma_f32_16x16x32_bf16 v[92:95], v[138:141], v[218:221], v[92:95]
	v_mfma_f32_16x16x32_bf16 v[88:91], v[150:153], v[218:221], v[88:91]
	v_mfma_f32_16x16x32_bf16 v[76:79], v[138:141], v[226:229], v[76:79]
	v_mfma_f32_16x16x32_bf16 v[72:75], v[150:153], v[226:229], v[72:75]
	v_mfma_f32_16x16x32_bf16 v[124:127], v[146:149], v[192:195], v[124:127]
	v_mfma_f32_16x16x32_bf16 v[120:123], v[154:157], v[192:195], v[120:123]
	v_mfma_f32_16x16x32_bf16 v[108:111], v[146:149], v[214:217], v[108:111]
	v_mfma_f32_16x16x32_bf16 v[104:107], v[154:157], v[214:217], v[104:107]
	v_mfma_f32_16x16x32_bf16 v[92:95], v[146:149], v[222:225], v[92:95]
	v_mfma_f32_16x16x32_bf16 v[88:91], v[154:157], v[222:225], v[88:91]
	v_mfma_f32_16x16x32_bf16 v[76:79], v[146:149], v[230:233], v[76:79]
	v_mfma_f32_16x16x32_bf16 v[72:75], v[154:157], v[230:233], v[72:75]
	s_setprio 0
	s_setprio 1
	v_mfma_f32_16x16x32_bf16 v[116:119], v[162:165], v[188:191], v[116:119]
	v_mfma_f32_16x16x32_bf16 v[112:115], v[170:173], v[188:191], v[112:115]
	v_mfma_f32_16x16x32_bf16 v[100:103], v[162:165], v[208:211], v[100:103]
	v_mfma_f32_16x16x32_bf16 v[96:99], v[170:173], v[208:211], v[96:99]
	v_mfma_f32_16x16x32_bf16 v[84:87], v[162:165], v[218:221], v[84:87]
	v_mfma_f32_16x16x32_bf16 v[80:83], v[170:173], v[218:221], v[80:83]
	v_mfma_f32_16x16x32_bf16 v[68:71], v[162:165], v[226:229], v[68:71]
	v_mfma_f32_16x16x32_bf16 v[64:67], v[170:173], v[226:229], v[64:67]
	v_mfma_f32_16x16x32_bf16 v[116:119], v[166:169], v[192:195], v[116:119]
	v_mfma_f32_16x16x32_bf16 v[112:115], v[184:187], v[192:195], v[112:115]
	v_mfma_f32_16x16x32_bf16 v[100:103], v[166:169], v[214:217], v[100:103]
	v_mfma_f32_16x16x32_bf16 v[96:99], v[184:187], v[214:217], v[96:99]
	v_mfma_f32_16x16x32_bf16 v[84:87], v[166:169], v[222:225], v[84:87]
	v_mfma_f32_16x16x32_bf16 v[80:83], v[184:187], v[222:225], v[80:83]
	v_mfma_f32_16x16x32_bf16 v[68:71], v[166:169], v[230:233], v[68:71]
	v_mfma_f32_16x16x32_bf16 v[64:67], v[184:187], v[230:233], v[64:67]
	s_setprio 0
	s_barrier
	s_add_i32 s63, s63, s46
	v_lshl_add_u64 v[158:159], s[64:65], 0, v[160:161]
	s_mov_b32 m0, s63
	ds_read_b128 v[188:191], v145 offset:16384
	ds_read_b128 v[192:195], v145 offset:17408
	ds_read_b128 v[208:211], v145 offset:18432
	ds_read_b128 v[214:217], v145 offset:19456
	ds_read_b128 v[218:221], v145 offset:20480
	ds_read_b128 v[222:225], v145 offset:21504
	ds_read_b128 v[226:229], v145 offset:22528
	ds_read_b128 v[230:233], v145 offset:23552
	global_load_lds_dwordx4 v[158:159], off
	s_add_i32 m0, s63, 0x2000
	v_lshl_add_u64 v[174:175], s[64:65], 0, v[132:133]
	s_add_u32 s64, s64, s12
	s_addc_u32 s65, s65, 0
	s_add_i32 s45, s45, s46
	global_load_lds_dwordx4 v[174:175], off
	v_lshl_add_u64 v[178:179], s[64:65], 0, v[160:161]
	s_mov_b32 m0, s45
	v_lshl_add_u64 v[180:181], s[64:65], 0, v[132:133]
	global_load_lds_dwordx4 v[178:179], off
	s_add_i32 m0, s45, 0x2000
	v_lshl_add_u64 v[196:197], s[30:31], 0, v[128:129]
	global_load_lds_dwordx4 v[180:181], off
	s_mov_b32 m0, s47
	v_lshl_add_u64 v[198:199], s[30:31], 0, v[130:131]
	global_load_lds_dwordx4 v[196:197], off
	s_mov_b32 m0, s48
	s_nop 0
	global_load_lds_dwordx4 v[198:199], off
	s_waitcnt vmcnt(8)
	s_waitcnt lgkmcnt(0)
	s_setprio 1
	s_barrier
	v_mfma_f32_16x16x32_bf16 v[60:63], v[138:141], v[188:191], v[60:63]
	v_mfma_f32_16x16x32_bf16 v[56:59], v[150:153], v[188:191], v[56:59]
	v_mfma_f32_16x16x32_bf16 v[44:47], v[138:141], v[208:211], v[44:47]
	v_mfma_f32_16x16x32_bf16 v[40:43], v[150:153], v[208:211], v[40:43]
	v_mfma_f32_16x16x32_bf16 v[28:31], v[138:141], v[218:221], v[28:31]
	v_mfma_f32_16x16x32_bf16 v[24:27], v[150:153], v[218:221], v[24:27]
	v_mfma_f32_16x16x32_bf16 v[12:15], v[138:141], v[226:229], v[12:15]
	v_mfma_f32_16x16x32_bf16 v[8:11], v[150:153], v[226:229], v[8:11]
	v_mfma_f32_16x16x32_bf16 v[60:63], v[146:149], v[192:195], v[60:63]
	v_mfma_f32_16x16x32_bf16 v[56:59], v[154:157], v[192:195], v[56:59]
	v_mfma_f32_16x16x32_bf16 v[44:47], v[146:149], v[214:217], v[44:47]
	v_mfma_f32_16x16x32_bf16 v[40:43], v[154:157], v[214:217], v[40:43]
	v_mfma_f32_16x16x32_bf16 v[28:31], v[146:149], v[222:225], v[28:31]
	v_mfma_f32_16x16x32_bf16 v[24:27], v[154:157], v[222:225], v[24:27]
	v_mfma_f32_16x16x32_bf16 v[12:15], v[146:149], v[230:233], v[12:15]
	v_mfma_f32_16x16x32_bf16 v[8:11], v[154:157], v[230:233], v[8:11]
	s_setprio 0
	s_setprio 1
	v_mfma_f32_16x16x32_bf16 v[52:55], v[162:165], v[188:191], v[52:55]
	v_mfma_f32_16x16x32_bf16 v[48:51], v[170:173], v[188:191], v[48:51]
	v_mfma_f32_16x16x32_bf16 v[36:39], v[162:165], v[208:211], v[36:39]
	v_mfma_f32_16x16x32_bf16 v[32:35], v[170:173], v[208:211], v[32:35]
	v_mfma_f32_16x16x32_bf16 v[20:23], v[162:165], v[218:221], v[20:23]
	v_mfma_f32_16x16x32_bf16 v[16:19], v[170:173], v[218:221], v[16:19]
	v_mfma_f32_16x16x32_bf16 v[4:7], v[162:165], v[226:229], v[4:7]
	v_mfma_f32_16x16x32_bf16 v[0:3], v[170:173], v[226:229], v[0:3]
	v_mfma_f32_16x16x32_bf16 v[52:55], v[166:169], v[192:195], v[52:55]
	v_mfma_f32_16x16x32_bf16 v[48:51], v[184:187], v[192:195], v[48:51]
	v_mfma_f32_16x16x32_bf16 v[36:39], v[166:169], v[214:217], v[36:39]
	v_mfma_f32_16x16x32_bf16 v[32:35], v[184:187], v[214:217], v[32:35]
	v_mfma_f32_16x16x32_bf16 v[20:23], v[166:169], v[222:225], v[20:23]
	v_mfma_f32_16x16x32_bf16 v[16:19], v[184:187], v[222:225], v[16:19]
	v_mfma_f32_16x16x32_bf16 v[4:7], v[166:169], v[230:233], v[4:7]
	v_mfma_f32_16x16x32_bf16 v[0:3], v[184:187], v[230:233], v[0:3]
	s_setprio 0
	s_barrier
; #define PG8_STAGE(bufoff, gbase, voff) do { _Pragma("unroll") for (int _i = 0; _i < 2; ++_i) \
;         __builtin_amdgcn_global_load_lds((const unsigned*)((const char*)(gbase) + (voff)[_i]), (PG8_LAS unsigned*)(lds + (bufoff) + ldsw + _i * 8192), 16, 0, 0); } while (0)
; #define PG8_LDA(dst, b, h) do { _Pragma("unroll") for (int m = 0; m < 4; ++m) _Pragma("unroll") for (int k = 0; k < 2; ++k) dst[m][k] = *(const PG8_LAS bf16x8*)(lds + PG8_SA(b, h) + aoff + m * 2048 + k * 1024); } while (0)
; #define PG8_LDB(dst, b, h) do { _Pragma("unroll") for (int n = 0; n < 2; ++n) _Pragma("unroll") for (int k = 0; k < 2; ++k) dst[n][k] = *(const PG8_LAS bf16x8*)(lds + PG8_SB(b, h) + boff + n * 2048 + k * 1024); } while (0)
; #define PG8_MMA(ai, bj, At, Bt) do { __builtin_amdgcn_s_setprio(1); _Pragma("unroll") for (int m = 0; m < 4; ++m) _Pragma("unroll") for (int n = 0; n < 2; ++n) _Pragma("unroll") for (int k = 0; k < 2; ++k) \
;         acc[ai][bj][m][n] = __builtin_amdgcn_mfma_f32_16x16x32_bf16(Bt[n][k], At[m][k], acc[ai][bj][m][n], 0, 0, 0); __builtin_amdgcn_s_setprio(0); } while (0)
; #define PG8_WAIT_V(n) asm volatile("s_waitcnt vmcnt(" #n ")" ::: "memory")
; #define PG8_WAIT_L(n) asm volatile("s_waitcnt lgkmcnt(" #n ")" ::: "memory")
; #define PG8_BAR __builtin_amdgcn_s_barrier()
; #define PG8_SCHED __builtin_amdgcn_sched_barrier(0)
; template <class Epi, class Sched, bool ALIGN_EPI = false, bool SP2 = false>
; __device__ __forceinline__ void gemm_phase(PG8_LAS unsigned char* lds, const Gemm g, const Sched& S, const Epi& E, const int tid) {
;     ...
;             PG8_LDB(B0, 1, 0); PG8_LDB(B1, 1, 1); PG8_SCHED; PG8_LDA(At, 1, 0); PG8_STAGE(PG8_SA(0, 1), a2 + hstep, voffA);
;             PG8_WAIT_V(8); PG8_WAIT_L(0); PG8_BAR; PG8_MMA(0, 0, At, B0); PG8_MMA(0, 1, At, B1); PG8_BAR; PG8_SCHED;
;             PG8_LDA(At, 1, 1); PG8_STAGE(PG8_SB(1, 0), b3, voffB); PG8_STAGE(PG8_SB(1, 1), b3 + hstep, voffB); PG8_STAGE(PG8_SA(1, 0), a3, voffA);
;             PG8_WAIT_V(8); PG8_WAIT_L(0); PG8_BAR; PG8_MMA(1, 0, At, B0); PG8_MMA(1, 1, At, B1); PG8_BAR; PG8_SCHED;
	s_add_i32 s45, 0, 0x18000
	s_add_i32 s63, 0, 0x1c000
	v_add_u32_e32 v154, s45, v143
	v_add_u32_e32 v183, s63, v143
	ds_read_b128 v[138:141], v154
	ds_read_b128 v[146:149], v154 offset:1024
	ds_read_b128 v[150:153], v154 offset:2048
	ds_read_b128 v[154:157], v154 offset:3072
	ds_read_b128 v[162:165], v183
	ds_read_b128 v[166:169], v183 offset:1024
	ds_read_b128 v[170:173], v183 offset:2048
	ds_read_b128 v[184:187], v183 offset:3072
	s_add_u32 s30, s30, s12
	s_addc_u32 s31, s31, 0
	s_mov_b32 m0, s49
	v_lshl_add_u64 v[204:205], s[30:31], 0, v[128:129]
	ds_read_b128 v[188:191], v145 offset:32768
	ds_read_b128 v[192:195], v145 offset:33792
	ds_read_b128 v[208:211], v145 offset:34816
	ds_read_b128 v[214:217], v145 offset:35840
	ds_read_b128 v[218:221], v145 offset:36864
	ds_read_b128 v[222:225], v145 offset:37888
	ds_read_b128 v[226:229], v145 offset:38912
	ds_read_b128 v[230:233], v145 offset:39936
	global_load_lds_dwordx4 v[204:205], off
	v_lshl_add_u64 v[204:205], s[30:31], 0, v[130:131]
	s_mov_b32 m0, s50
	s_nop 0
	global_load_lds_dwordx4 v[204:205], off
	s_waitcnt vmcnt(8)
	s_waitcnt lgkmcnt(0)
	s_setprio 1
	s_barrier
	v_mfma_f32_16x16x32_bf16 v[124:127], v[138:141], v[188:191], v[124:127]
	v_mfma_f32_16x16x32_bf16 v[120:123], v[150:153], v[188:191], v[120:123]
	v_mfma_f32_16x16x32_bf16 v[108:111], v[138:141], v[208:211], v[108:111]
	v_mfma_f32_16x16x32_bf16 v[104:107], v[150:153], v[208:211], v[104:107]
	v_mfma_f32_16x16x32_bf16 v[92:95], v[138:141], v[218:221], v[92:95]
	v_mfma_f32_16x16x32_bf16 v[88:91], v[150:153], v[218:221], v[88:91]
	v_mfma_f32_16x16x32_bf16 v[76:79], v[138:141], v[226:229], v[76:79]
	v_mfma_f32_16x16x32_bf16 v[72:75], v[150:153], v[226:229], v[72:75]
	v_mfma_f32_16x16x32_bf16 v[124:127], v[146:149], v[192:195], v[124:127]
	v_mfma_f32_16x16x32_bf16 v[120:123], v[154:157], v[192:195], v[120:123]
	v_mfma_f32_16x16x32_bf16 v[108:111], v[146:149], v[214:217], v[108:111]
	v_mfma_f32_16x16x32_bf16 v[104:107], v[154:157], v[214:217], v[104:107]
	v_mfma_f32_16x16x32_bf16 v[92:95], v[146:149], v[222:225], v[92:95]
	v_mfma_f32_16x16x32_bf16 v[88:91], v[154:157], v[222:225], v[88:91]
	v_mfma_f32_16x16x32_bf16 v[76:79], v[146:149], v[230:233], v[76:79]
	v_mfma_f32_16x16x32_bf16 v[72:75], v[154:157], v[230:233], v[72:75]
	s_setprio 0
	s_setprio 1
	v_mfma_f32_16x16x32_bf16 v[116:119], v[162:165], v[188:191], v[116:119]
	v_mfma_f32_16x16x32_bf16 v[112:115], v[170:173], v[188:191], v[112:115]
	v_mfma_f32_16x16x32_bf16 v[100:103], v[162:165], v[208:211], v[100:103]
	v_mfma_f32_16x16x32_bf16 v[96:99], v[170:173], v[208:211], v[96:99]
	v_mfma_f32_16x16x32_bf16 v[84:87], v[162:165], v[218:221], v[84:87]
	v_mfma_f32_16x16x32_bf16 v[80:83], v[170:173], v[218:221], v[80:83]
	v_mfma_f32_16x16x32_bf16 v[68:71], v[162:165], v[226:229], v[68:71]
	v_mfma_f32_16x16x32_bf16 v[64:67], v[170:173], v[226:229], v[64:67]
	v_mfma_f32_16x16x32_bf16 v[116:119], v[166:169], v[192:195], v[116:119]
	v_mfma_f32_16x16x32_bf16 v[112:115], v[184:187], v[192:195], v[112:115]
	v_mfma_f32_16x16x32_bf16 v[100:103], v[166:169], v[214:217], v[100:103]
	v_mfma_f32_16x16x32_bf16 v[96:99], v[184:187], v[214:217], v[96:99]
	v_mfma_f32_16x16x32_bf16 v[84:87], v[166:169], v[222:225], v[84:87]
	v_mfma_f32_16x16x32_bf16 v[80:83], v[184:187], v[222:225], v[80:83]
	v_mfma_f32_16x16x32_bf16 v[68:71], v[166:169], v[230:233], v[68:71]
	v_mfma_f32_16x16x32_bf16 v[64:67], v[184:187], v[230:233], v[64:67]
	s_setprio 0
	s_barrier
	s_add_i32 s30, s45, s46
	v_lshl_add_u64 v[158:159], v[158:159], 0, s[28:29]
	s_mov_b32 m0, s30
	ds_read_b128 v[188:191], v145 offset:49152
	ds_read_b128 v[192:195], v145 offset:50176
	ds_read_b128 v[208:211], v145 offset:51200
	ds_read_b128 v[214:217], v145 offset:52224
	ds_read_b128 v[218:221], v145 offset:53248
	ds_read_b128 v[222:225], v145 offset:54272
	ds_read_b128 v[226:229], v145 offset:55296
	ds_read_b128 v[230:233], v145 offset:56320
	global_load_lds_dwordx4 v[158:159], off
	v_lshl_add_u64 v[158:159], v[174:175], 0, s[28:29]
	s_add_i32 m0, s30, 0x2000
	s_add_i32 s30, s63, s46
	global_load_lds_dwordx4 v[158:159], off
	v_lshl_add_u64 v[158:159], v[178:179], 0, s[28:29]
	s_mov_b32 m0, s30
	s_nop 0
	global_load_lds_dwordx4 v[158:159], off
	v_lshl_add_u64 v[158:159], v[180:181], 0, s[28:29]
	s_add_i32 m0, s30, 0x2000
	s_nop 0
	global_load_lds_dwordx4 v[158:159], off
	v_lshl_add_u64 v[158:159], v[196:197], 0, s[28:29]
	s_mov_b32 m0, s51
	s_nop 0
	global_load_lds_dwordx4 v[158:159], off
	v_lshl_add_u64 v[158:159], v[198:199], 0, s[28:29]
	s_mov_b32 m0, s52
	s_nop 0
	global_load_lds_dwordx4 v[158:159], off
	s_waitcnt vmcnt(8)
	s_waitcnt lgkmcnt(0)
	s_setprio 1
	s_barrier
	v_mfma_f32_16x16x32_bf16 v[60:63], v[138:141], v[188:191], v[60:63]
	v_mfma_f32_16x16x32_bf16 v[56:59], v[150:153], v[188:191], v[56:59]
	v_mfma_f32_16x16x32_bf16 v[44:47], v[138:141], v[208:211], v[44:47]
	v_mfma_f32_16x16x32_bf16 v[40:43], v[150:153], v[208:211], v[40:43]
	v_mfma_f32_16x16x32_bf16 v[28:31], v[138:141], v[218:221], v[28:31]
	v_mfma_f32_16x16x32_bf16 v[24:27], v[150:153], v[218:221], v[24:27]
	v_mfma_f32_16x16x32_bf16 v[12:15], v[138:141], v[226:229], v[12:15]
	v_mfma_f32_16x16x32_bf16 v[8:11], v[150:153], v[226:229], v[8:11]
	v_mfma_f32_16x16x32_bf16 v[60:63], v[146:149], v[192:195], v[60:63]
	v_mfma_f32_16x16x32_bf16 v[56:59], v[154:157], v[192:195], v[56:59]
	v_mfma_f32_16x16x32_bf16 v[44:47], v[146:149], v[214:217], v[44:47]
	v_mfma_f32_16x16x32_bf16 v[40:43], v[154:157], v[214:217], v[40:43]
	v_mfma_f32_16x16x32_bf16 v[28:31], v[146:149], v[222:225], v[28:31]
	v_mfma_f32_16x16x32_bf16 v[24:27], v[154:157], v[222:225], v[24:27]
	v_mfma_f32_16x16x32_bf16 v[12:15], v[146:149], v[230:233], v[12:15]
	v_mfma_f32_16x16x32_bf16 v[8:11], v[154:157], v[230:233], v[8:11]
	s_setprio 0
	s_setprio 1
	v_mfma_f32_16x16x32_bf16 v[52:55], v[162:165], v[188:191], v[52:55]
	v_mfma_f32_16x16x32_bf16 v[48:51], v[170:173], v[188:191], v[48:51]
	v_mfma_f32_16x16x32_bf16 v[36:39], v[162:165], v[208:211], v[36:39]
	v_mfma_f32_16x16x32_bf16 v[32:35], v[170:173], v[208:211], v[32:35]
	v_mfma_f32_16x16x32_bf16 v[20:23], v[162:165], v[218:221], v[20:23]
	v_mfma_f32_16x16x32_bf16 v[16:19], v[170:173], v[218:221], v[16:19]
	v_mfma_f32_16x16x32_bf16 v[4:7], v[162:165], v[226:229], v[4:7]
	v_mfma_f32_16x16x32_bf16 v[0:3], v[170:173], v[226:229], v[0:3]
	v_mfma_f32_16x16x32_bf16 v[52:55], v[166:169], v[192:195], v[52:55]
	v_mfma_f32_16x16x32_bf16 v[48:51], v[184:187], v[192:195], v[48:51]
	v_mfma_f32_16x16x32_bf16 v[36:39], v[166:169], v[214:217], v[36:39]
	v_mfma_f32_16x16x32_bf16 v[32:35], v[184:187], v[214:217], v[32:35]
	v_mfma_f32_16x16x32_bf16 v[20:23], v[166:169], v[222:225], v[20:23]
	v_mfma_f32_16x16x32_bf16 v[16:19], v[184:187], v[222:225], v[16:19]
	v_mfma_f32_16x16x32_bf16 v[4:7], v[166:169], v[230:233], v[4:7]
	v_mfma_f32_16x16x32_bf16 v[0:3], v[184:187], v[230:233], v[0:3]
	s_setprio 0
	s_barrier
	s_add_u32 s26, s26, 0x100
	s_addc_u32 s27, s27, 0
	s_add_u32 s36, s36, 0x100
	s_addc_u32 s37, s37, 0
	s_cmp_ge_u32 s44, s57
	s_mov_b32 s30, s44
	s_cbranch_scc0 .LBB0_60

; #define PG8_STAGE(bufoff, gbase, voff) do { _Pragma("unroll") for (int _i = 0; _i < 2; ++_i) \
;         __builtin_amdgcn_global_load_lds((const unsigned*)((const char*)(gbase) + (voff)[_i]), (PG8_LAS unsigned*)(lds + (bufoff) + ldsw + _i * 8192), 16, 0, 0); } while (0)
; #define PG8_LDA(dst, b, h) do { _Pragma("unroll") for (int m = 0; m < 4; ++m) _Pragma("unroll") for (int k = 0; k < 2; ++k) dst[m][k] = *(const PG8_LAS bf16x8*)(lds + PG8_SA(b, h) + aoff + m * 2048 + k * 1024); } while (0)
; #define PG8_LDB(dst, b, h) do { _Pragma("unroll") for (int n = 0; n < 2; ++n) _Pragma("unroll") for (int k = 0; k < 2; ++k) dst[n][k] = *(const PG8_LAS bf16x8*)(lds + PG8_SB(b, h) + boff + n * 2048 + k * 1024); } while (0)
; #define PG8_WAIT_V(n) asm volatile("s_waitcnt vmcnt(" #n ")" ::: "memory")
; #define PG8_WAIT_L(n) asm volatile("s_waitcnt lgkmcnt(" #n ")" ::: "memory")
; #define PG8_BAR __builtin_amdgcn_s_barrier()
; #define PG8_SCHED __builtin_amdgcn_sched_barrier(0)
; template <class Epi, class Sched, bool ALIGN_EPI = false, bool SP2 = false>
; __device__ __forceinline__ void gemm_phase(PG8_LAS unsigned char* lds, const Gemm g, const Sched& S, const Epi& E, const int tid) {
;     ...
;         const bool has_next = S.next(ui + 1, nxt);
;         const char* nA = has_next ? (const char*)g.A + (size_t)nxt.pm * tstep : cA; const char* nB = has_next ? (const char*)g.Bt + (size_t)nxt.pn * tstep : cB;
;         for (int t = 0; t < nt; t += 2) {
;             const bool last = (t == nt - 2);
;             const char* a1 = cA + (size_t)(t + 1) * kstep;
;             const char* a2 = last ? nA : cA + (size_t)(t + 2) * kstep; const char* b2 = last ? nB : cB + (size_t)(t + 2) * kstep;
;             const char* a3 = a2 + kstep; const char* b3 = b2 + kstep;
;             if (last && has_next) S.a_ready(nxt);
;             if constexpr (SP2) {
;             PG8_LDB(B0, 0, 0); PG8_LDB(B1, 0, 1); PG8_SCHED; PG8_LDA(At, 0, 0); PG8_STAGE(PG8_SA(1, 1), a1 + hstep, voffA);
;             PG8_WAIT_V(8); PG8_WAIT_L(0); PG8_BAR; PG8_MMA(0, 0, At, B0); PG8_MMA(0, 1, At, B1); PG8_BAR; PG8_SCHED;
;             PG8_LDA(At, 0, 1); PG8_STAGE(PG8_SB(0, 0), b2, voffB); PG8_STAGE(PG8_SB(0, 1), b2 + hstep, voffB); PG8_STAGE(PG8_SA(0, 0), a2, voffA);
;             PG8_WAIT_V(8); PG8_WAIT_L(0); PG8_BAR; PG8_MMA(1, 0, At, B0); PG8_MMA(1, 1, At, B1); PG8_BAR; PG8_SCHED;
.LBB0_466:
	s_ashr_i32 s51, s50, 31
	s_lshl_b64 s[20:21], s[50:51], 19
	s_add_u32 s52, s12, s20
	s_addc_u32 s53, s13, s21
	s_and_b64 s[20:21], s[40:41], exec
	s_cselect_b32 s1, s53, s15
	s_cselect_b32 s36, s52, s14
	s_ashr_i32 s49, s48, 31
	s_lshl_b64 s[20:21], s[48:49], 19
	s_add_u32 s68, s22, s20
	s_addc_u32 s69, s23, s21
	s_and_b64 s[20:21], s[40:41], exec
	s_cselect_b32 s37, s69, s17
	s_cselect_b32 s42, s68, s16
	s_add_u32 s14, s14, 0x40080
	s_addc_u32 s15, s15, 0
	s_add_u32 s43, s16, 0x100
	s_addc_u32 s49, s17, 0
	s_mov_b32 s51, -2
	s_add_u32 s16, s14, 0xfffc0080
	s_addc_u32 s17, s15, -1
	s_add_i32 s56, 0, 0x10000
	s_cmp_eq_u32 s51, 12
	s_cselect_b32 s21, s1, s17
	s_cselect_b32 s20, s36, s16
	v_add_u32_e32 v138, s56, v147
	s_cselect_b32 s17, s37, s49
	s_cselect_b32 s16, s42, s43
	s_add_i32 s58, 0, 0x14000
	ds_read_b128 v[140:143], v138
	ds_read_b128 v[154:157], v138 offset:1024
	ds_read_b128 v[162:165], v138 offset:2048
	ds_read_b128 v[166:169], v138 offset:3072
	v_add_u32_e32 v138, s58, v147
	ds_read_b128 v[170:173], v138
	ds_read_b128 v[184:187], v138 offset:1024
	ds_read_b128 v[188:191], v138 offset:2048
	ds_read_b128 v[192:195], v138 offset:3072
	v_lshl_add_u64 v[158:159], s[14:15], 0, v[134:135]
	s_add_i32 m0, s3, 0xc000
	ds_read_b128 v[208:211], v153
	ds_read_b128 v[214:217], v153 offset:1024
	ds_read_b128 v[218:221], v153 offset:2048
	ds_read_b128 v[222:225], v153 offset:3072
	ds_read_b128 v[226:229], v153 offset:4096
	ds_read_b128 v[230:233], v153 offset:5120
	ds_read_b128 v[234:237], v153 offset:6144
	ds_read_b128 v[238:241], v153 offset:7168
	global_load_lds_dwordx4 v[158:159], off
	v_lshl_add_u64 v[158:159], s[14:15], 0, v[136:137]
	s_add_i32 m0, s3, 0xe000
	s_nop 0
	global_load_lds_dwordx4 v[158:159], off
	s_waitcnt vmcnt(24)
	s_waitcnt lgkmcnt(0)
	s_setprio 1
	s_barrier
	v_mfma_f32_16x16x32_bf16 v[124:127], v[140:143], v[208:211], 0
	v_mfma_f32_16x16x32_bf16 v[120:123], v[162:165], v[208:211], 0
	v_mfma_f32_16x16x32_bf16 v[108:111], v[140:143], v[218:221], 0
	v_mfma_f32_16x16x32_bf16 v[104:107], v[162:165], v[218:221], 0
	v_mfma_f32_16x16x32_bf16 v[92:95], v[140:143], v[226:229], 0
	v_mfma_f32_16x16x32_bf16 v[88:91], v[162:165], v[226:229], 0
	v_mfma_f32_16x16x32_bf16 v[76:79], v[140:143], v[234:237], 0
	v_mfma_f32_16x16x32_bf16 v[72:75], v[162:165], v[234:237], 0
	v_mfma_f32_16x16x32_bf16 v[124:127], v[154:157], v[214:217], v[124:127]
	v_mfma_f32_16x16x32_bf16 v[120:123], v[166:169], v[214:217], v[120:123]
	v_mfma_f32_16x16x32_bf16 v[108:111], v[154:157], v[222:225], v[108:111]
	v_mfma_f32_16x16x32_bf16 v[104:107], v[166:169], v[222:225], v[104:107]
	v_mfma_f32_16x16x32_bf16 v[92:95], v[154:157], v[230:233], v[92:95]
	v_mfma_f32_16x16x32_bf16 v[88:91], v[166:169], v[230:233], v[88:91]
	v_mfma_f32_16x16x32_bf16 v[76:79], v[154:157], v[238:241], v[76:79]
	v_mfma_f32_16x16x32_bf16 v[72:75], v[166:169], v[238:241], v[72:75]
	s_setprio 0
	s_setprio 1
	v_mfma_f32_16x16x32_bf16 v[116:119], v[170:173], v[208:211], 0
	v_mfma_f32_16x16x32_bf16 v[112:115], v[188:191], v[208:211], 0
	v_mfma_f32_16x16x32_bf16 v[100:103], v[170:173], v[218:221], 0
	v_mfma_f32_16x16x32_bf16 v[96:99], v[188:191], v[218:221], 0
	v_mfma_f32_16x16x32_bf16 v[84:87], v[170:173], v[226:229], 0
	v_mfma_f32_16x16x32_bf16 v[80:83], v[188:191], v[226:229], 0
	v_mfma_f32_16x16x32_bf16 v[68:71], v[170:173], v[234:237], 0
	v_mfma_f32_16x16x32_bf16 v[64:67], v[188:191], v[234:237], 0
	v_mfma_f32_16x16x32_bf16 v[116:119], v[184:187], v[214:217], v[116:119]
	v_mfma_f32_16x16x32_bf16 v[112:115], v[192:195], v[214:217], v[112:115]
	v_mfma_f32_16x16x32_bf16 v[100:103], v[184:187], v[222:225], v[100:103]
	v_mfma_f32_16x16x32_bf16 v[96:99], v[192:195], v[222:225], v[96:99]
	v_mfma_f32_16x16x32_bf16 v[84:87], v[184:187], v[230:233], v[84:87]
	v_mfma_f32_16x16x32_bf16 v[80:83], v[192:195], v[230:233], v[80:83]
	v_mfma_f32_16x16x32_bf16 v[68:71], v[184:187], v[238:241], v[68:71]
	v_mfma_f32_16x16x32_bf16 v[64:67], v[192:195], v[238:241], v[64:67]
	s_setprio 0
	s_barrier
	s_add_i32 s56, s56, s27
	v_lshl_add_u64 v[158:159], s[16:17], 0, v[160:161]
	s_mov_b32 m0, s56
	ds_read_b128 v[208:211], v153 offset:16384
	ds_read_b128 v[214:217], v153 offset:17408
	ds_read_b128 v[218:221], v153 offset:18432
	ds_read_b128 v[222:225], v153 offset:19456
	ds_read_b128 v[226:229], v153 offset:20480
	ds_read_b128 v[230:233], v153 offset:21504
	ds_read_b128 v[234:237], v153 offset:22528
	ds_read_b128 v[238:241], v153 offset:23552
	global_load_lds_dwordx4 v[158:159], off
	s_add_i32 m0, s56, 0x2000
	s_add_u32 s56, s16, 0x40000
	v_lshl_add_u64 v[174:175], s[16:17], 0, v[132:133]
	s_addc_u32 s57, s17, 0
	s_add_i32 s58, s58, s27
	global_load_lds_dwordx4 v[174:175], off
	v_lshl_add_u64 v[178:179], s[56:57], 0, v[160:161]
	s_mov_b32 m0, s58
	v_lshl_add_u64 v[180:181], s[20:21], 0, v[130:131]
	global_load_lds_dwordx4 v[178:179], off
	v_lshl_add_u64 v[178:179], s[56:57], 0, v[132:133]
	s_add_i32 m0, s58, 0x2000
	s_nop 0
	global_load_lds_dwordx4 v[178:179], off
	v_lshl_add_u64 v[178:179], s[20:21], 0, v[128:129]
	s_mov_b32 m0, s3
	s_nop 0
	global_load_lds_dwordx4 v[178:179], off
	s_mov_b32 m0, s30
	s_nop 0
	global_load_lds_dwordx4 v[180:181], off
	s_cmp_lt_u32 s83, 2
	s_cbranch_scc1 .Lmy_w8_1
	s_waitcnt vmcnt(24)
	s_branch .Lmy_wj_1

; #define PG8_STAGE(bufoff, gbase, voff) do { _Pragma("unroll") for (int _i = 0; _i < 2; ++_i) \
;         __builtin_amdgcn_global_load_lds((const unsigned*)((const char*)(gbase) + (voff)[_i]), (PG8_LAS unsigned*)(lds + (bufoff) + ldsw + _i * 8192), 16, 0, 0); } while (0)
; #define PG8_LDA(dst, b, h) do { _Pragma("unroll") for (int m = 0; m < 4; ++m) _Pragma("unroll") for (int k = 0; k < 2; ++k) dst[m][k] = *(const PG8_LAS bf16x8*)(lds + PG8_SA(b, h) + aoff + m * 2048 + k * 1024); } while (0)
; #define PG8_LDB(dst, b, h) do { _Pragma("unroll") for (int n = 0; n < 2; ++n) _Pragma("unroll") for (int k = 0; k < 2; ++k) dst[n][k] = *(const PG8_LAS bf16x8*)(lds + PG8_SB(b, h) + boff + n * 2048 + k * 1024); } while (0)
; #define PG8_MMA(ai, bj, At, Bt) do { __builtin_amdgcn_s_setprio(1); _Pragma("unroll") for (int m = 0; m < 4; ++m) _Pragma("unroll") for (int n = 0; n < 2; ++n) _Pragma("unroll") for (int k = 0; k < 2; ++k) \
;         acc[ai][bj][m][n] = __builtin_amdgcn_mfma_f32_16x16x32_bf16(Bt[n][k], At[m][k], acc[ai][bj][m][n], 0, 0, 0); __builtin_amdgcn_s_setprio(0); } while (0)
; #define PG8_WAIT_V(n) asm volatile("s_waitcnt vmcnt(" #n ")" ::: "memory")
; #define PG8_WAIT_L(n) asm volatile("s_waitcnt lgkmcnt(" #n ")" ::: "memory")
; #define PG8_BAR __builtin_amdgcn_s_barrier()
; #define PG8_SCHED __builtin_amdgcn_sched_barrier(0)
; template <class Epi, class Sched, bool ALIGN_EPI = false, bool SP2 = false>
; __device__ __forceinline__ void gemm_phase(PG8_LAS unsigned char* lds, const Gemm g, const Sched& S, const Epi& E, const int tid) {
;     ...
;             PG8_WAIT_V(8); PG8_WAIT_L(0); PG8_BAR; PG8_MMA(1, 0, At, B0); PG8_MMA(1, 1, At, B1); PG8_BAR; PG8_SCHED;
;             PG8_LDB(B0, 1, 0); PG8_LDB(B1, 1, 1); PG8_SCHED; PG8_LDA(At, 1, 0); PG8_STAGE(PG8_SA(0, 1), a2 + hstep, voffA);
;             PG8_WAIT_V(8); PG8_WAIT_L(0); PG8_BAR; PG8_MMA(0, 0, At, B0); PG8_MMA(0, 1, At, B1); PG8_BAR; PG8_SCHED;
.Lmy_wj_1:
	s_waitcnt lgkmcnt(0)
	s_setprio 1
	s_barrier
	v_mfma_f32_16x16x32_bf16 v[60:63], v[140:143], v[208:211], 0
	v_mfma_f32_16x16x32_bf16 v[56:59], v[162:165], v[208:211], 0
	v_mfma_f32_16x16x32_bf16 v[44:47], v[140:143], v[218:221], 0
	v_mfma_f32_16x16x32_bf16 v[40:43], v[162:165], v[218:221], 0
	v_mfma_f32_16x16x32_bf16 v[28:31], v[140:143], v[226:229], 0
	v_mfma_f32_16x16x32_bf16 v[24:27], v[162:165], v[226:229], 0
	v_mfma_f32_16x16x32_bf16 v[12:15], v[140:143], v[234:237], 0
	v_mfma_f32_16x16x32_bf16 v[8:11], v[162:165], v[234:237], 0
	v_mfma_f32_16x16x32_bf16 v[60:63], v[154:157], v[214:217], v[60:63]
	v_mfma_f32_16x16x32_bf16 v[56:59], v[166:169], v[214:217], v[56:59]
	v_mfma_f32_16x16x32_bf16 v[44:47], v[154:157], v[222:225], v[44:47]
	v_mfma_f32_16x16x32_bf16 v[40:43], v[166:169], v[222:225], v[40:43]
	v_mfma_f32_16x16x32_bf16 v[28:31], v[154:157], v[230:233], v[28:31]
	v_mfma_f32_16x16x32_bf16 v[24:27], v[166:169], v[230:233], v[24:27]
	v_mfma_f32_16x16x32_bf16 v[12:15], v[154:157], v[238:241], v[12:15]
	v_mfma_f32_16x16x32_bf16 v[8:11], v[166:169], v[238:241], v[8:11]
	s_setprio 0
	s_setprio 1
	v_mfma_f32_16x16x32_bf16 v[52:55], v[170:173], v[208:211], 0
	v_mfma_f32_16x16x32_bf16 v[48:51], v[188:191], v[208:211], 0
	v_mfma_f32_16x16x32_bf16 v[36:39], v[170:173], v[218:221], 0
	v_mfma_f32_16x16x32_bf16 v[32:35], v[188:191], v[218:221], 0
	v_mfma_f32_16x16x32_bf16 v[20:23], v[170:173], v[226:229], 0
	v_mfma_f32_16x16x32_bf16 v[16:19], v[188:191], v[226:229], 0
	v_mfma_f32_16x16x32_bf16 v[4:7], v[170:173], v[234:237], 0
	v_mfma_f32_16x16x32_bf16 v[0:3], v[188:191], v[234:237], 0
	v_mfma_f32_16x16x32_bf16 v[52:55], v[184:187], v[214:217], v[52:55]
	v_mfma_f32_16x16x32_bf16 v[48:51], v[192:195], v[214:217], v[48:51]
	v_mfma_f32_16x16x32_bf16 v[36:39], v[184:187], v[222:225], v[36:39]
	v_mfma_f32_16x16x32_bf16 v[32:35], v[192:195], v[222:225], v[32:35]
	v_mfma_f32_16x16x32_bf16 v[20:23], v[184:187], v[230:233], v[20:23]
	v_mfma_f32_16x16x32_bf16 v[16:19], v[192:195], v[230:233], v[16:19]
	v_mfma_f32_16x16x32_bf16 v[4:7], v[184:187], v[238:241], v[4:7]
	v_mfma_f32_16x16x32_bf16 v[0:3], v[192:195], v[238:241], v[0:3]
	s_setprio 0
	s_barrier
	s_add_i32 s56, 0, 0x18000
	v_add_u32_e32 v138, s56, v147
	s_add_i32 s57, 0, 0x1c000
	ds_read_b128 v[140:143], v138
	ds_read_b128 v[154:157], v138 offset:1024
	ds_read_b128 v[162:165], v138 offset:2048
	ds_read_b128 v[166:169], v138 offset:3072
	v_add_u32_e32 v138, s57, v147
	ds_read_b128 v[170:173], v138
	ds_read_b128 v[184:187], v138 offset:1024
	ds_read_b128 v[188:191], v138 offset:2048
	ds_read_b128 v[192:195], v138 offset:3072
	s_add_u32 s20, s20, 0x40000
	s_addc_u32 s21, s21, 0
	s_mov_b32 m0, s31
	v_lshl_add_u64 v[196:197], s[20:21], 0, v[128:129]
	ds_read_b128 v[208:211], v153 offset:32768
	ds_read_b128 v[214:217], v153 offset:33792
	ds_read_b128 v[218:221], v153 offset:34816
	ds_read_b128 v[222:225], v153 offset:35840
	ds_read_b128 v[226:229], v153 offset:36864
	ds_read_b128 v[230:233], v153 offset:37888
	ds_read_b128 v[234:237], v153 offset:38912
	ds_read_b128 v[238:241], v153 offset:39936
	global_load_lds_dwordx4 v[196:197], off
	v_lshl_add_u64 v[196:197], s[20:21], 0, v[130:131]
	s_mov_b32 m0, s34
	s_nop 0
	global_load_lds_dwordx4 v[196:197], off
	s_waitcnt vmcnt(8)
	s_waitcnt lgkmcnt(0)
	s_setprio 1
	s_barrier
	v_mfma_f32_16x16x32_bf16 v[124:127], v[140:143], v[208:211], v[124:127]
	v_mfma_f32_16x16x32_bf16 v[120:123], v[162:165], v[208:211], v[120:123]
	v_mfma_f32_16x16x32_bf16 v[108:111], v[140:143], v[218:221], v[108:111]
	v_mfma_f32_16x16x32_bf16 v[104:107], v[162:165], v[218:221], v[104:107]
	v_mfma_f32_16x16x32_bf16 v[92:95], v[140:143], v[226:229], v[92:95]
	v_mfma_f32_16x16x32_bf16 v[88:91], v[162:165], v[226:229], v[88:91]
	v_mfma_f32_16x16x32_bf16 v[76:79], v[140:143], v[234:237], v[76:79]
	v_mfma_f32_16x16x32_bf16 v[72:75], v[162:165], v[234:237], v[72:75]
	v_mfma_f32_16x16x32_bf16 v[124:127], v[154:157], v[214:217], v[124:127]
	v_mfma_f32_16x16x32_bf16 v[120:123], v[166:169], v[214:217], v[120:123]
	v_mfma_f32_16x16x32_bf16 v[108:111], v[154:157], v[222:225], v[108:111]
	v_mfma_f32_16x16x32_bf16 v[104:107], v[166:169], v[222:225], v[104:107]
	v_mfma_f32_16x16x32_bf16 v[92:95], v[154:157], v[230:233], v[92:95]
	v_mfma_f32_16x16x32_bf16 v[88:91], v[166:169], v[230:233], v[88:91]
	v_mfma_f32_16x16x32_bf16 v[76:79], v[154:157], v[238:241], v[76:79]
	v_mfma_f32_16x16x32_bf16 v[72:75], v[166:169], v[238:241], v[72:75]
	s_setprio 0
	s_setprio 1
	v_mfma_f32_16x16x32_bf16 v[116:119], v[170:173], v[208:211], v[116:119]
	v_mfma_f32_16x16x32_bf16 v[112:115], v[188:191], v[208:211], v[112:115]
	v_mfma_f32_16x16x32_bf16 v[100:103], v[170:173], v[218:221], v[100:103]
	v_mfma_f32_16x16x32_bf16 v[96:99], v[188:191], v[218:221], v[96:99]
	v_mfma_f32_16x16x32_bf16 v[84:87], v[170:173], v[226:229], v[84:87]
	v_mfma_f32_16x16x32_bf16 v[80:83], v[188:191], v[226:229], v[80:83]
	v_mfma_f32_16x16x32_bf16 v[68:71], v[170:173], v[234:237], v[68:71]
	v_mfma_f32_16x16x32_bf16 v[64:67], v[188:191], v[234:237], v[64:67]
	v_mfma_f32_16x16x32_bf16 v[116:119], v[184:187], v[214:217], v[116:119]
	v_mfma_f32_16x16x32_bf16 v[112:115], v[192:195], v[214:217], v[112:115]
	v_mfma_f32_16x16x32_bf16 v[100:103], v[184:187], v[222:225], v[100:103]
	v_mfma_f32_16x16x32_bf16 v[96:99], v[192:195], v[222:225], v[96:99]
	v_mfma_f32_16x16x32_bf16 v[84:87], v[184:187], v[230:233], v[84:87]
	v_mfma_f32_16x16x32_bf16 v[80:83], v[192:195], v[230:233], v[80:83]
	v_mfma_f32_16x16x32_bf16 v[68:71], v[184:187], v[238:241], v[68:71]
	v_mfma_f32_16x16x32_bf16 v[64:67], v[192:195], v[238:241], v[64:67]
	s_setprio 0
	s_barrier
; #define PG8_STAGE(bufoff, gbase, voff) do { _Pragma("unroll") for (int _i = 0; _i < 2; ++_i) \
;         __builtin_amdgcn_global_load_lds((const unsigned*)((const char*)(gbase) + (voff)[_i]), (PG8_LAS unsigned*)(lds + (bufoff) + ldsw + _i * 8192), 16, 0, 0); } while (0)
; #define PG8_LDA(dst, b, h) do { _Pragma("unroll") for (int m = 0; m < 4; ++m) _Pragma("unroll") for (int k = 0; k < 2; ++k) dst[m][k] = *(const PG8_LAS bf16x8*)(lds + PG8_SA(b, h) + aoff + m * 2048 + k * 1024); } while (0)
; #define PG8_WAIT_V(n) asm volatile("s_waitcnt vmcnt(" #n ")" ::: "memory")
; #define PG8_WAIT_L(n) asm volatile("s_waitcnt lgkmcnt(" #n ")" ::: "memory")
; #define PG8_BAR __builtin_amdgcn_s_barrier()
; template <class Epi, class Sched, bool ALIGN_EPI = false, bool SP2 = false>
; __device__ __forceinline__ void gemm_phase(PG8_LAS unsigned char* lds, const Gemm g, const Sched& S, const Epi& E, const int tid) {
;     ...
;         for (int t = 0; t < nt; t += 2) {
;             const bool last = (t == nt - 2);
;             const char* a1 = cA + (size_t)(t + 1) * kstep;
;             const char* a2 = last ? nA : cA + (size_t)(t + 2) * kstep; const char* b2 = last ? nB : cB + (size_t)(t + 2) * kstep;
;             const char* a3 = a2 + kstep; const char* b3 = b2 + kstep;
;             if (last && has_next) S.a_ready(nxt);
;             if constexpr (SP2) {
;             PG8_LDB(B0, 0, 0); PG8_LDB(B1, 0, 1); PG8_SCHED; PG8_LDA(At, 0, 0); PG8_STAGE(PG8_SA(1, 1), a1 + hstep, voffA);
;             PG8_WAIT_V(8); PG8_WAIT_L(0); PG8_BAR; PG8_MMA(0, 0, At, B0); PG8_MMA(0, 1, At, B1); PG8_BAR; PG8_SCHED;
;             PG8_LDA(At, 0, 1); PG8_STAGE(PG8_SB(0, 0), b2, voffB); PG8_STAGE(PG8_SB(0, 1), b2 + hstep, voffB); PG8_STAGE(PG8_SA(0, 0), a2, voffA);
;             PG8_WAIT_V(8); PG8_WAIT_L(0); PG8_BAR; PG8_MMA(1, 0, At, B0); PG8_MMA(1, 1, At, B1); PG8_BAR; PG8_SCHED;
;             PG8_LDB(B0, 1, 0); PG8_LDB(B1, 1, 1); PG8_SCHED; PG8_LDA(At, 1, 0); PG8_STAGE(PG8_SA(0, 1), a2 + hstep, voffA);
;             PG8_WAIT_V(8); PG8_WAIT_L(0); PG8_BAR; PG8_MMA(0, 0, At, B0); PG8_MMA(0, 1, At, B1); PG8_BAR; PG8_SCHED;
;             PG8_LDA(At, 1, 1); PG8_STAGE(PG8_SB(1, 0), b3, voffB); PG8_STAGE(PG8_SB(1, 1), b3 + hstep, voffB); PG8_STAGE(PG8_SA(1, 0), a3, voffA);
;             PG8_WAIT_V(8); PG8_WAIT_L(0); PG8_BAR; PG8_MMA(1, 0, At, B0); PG8_MMA(1, 1, At, B1); PG8_BAR; PG8_SCHED;
	s_add_i32 s20, s56, s27
	v_lshl_add_u64 v[158:159], v[158:159], 0, s[28:29]
	s_mov_b32 m0, s20
	ds_read_b128 v[208:211], v153 offset:49152
	ds_read_b128 v[214:217], v153 offset:50176
	ds_read_b128 v[218:221], v153 offset:51200
	ds_read_b128 v[222:225], v153 offset:52224
	ds_read_b128 v[226:229], v153 offset:53248
	ds_read_b128 v[230:233], v153 offset:54272
	ds_read_b128 v[234:237], v153 offset:55296
	ds_read_b128 v[238:241], v153 offset:56320
	global_load_lds_dwordx4 v[158:159], off
	s_add_i32 m0, s20, 0x2000
	s_add_u32 s16, s16, 0x40080
	v_lshl_add_u64 v[158:159], v[174:175], 0, s[28:29]
	s_addc_u32 s17, s17, 0
	s_add_i32 s20, s57, s27
	global_load_lds_dwordx4 v[158:159], off
	v_lshl_add_u64 v[158:159], s[16:17], 0, v[160:161]
	s_mov_b32 m0, s20
	s_nop 0
	global_load_lds_dwordx4 v[158:159], off
	v_lshl_add_u64 v[158:159], s[16:17], 0, v[132:133]
	s_add_i32 m0, s20, 0x2000
	s_nop 0
	global_load_lds_dwordx4 v[158:159], off
	v_lshl_add_u64 v[158:159], v[178:179], 0, s[28:29]
	s_mov_b32 m0, s81
	s_nop 0
	global_load_lds_dwordx4 v[158:159], off
	v_lshl_add_u64 v[158:159], v[180:181], 0, s[28:29]
	s_mov_b32 m0, s82
	s_nop 0
	global_load_lds_dwordx4 v[158:159], off
	s_waitcnt vmcnt(8)
	s_waitcnt lgkmcnt(0)
	s_setprio 1
	s_barrier
	v_mfma_f32_16x16x32_bf16 v[60:63], v[140:143], v[208:211], v[60:63]
	v_mfma_f32_16x16x32_bf16 v[56:59], v[162:165], v[208:211], v[56:59]
	v_mfma_f32_16x16x32_bf16 v[44:47], v[140:143], v[218:221], v[44:47]
	v_mfma_f32_16x16x32_bf16 v[40:43], v[162:165], v[218:221], v[40:43]
	v_mfma_f32_16x16x32_bf16 v[28:31], v[140:143], v[226:229], v[28:31]
	v_mfma_f32_16x16x32_bf16 v[24:27], v[162:165], v[226:229], v[24:27]
	v_mfma_f32_16x16x32_bf16 v[12:15], v[140:143], v[234:237], v[12:15]
	v_mfma_f32_16x16x32_bf16 v[8:11], v[162:165], v[234:237], v[8:11]
	v_mfma_f32_16x16x32_bf16 v[60:63], v[154:157], v[214:217], v[60:63]
	v_mfma_f32_16x16x32_bf16 v[56:59], v[166:169], v[214:217], v[56:59]
	v_mfma_f32_16x16x32_bf16 v[44:47], v[154:157], v[222:225], v[44:47]
	v_mfma_f32_16x16x32_bf16 v[40:43], v[166:169], v[222:225], v[40:43]
	v_mfma_f32_16x16x32_bf16 v[28:31], v[154:157], v[230:233], v[28:31]
	v_mfma_f32_16x16x32_bf16 v[24:27], v[166:169], v[230:233], v[24:27]
	v_mfma_f32_16x16x32_bf16 v[12:15], v[154:157], v[238:241], v[12:15]
	v_mfma_f32_16x16x32_bf16 v[8:11], v[166:169], v[238:241], v[8:11]
	s_setprio 0
	s_setprio 1
	v_mfma_f32_16x16x32_bf16 v[52:55], v[170:173], v[208:211], v[52:55]
	v_mfma_f32_16x16x32_bf16 v[48:51], v[188:191], v[208:211], v[48:51]
	v_mfma_f32_16x16x32_bf16 v[36:39], v[170:173], v[218:221], v[36:39]
	v_mfma_f32_16x16x32_bf16 v[32:35], v[188:191], v[218:221], v[32:35]
	v_mfma_f32_16x16x32_bf16 v[20:23], v[170:173], v[226:229], v[20:23]
	v_mfma_f32_16x16x32_bf16 v[16:19], v[188:191], v[226:229], v[16:19]
	v_mfma_f32_16x16x32_bf16 v[4:7], v[170:173], v[234:237], v[4:7]
	v_mfma_f32_16x16x32_bf16 v[0:3], v[188:191], v[234:237], v[0:3]
	v_mfma_f32_16x16x32_bf16 v[52:55], v[184:187], v[214:217], v[52:55]
	v_mfma_f32_16x16x32_bf16 v[48:51], v[192:195], v[214:217], v[48:51]
	v_mfma_f32_16x16x32_bf16 v[36:39], v[184:187], v[222:225], v[36:39]
	v_mfma_f32_16x16x32_bf16 v[32:35], v[192:195], v[222:225], v[32:35]
	v_mfma_f32_16x16x32_bf16 v[20:23], v[184:187], v[230:233], v[20:23]
	v_mfma_f32_16x16x32_bf16 v[16:19], v[192:195], v[230:233], v[16:19]
	v_mfma_f32_16x16x32_bf16 v[4:7], v[184:187], v[238:241], v[4:7]
	v_mfma_f32_16x16x32_bf16 v[0:3], v[192:195], v[238:241], v[0:3]
	s_setprio 0
	s_barrier
	s_add_i32 s51, s51, 2
	s_add_u32 s14, s14, 0x100
	s_addc_u32 s15, s15, 0
	s_add_u32 s43, s43, 0x100
	s_addc_u32 s49, s49, 0
	s_cmp_gt_u32 s51, 13
	s_cbranch_scc1 .Lmy_kdone_1
.LBB0_467:
	s_add_u32 s16, s14, 0xfffc0080
	s_addc_u32 s17, s15, -1
	s_add_i32 s56, 0, 0x10000
	s_cmp_eq_u32 s51, 12
	s_cselect_b32 s21, s1, s17
	s_cselect_b32 s20, s36, s16
	v_add_u32_e32 v138, s56, v147
	s_cselect_b32 s17, s37, s49
	s_cselect_b32 s16, s42, s43
	s_add_i32 s58, 0, 0x14000
	ds_read_b128 v[140:143], v138
	ds_read_b128 v[154:157], v138 offset:1024
	ds_read_b128 v[162:165], v138 offset:2048
	ds_read_b128 v[166:169], v138 offset:3072
	v_add_u32_e32 v138, s58, v147
	ds_read_b128 v[170:173], v138
	ds_read_b128 v[184:187], v138 offset:1024
	ds_read_b128 v[188:191], v138 offset:2048
	ds_read_b128 v[192:195], v138 offset:3072
	v_lshl_add_u64 v[158:159], s[14:15], 0, v[134:135]
	s_add_i32 m0, s3, 0xc000
	ds_read_b128 v[208:211], v153
	ds_read_b128 v[214:217], v153 offset:1024
	ds_read_b128 v[218:221], v153 offset:2048
	ds_read_b128 v[222:225], v153 offset:3072
	ds_read_b128 v[226:229], v153 offset:4096
	ds_read_b128 v[230:233], v153 offset:5120
	ds_read_b128 v[234:237], v153 offset:6144
	ds_read_b128 v[238:241], v153 offset:7168
	global_load_lds_dwordx4 v[158:159], off
	v_lshl_add_u64 v[158:159], s[14:15], 0, v[136:137]
	s_add_i32 m0, s3, 0xe000
	s_nop 0
	global_load_lds_dwordx4 v[158:159], off
	s_waitcnt vmcnt(8)
	s_waitcnt lgkmcnt(0)
	s_setprio 1
	s_barrier
; #define PG8_STAGE(bufoff, gbase, voff) do { _Pragma("unroll") for (int _i = 0; _i < 2; ++_i) \
;         __builtin_amdgcn_global_load_lds((const unsigned*)((const char*)(gbase) + (voff)[_i]), (PG8_LAS unsigned*)(lds + (bufoff) + ldsw + _i * 8192), 16, 0, 0); } while (0)
; #define PG8_LDA(dst, b, h) do { _Pragma("unroll") for (int m = 0; m < 4; ++m) _Pragma("unroll") for (int k = 0; k < 2; ++k) dst[m][k] = *(const PG8_LAS bf16x8*)(lds + PG8_SA(b, h) + aoff + m * 2048 + k * 1024); } while (0)
; #define PG8_MMA(ai, bj, At, Bt) do { __builtin_amdgcn_s_setprio(1); _Pragma("unroll") for (int m = 0; m < 4; ++m) _Pragma("unroll") for (int n = 0; n < 2; ++n) _Pragma("unroll") for (int k = 0; k < 2; ++k) \
;         acc[ai][bj][m][n] = __builtin_amdgcn_mfma_f32_16x16x32_bf16(Bt[n][k], At[m][k], acc[ai][bj][m][n], 0, 0, 0); __builtin_amdgcn_s_setprio(0); } while (0)
; #define PG8_WAIT_V(n) asm volatile("s_waitcnt vmcnt(" #n ")" ::: "memory")
; #define PG8_WAIT_L(n) asm volatile("s_waitcnt lgkmcnt(" #n ")" ::: "memory")
; #define PG8_BAR __builtin_amdgcn_s_barrier()
; #define PG8_SCHED __builtin_amdgcn_sched_barrier(0)
; template <class Epi, class Sched, bool ALIGN_EPI = false, bool SP2 = false>
; __device__ __forceinline__ void gemm_phase(PG8_LAS unsigned char* lds, const Gemm g, const Sched& S, const Epi& E, const int tid) {
;     ...
;             PG8_WAIT_V(8); PG8_WAIT_L(0); PG8_BAR; PG8_MMA(0, 0, At, B0); PG8_MMA(0, 1, At, B1); PG8_BAR; PG8_SCHED;
;             PG8_LDA(At, 0, 1); PG8_STAGE(PG8_SB(0, 0), b2, voffB); PG8_STAGE(PG8_SB(0, 1), b2 + hstep, voffB); PG8_STAGE(PG8_SA(0, 0), a2, voffA);
;             PG8_WAIT_V(8); PG8_WAIT_L(0); PG8_BAR; PG8_MMA(1, 0, At, B0); PG8_MMA(1, 1, At, B1); PG8_BAR; PG8_SCHED;
	v_mfma_f32_16x16x32_bf16 v[124:127], v[140:143], v[208:211], v[124:127]
	v_mfma_f32_16x16x32_bf16 v[120:123], v[162:165], v[208:211], v[120:123]
	v_mfma_f32_16x16x32_bf16 v[108:111], v[140:143], v[218:221], v[108:111]
	v_mfma_f32_16x16x32_bf16 v[104:107], v[162:165], v[218:221], v[104:107]
	v_mfma_f32_16x16x32_bf16 v[92:95], v[140:143], v[226:229], v[92:95]
	v_mfma_f32_16x16x32_bf16 v[88:91], v[162:165], v[226:229], v[88:91]
	v_mfma_f32_16x16x32_bf16 v[76:79], v[140:143], v[234:237], v[76:79]
	v_mfma_f32_16x16x32_bf16 v[72:75], v[162:165], v[234:237], v[72:75]
	v_mfma_f32_16x16x32_bf16 v[124:127], v[154:157], v[214:217], v[124:127]
	v_mfma_f32_16x16x32_bf16 v[120:123], v[166:169], v[214:217], v[120:123]
	v_mfma_f32_16x16x32_bf16 v[108:111], v[154:157], v[222:225], v[108:111]
	v_mfma_f32_16x16x32_bf16 v[104:107], v[166:169], v[222:225], v[104:107]
	v_mfma_f32_16x16x32_bf16 v[92:95], v[154:157], v[230:233], v[92:95]
	v_mfma_f32_16x16x32_bf16 v[88:91], v[166:169], v[230:233], v[88:91]
	v_mfma_f32_16x16x32_bf16 v[76:79], v[154:157], v[238:241], v[76:79]
	v_mfma_f32_16x16x32_bf16 v[72:75], v[166:169], v[238:241], v[72:75]
	s_setprio 0
	s_setprio 1
	v_mfma_f32_16x16x32_bf16 v[116:119], v[170:173], v[208:211], v[116:119]
	v_mfma_f32_16x16x32_bf16 v[112:115], v[188:191], v[208:211], v[112:115]
	v_mfma_f32_16x16x32_bf16 v[100:103], v[170:173], v[218:221], v[100:103]
	v_mfma_f32_16x16x32_bf16 v[96:99], v[188:191], v[218:221], v[96:99]
	v_mfma_f32_16x16x32_bf16 v[84:87], v[170:173], v[226:229], v[84:87]
	v_mfma_f32_16x16x32_bf16 v[80:83], v[188:191], v[226:229], v[80:83]
	v_mfma_f32_16x16x32_bf16 v[68:71], v[170:173], v[234:237], v[68:71]
	v_mfma_f32_16x16x32_bf16 v[64:67], v[188:191], v[234:237], v[64:67]
	v_mfma_f32_16x16x32_bf16 v[116:119], v[184:187], v[214:217], v[116:119]
	v_mfma_f32_16x16x32_bf16 v[112:115], v[192:195], v[214:217], v[112:115]
	v_mfma_f32_16x16x32_bf16 v[100:103], v[184:187], v[222:225], v[100:103]
	v_mfma_f32_16x16x32_bf16 v[96:99], v[192:195], v[222:225], v[96:99]
	v_mfma_f32_16x16x32_bf16 v[84:87], v[184:187], v[230:233], v[84:87]
	v_mfma_f32_16x16x32_bf16 v[80:83], v[192:195], v[230:233], v[80:83]
	v_mfma_f32_16x16x32_bf16 v[68:71], v[184:187], v[238:241], v[68:71]
	v_mfma_f32_16x16x32_bf16 v[64:67], v[192:195], v[238:241], v[64:67]
	s_setprio 0
	s_barrier
	s_add_i32 s56, s56, s27
	v_lshl_add_u64 v[158:159], s[16:17], 0, v[160:161]
	s_mov_b32 m0, s56
	ds_read_b128 v[208:211], v153 offset:16384
	ds_read_b128 v[214:217], v153 offset:17408
	ds_read_b128 v[218:221], v153 offset:18432
	ds_read_b128 v[222:225], v153 offset:19456
	ds_read_b128 v[226:229], v153 offset:20480
	ds_read_b128 v[230:233], v153 offset:21504
	ds_read_b128 v[234:237], v153 offset:22528
	ds_read_b128 v[238:241], v153 offset:23552
	global_load_lds_dwordx4 v[158:159], off
	s_add_i32 m0, s56, 0x2000
	s_add_u32 s56, s16, 0x40000
	v_lshl_add_u64 v[174:175], s[16:17], 0, v[132:133]
	s_addc_u32 s57, s17, 0
	s_add_i32 s58, s58, s27
	global_load_lds_dwordx4 v[174:175], off
	v_lshl_add_u64 v[178:179], s[56:57], 0, v[160:161]
	s_mov_b32 m0, s58
	v_lshl_add_u64 v[180:181], s[20:21], 0, v[130:131]
	global_load_lds_dwordx4 v[178:179], off
	v_lshl_add_u64 v[178:179], s[56:57], 0, v[132:133]
	s_add_i32 m0, s58, 0x2000
	s_nop 0
	global_load_lds_dwordx4 v[178:179], off
	v_lshl_add_u64 v[178:179], s[20:21], 0, v[128:129]
	s_mov_b32 m0, s3
	s_nop 0
	global_load_lds_dwordx4 v[178:179], off
	s_mov_b32 m0, s30
	s_nop 0
	global_load_lds_dwordx4 v[180:181], off
	s_waitcnt vmcnt(8)
	s_waitcnt lgkmcnt(0)
	s_setprio 1
	s_barrier
	v_mfma_f32_16x16x32_bf16 v[60:63], v[140:143], v[208:211], v[60:63]
	v_mfma_f32_16x16x32_bf16 v[56:59], v[162:165], v[208:211], v[56:59]
	v_mfma_f32_16x16x32_bf16 v[44:47], v[140:143], v[218:221], v[44:47]
	v_mfma_f32_16x16x32_bf16 v[40:43], v[162:165], v[218:221], v[40:43]
	v_mfma_f32_16x16x32_bf16 v[28:31], v[140:143], v[226:229], v[28:31]
	v_mfma_f32_16x16x32_bf16 v[24:27], v[162:165], v[226:229], v[24:27]
	v_mfma_f32_16x16x32_bf16 v[12:15], v[140:143], v[234:237], v[12:15]
	v_mfma_f32_16x16x32_bf16 v[8:11], v[162:165], v[234:237], v[8:11]
	v_mfma_f32_16x16x32_bf16 v[60:63], v[154:157], v[214:217], v[60:63]
	v_mfma_f32_16x16x32_bf16 v[56:59], v[166:169], v[214:217], v[56:59]
	v_mfma_f32_16x16x32_bf16 v[44:47], v[154:157], v[222:225], v[44:47]
	v_mfma_f32_16x16x32_bf16 v[40:43], v[166:169], v[222:225], v[40:43]
	v_mfma_f32_16x16x32_bf16 v[28:31], v[154:157], v[230:233], v[28:31]
	v_mfma_f32_16x16x32_bf16 v[24:27], v[166:169], v[230:233], v[24:27]
	v_mfma_f32_16x16x32_bf16 v[12:15], v[154:157], v[238:241], v[12:15]
	v_mfma_f32_16x16x32_bf16 v[8:11], v[166:169], v[238:241], v[8:11]
	s_setprio 0
	s_setprio 1
	v_mfma_f32_16x16x32_bf16 v[52:55], v[170:173], v[208:211], v[52:55]
	v_mfma_f32_16x16x32_bf16 v[48:51], v[188:191], v[208:211], v[48:51]
	v_mfma_f32_16x16x32_bf16 v[36:39], v[170:173], v[218:221], v[36:39]
	v_mfma_f32_16x16x32_bf16 v[32:35], v[188:191], v[218:221], v[32:35]
	v_mfma_f32_16x16x32_bf16 v[20:23], v[170:173], v[226:229], v[20:23]
	v_mfma_f32_16x16x32_bf16 v[16:19], v[188:191], v[226:229], v[16:19]
	v_mfma_f32_16x16x32_bf16 v[4:7], v[170:173], v[234:237], v[4:7]
	v_mfma_f32_16x16x32_bf16 v[0:3], v[188:191], v[234:237], v[0:3]
	v_mfma_f32_16x16x32_bf16 v[52:55], v[184:187], v[214:217], v[52:55]
	v_mfma_f32_16x16x32_bf16 v[48:51], v[192:195], v[214:217], v[48:51]
	v_mfma_f32_16x16x32_bf16 v[36:39], v[184:187], v[222:225], v[36:39]
	v_mfma_f32_16x16x32_bf16 v[32:35], v[192:195], v[222:225], v[32:35]
	v_mfma_f32_16x16x32_bf16 v[20:23], v[184:187], v[230:233], v[20:23]
	v_mfma_f32_16x16x32_bf16 v[16:19], v[192:195], v[230:233], v[16:19]
	v_mfma_f32_16x16x32_bf16 v[4:7], v[184:187], v[238:241], v[4:7]
	v_mfma_f32_16x16x32_bf16 v[0:3], v[192:195], v[238:241], v[0:3]
	s_setprio 0
	s_barrier
; #define PG8_STAGE(bufoff, gbase, voff) do { _Pragma("unroll") for (int _i = 0; _i < 2; ++_i) \
;         __builtin_amdgcn_global_load_lds((const unsigned*)((const char*)(gbase) + (voff)[_i]), (PG8_LAS unsigned*)(lds + (bufoff) + ldsw + _i * 8192), 16, 0, 0); } while (0)
; #define PG8_LDA(dst, b, h) do { _Pragma("unroll") for (int m = 0; m < 4; ++m) _Pragma("unroll") for (int k = 0; k < 2; ++k) dst[m][k] = *(const PG8_LAS bf16x8*)(lds + PG8_SA(b, h) + aoff + m * 2048 + k * 1024); } while (0)
; #define PG8_LDB(dst, b, h) do { _Pragma("unroll") for (int n = 0; n < 2; ++n) _Pragma("unroll") for (int k = 0; k < 2; ++k) dst[n][k] = *(const PG8_LAS bf16x8*)(lds + PG8_SB(b, h) + boff + n * 2048 + k * 1024); } while (0)
; #define PG8_MMA(ai, bj, At, Bt) do { __builtin_amdgcn_s_setprio(1); _Pragma("unroll") for (int m = 0; m < 4; ++m) _Pragma("unroll") for (int n = 0; n < 2; ++n) _Pragma("unroll") for (int k = 0; k < 2; ++k) \
;         acc[ai][bj][m][n] = __builtin_amdgcn_mfma_f32_16x16x32_bf16(Bt[n][k], At[m][k], acc[ai][bj][m][n], 0, 0, 0); __builtin_amdgcn_s_setprio(0); } while (0)
; #define PG8_WAIT_V(n) asm volatile("s_waitcnt vmcnt(" #n ")" ::: "memory")
; #define PG8_WAIT_L(n) asm volatile("s_waitcnt lgkmcnt(" #n ")" ::: "memory")
; #define PG8_BAR __builtin_amdgcn_s_barrier()
; #define PG8_SCHED __builtin_amdgcn_sched_barrier(0)
; template <class Epi, class Sched, bool ALIGN_EPI = false, bool SP2 = false>
; __device__ __forceinline__ void gemm_phase(PG8_LAS unsigned char* lds, const Gemm g, const Sched& S, const Epi& E, const int tid) {
;     ...
;             PG8_LDB(B0, 1, 0); PG8_LDB(B1, 1, 1); PG8_SCHED; PG8_LDA(At, 1, 0); PG8_STAGE(PG8_SA(0, 1), a2 + hstep, voffA);
;             PG8_WAIT_V(8); PG8_WAIT_L(0); PG8_BAR; PG8_MMA(0, 0, At, B0); PG8_MMA(0, 1, At, B1); PG8_BAR; PG8_SCHED;
	s_add_i32 s56, 0, 0x18000
	v_add_u32_e32 v138, s56, v147
	s_add_i32 s57, 0, 0x1c000
	ds_read_b128 v[140:143], v138
	ds_read_b128 v[154:157], v138 offset:1024
	ds_read_b128 v[162:165], v138 offset:2048
	ds_read_b128 v[166:169], v138 offset:3072
	v_add_u32_e32 v138, s57, v147
	ds_read_b128 v[170:173], v138
	ds_read_b128 v[184:187], v138 offset:1024
	ds_read_b128 v[188:191], v138 offset:2048
	ds_read_b128 v[192:195], v138 offset:3072
	s_add_u32 s20, s20, 0x40000
	s_addc_u32 s21, s21, 0
	s_mov_b32 m0, s31
	v_lshl_add_u64 v[196:197], s[20:21], 0, v[128:129]
	ds_read_b128 v[208:211], v153 offset:32768
	ds_read_b128 v[214:217], v153 offset:33792
	ds_read_b128 v[218:221], v153 offset:34816
	ds_read_b128 v[222:225], v153 offset:35840
	ds_read_b128 v[226:229], v153 offset:36864
	ds_read_b128 v[230:233], v153 offset:37888
	ds_read_b128 v[234:237], v153 offset:38912
	ds_read_b128 v[238:241], v153 offset:39936
	global_load_lds_dwordx4 v[196:197], off
	v_lshl_add_u64 v[196:197], s[20:21], 0, v[130:131]
	s_mov_b32 m0, s34
	s_nop 0
	global_load_lds_dwordx4 v[196:197], off
	s_waitcnt vmcnt(8)
	s_waitcnt lgkmcnt(0)
	s_setprio 1
	s_barrier
	v_mfma_f32_16x16x32_bf16 v[124:127], v[140:143], v[208:211], v[124:127]
	v_mfma_f32_16x16x32_bf16 v[120:123], v[162:165], v[208:211], v[120:123]
	v_mfma_f32_16x16x32_bf16 v[108:111], v[140:143], v[218:221], v[108:111]
	v_mfma_f32_16x16x32_bf16 v[104:107], v[162:165], v[218:221], v[104:107]
	v_mfma_f32_16x16x32_bf16 v[92:95], v[140:143], v[226:229], v[92:95]
	v_mfma_f32_16x16x32_bf16 v[88:91], v[162:165], v[226:229], v[88:91]
	v_mfma_f32_16x16x32_bf16 v[76:79], v[140:143], v[234:237], v[76:79]
	v_mfma_f32_16x16x32_bf16 v[72:75], v[162:165], v[234:237], v[72:75]
	v_mfma_f32_16x16x32_bf16 v[124:127], v[154:157], v[214:217], v[124:127]
	v_mfma_f32_16x16x32_bf16 v[120:123], v[166:169], v[214:217], v[120:123]
	v_mfma_f32_16x16x32_bf16 v[108:111], v[154:157], v[222:225], v[108:111]
	v_mfma_f32_16x16x32_bf16 v[104:107], v[166:169], v[222:225], v[104:107]
	v_mfma_f32_16x16x32_bf16 v[92:95], v[154:157], v[230:233], v[92:95]
	v_mfma_f32_16x16x32_bf16 v[88:91], v[166:169], v[230:233], v[88:91]
	v_mfma_f32_16x16x32_bf16 v[76:79], v[154:157], v[238:241], v[76:79]
	v_mfma_f32_16x16x32_bf16 v[72:75], v[166:169], v[238:241], v[72:75]
	s_setprio 0
	s_setprio 1
	v_mfma_f32_16x16x32_bf16 v[116:119], v[170:173], v[208:211], v[116:119]
	v_mfma_f32_16x16x32_bf16 v[112:115], v[188:191], v[208:211], v[112:115]
	v_mfma_f32_16x16x32_bf16 v[100:103], v[170:173], v[218:221], v[100:103]
	v_mfma_f32_16x16x32_bf16 v[96:99], v[188:191], v[218:221], v[96:99]
	v_mfma_f32_16x16x32_bf16 v[84:87], v[170:173], v[226:229], v[84:87]
	v_mfma_f32_16x16x32_bf16 v[80:83], v[188:191], v[226:229], v[80:83]
	v_mfma_f32_16x16x32_bf16 v[68:71], v[170:173], v[234:237], v[68:71]
	v_mfma_f32_16x16x32_bf16 v[64:67], v[188:191], v[234:237], v[64:67]
	v_mfma_f32_16x16x32_bf16 v[116:119], v[184:187], v[214:217], v[116:119]
	v_mfma_f32_16x16x32_bf16 v[112:115], v[192:195], v[214:217], v[112:115]
	v_mfma_f32_16x16x32_bf16 v[100:103], v[184:187], v[222:225], v[100:103]
	v_mfma_f32_16x16x32_bf16 v[96:99], v[192:195], v[222:225], v[96:99]
	v_mfma_f32_16x16x32_bf16 v[84:87], v[184:187], v[230:233], v[84:87]
	v_mfma_f32_16x16x32_bf16 v[80:83], v[192:195], v[230:233], v[80:83]
	v_mfma_f32_16x16x32_bf16 v[68:71], v[184:187], v[238:241], v[68:71]
	v_mfma_f32_16x16x32_bf16 v[64:67], v[192:195], v[238:241], v[64:67]
	s_setprio 0
	s_barrier
; #define PG8_STAGE(bufoff, gbase, voff) do { _Pragma("unroll") for (int _i = 0; _i < 2; ++_i) \
;         __builtin_amdgcn_global_load_lds((const unsigned*)((const char*)(gbase) + (voff)[_i]), (PG8_LAS unsigned*)(lds + (bufoff) + ldsw + _i * 8192), 16, 0, 0); } while (0)
; #define PG8_LDA(dst, b, h) do { _Pragma("unroll") for (int m = 0; m < 4; ++m) _Pragma("unroll") for (int k = 0; k < 2; ++k) dst[m][k] = *(const PG8_LAS bf16x8*)(lds + PG8_SA(b, h) + aoff + m * 2048 + k * 1024); } while (0)
; #define PG8_MMA(ai, bj, At, Bt) do { __builtin_amdgcn_s_setprio(1); _Pragma("unroll") for (int m = 0; m < 4; ++m) _Pragma("unroll") for (int n = 0; n < 2; ++n) _Pragma("unroll") for (int k = 0; k < 2; ++k) \
;         acc[ai][bj][m][n] = __builtin_amdgcn_mfma_f32_16x16x32_bf16(Bt[n][k], At[m][k], acc[ai][bj][m][n], 0, 0, 0); __builtin_amdgcn_s_setprio(0); } while (0)
; #define PG8_WAIT_V(n) asm volatile("s_waitcnt vmcnt(" #n ")" ::: "memory")
; #define PG8_WAIT_L(n) asm volatile("s_waitcnt lgkmcnt(" #n ")" ::: "memory")
; #define PG8_BAR __builtin_amdgcn_s_barrier()
; #define PG8_SCHED __builtin_amdgcn_sched_barrier(0)
; template <class Epi, class Sched, bool ALIGN_EPI = false, bool SP2 = false>
; __device__ __forceinline__ void gemm_phase(PG8_LAS unsigned char* lds, const Gemm g, const Sched& S, const Epi& E, const int tid) {
;     ...
;             PG8_LDA(At, 1, 1); PG8_STAGE(PG8_SB(1, 0), b3, voffB); PG8_STAGE(PG8_SB(1, 1), b3 + hstep, voffB); PG8_STAGE(PG8_SA(1, 0), a3, voffA);
;             PG8_WAIT_V(8); PG8_WAIT_L(0); PG8_BAR; PG8_MMA(1, 0, At, B0); PG8_MMA(1, 1, At, B1); PG8_BAR; PG8_SCHED;
	s_add_i32 s20, s56, s27
	v_lshl_add_u64 v[158:159], v[158:159], 0, s[28:29]
	s_mov_b32 m0, s20
	ds_read_b128 v[208:211], v153 offset:49152
	ds_read_b128 v[214:217], v153 offset:50176
	ds_read_b128 v[218:221], v153 offset:51200
	ds_read_b128 v[222:225], v153 offset:52224
	ds_read_b128 v[226:229], v153 offset:53248
	ds_read_b128 v[230:233], v153 offset:54272
	ds_read_b128 v[234:237], v153 offset:55296
	ds_read_b128 v[238:241], v153 offset:56320
	global_load_lds_dwordx4 v[158:159], off
	s_add_i32 m0, s20, 0x2000
	s_add_u32 s16, s16, 0x40080
	v_lshl_add_u64 v[158:159], v[174:175], 0, s[28:29]
	s_addc_u32 s17, s17, 0
	s_add_i32 s20, s57, s27
	global_load_lds_dwordx4 v[158:159], off
	v_lshl_add_u64 v[158:159], s[16:17], 0, v[160:161]
	s_mov_b32 m0, s20
	s_nop 0
	global_load_lds_dwordx4 v[158:159], off
	v_lshl_add_u64 v[158:159], s[16:17], 0, v[132:133]
	s_add_i32 m0, s20, 0x2000
	s_nop 0
	global_load_lds_dwordx4 v[158:159], off
	v_lshl_add_u64 v[158:159], v[178:179], 0, s[28:29]
	s_mov_b32 m0, s81
	s_nop 0
	global_load_lds_dwordx4 v[158:159], off
	v_lshl_add_u64 v[158:159], v[180:181], 0, s[28:29]
	s_mov_b32 m0, s82
	s_nop 0
	global_load_lds_dwordx4 v[158:159], off
	s_waitcnt vmcnt(8)
	s_waitcnt lgkmcnt(0)
	s_setprio 1
	s_barrier
	v_mfma_f32_16x16x32_bf16 v[60:63], v[140:143], v[208:211], v[60:63]
	v_mfma_f32_16x16x32_bf16 v[56:59], v[162:165], v[208:211], v[56:59]
	v_mfma_f32_16x16x32_bf16 v[44:47], v[140:143], v[218:221], v[44:47]
	v_mfma_f32_16x16x32_bf16 v[40:43], v[162:165], v[218:221], v[40:43]
	v_mfma_f32_16x16x32_bf16 v[28:31], v[140:143], v[226:229], v[28:31]
	v_mfma_f32_16x16x32_bf16 v[24:27], v[162:165], v[226:229], v[24:27]
	v_mfma_f32_16x16x32_bf16 v[12:15], v[140:143], v[234:237], v[12:15]
	v_mfma_f32_16x16x32_bf16 v[8:11], v[162:165], v[234:237], v[8:11]
	v_mfma_f32_16x16x32_bf16 v[60:63], v[154:157], v[214:217], v[60:63]
	v_mfma_f32_16x16x32_bf16 v[56:59], v[166:169], v[214:217], v[56:59]
	v_mfma_f32_16x16x32_bf16 v[44:47], v[154:157], v[222:225], v[44:47]
	v_mfma_f32_16x16x32_bf16 v[40:43], v[166:169], v[222:225], v[40:43]
	v_mfma_f32_16x16x32_bf16 v[28:31], v[154:157], v[230:233], v[28:31]
	v_mfma_f32_16x16x32_bf16 v[24:27], v[166:169], v[230:233], v[24:27]
	v_mfma_f32_16x16x32_bf16 v[12:15], v[154:157], v[238:241], v[12:15]
	v_mfma_f32_16x16x32_bf16 v[8:11], v[166:169], v[238:241], v[8:11]
	s_setprio 0
	s_setprio 1
	v_mfma_f32_16x16x32_bf16 v[52:55], v[170:173], v[208:211], v[52:55]
	v_mfma_f32_16x16x32_bf16 v[48:51], v[188:191], v[208:211], v[48:51]
	v_mfma_f32_16x16x32_bf16 v[36:39], v[170:173], v[218:221], v[36:39]
	v_mfma_f32_16x16x32_bf16 v[32:35], v[188:191], v[218:221], v[32:35]
	v_mfma_f32_16x16x32_bf16 v[20:23], v[170:173], v[226:229], v[20:23]
	v_mfma_f32_16x16x32_bf16 v[16:19], v[188:191], v[226:229], v[16:19]
	v_mfma_f32_16x16x32_bf16 v[4:7], v[170:173], v[234:237], v[4:7]
	v_mfma_f32_16x16x32_bf16 v[0:3], v[188:191], v[234:237], v[0:3]
	v_mfma_f32_16x16x32_bf16 v[52:55], v[184:187], v[214:217], v[52:55]
	v_mfma_f32_16x16x32_bf16 v[48:51], v[192:195], v[214:217], v[48:51]
	v_mfma_f32_16x16x32_bf16 v[36:39], v[184:187], v[222:225], v[36:39]
	v_mfma_f32_16x16x32_bf16 v[32:35], v[192:195], v[222:225], v[32:35]
	v_mfma_f32_16x16x32_bf16 v[20:23], v[184:187], v[230:233], v[20:23]
	v_mfma_f32_16x16x32_bf16 v[16:19], v[192:195], v[230:233], v[16:19]
	v_mfma_f32_16x16x32_bf16 v[4:7], v[184:187], v[238:241], v[4:7]
	v_mfma_f32_16x16x32_bf16 v[0:3], v[192:195], v[238:241], v[0:3]
	s_setprio 0
	s_barrier
	s_add_i32 s51, s51, 2
	s_add_u32 s14, s14, 0x100
	s_addc_u32 s15, s15, 0
	s_add_u32 s43, s43, 0x100
	s_addc_u32 s49, s49, 0
	s_cmp_gt_u32 s51, 13
	s_cbranch_scc0 .LBB0_467

; #define PG8_STAGE(bufoff, gbase, voff) do { _Pragma("unroll") for (int _i = 0; _i < 2; ++_i) \
;         __builtin_amdgcn_global_load_lds((const unsigned*)((const char*)(gbase) + (voff)[_i]), (PG8_LAS unsigned*)(lds + (bufoff) + ldsw + _i * 8192), 16, 0, 0); } while (0)
; #define PG8_LDA(dst, b, h) do { _Pragma("unroll") for (int m = 0; m < 4; ++m) _Pragma("unroll") for (int k = 0; k < 2; ++k) dst[m][k] = *(const PG8_LAS bf16x8*)(lds + PG8_SA(b, h) + aoff + m * 2048 + k * 1024); } while (0)
; #define PG8_LDB(dst, b, h) do { _Pragma("unroll") for (int n = 0; n < 2; ++n) _Pragma("unroll") for (int k = 0; k < 2; ++k) dst[n][k] = *(const PG8_LAS bf16x8*)(lds + PG8_SB(b, h) + boff + n * 2048 + k * 1024); } while (0)
; #define PG8_WAIT_V(n) asm volatile("s_waitcnt vmcnt(" #n ")" ::: "memory")
; #define PG8_WAIT_L(n) asm volatile("s_waitcnt lgkmcnt(" #n ")" ::: "memory")
; #define PG8_BAR __builtin_amdgcn_s_barrier()
; #define PG8_SCHED __builtin_amdgcn_sched_barrier(0)
; template <class Epi, class Sched, bool ALIGN_EPI = false, bool SP2 = false>
; __device__ __forceinline__ void gemm_phase(PG8_LAS unsigned char* lds, const Gemm g, const Sched& S, const Epi& E, const int tid) {
;     ...
;         const bool has_next = S.next(ui + 1, nxt);
;         const char* nA = has_next ? (const char*)g.A + (size_t)nxt.pm * tstep : cA; const char* nB = has_next ? (const char*)g.Bt + (size_t)nxt.pn * tstep : cB;
;         for (int t = 0; t < nt; t += 2) {
;             const bool last = (t == nt - 2);
;             const char* a1 = cA + (size_t)(t + 1) * kstep;
;             const char* a2 = last ? nA : cA + (size_t)(t + 2) * kstep; const char* b2 = last ? nB : cB + (size_t)(t + 2) * kstep;
;             const char* a3 = a2 + kstep; const char* b3 = b2 + kstep;
;             if (last && has_next) S.a_ready(nxt);
;             if constexpr (SP2) {
;             PG8_LDB(B0, 0, 0); PG8_LDB(B1, 0, 1); PG8_SCHED; PG8_LDA(At, 0, 0); PG8_STAGE(PG8_SA(1, 1), a1 + hstep, voffA);
;             PG8_WAIT_V(8); PG8_WAIT_L(0); PG8_BAR; PG8_MMA(0, 0, At, B0); PG8_MMA(0, 1, At, B1); PG8_BAR; PG8_SCHED;
;             PG8_LDA(At, 0, 1); PG8_STAGE(PG8_SB(0, 0), b2, voffB); PG8_STAGE(PG8_SB(0, 1), b2 + hstep, voffB); PG8_STAGE(PG8_SA(0, 0), a2, voffA);
;             PG8_WAIT_V(8); PG8_WAIT_L(0); PG8_BAR; PG8_MMA(1, 0, At, B0); PG8_MMA(1, 1, At, B1); PG8_BAR; PG8_SCHED;
.LBB0_516:
	s_ashr_i32 s11, s10, 31
	s_lshl_b64 s[12:13], s[10:11], 19
	s_add_u32 s12, s27, s12
	s_addc_u32 s13, s26, s13
	s_and_b64 s[14:15], s[40:41], exec
	s_cselect_b32 s11, s13, s19
	s_cselect_b32 s36, s12, s18
	s_ashr_i32 s9, s8, 31
	s_lshl_b64 s[14:15], s[8:9], 19
	s_add_u32 s14, s30, s14
	s_addc_u32 s15, s31, s15
	s_and_b64 s[22:23], s[40:41], exec
	s_cselect_b32 s9, s15, s21
	s_cselect_b32 s37, s14, s20
	s_add_u32 s18, s18, 0x40080
	s_addc_u32 s19, s19, 0
	s_add_u32 s42, s20, 0x100
	s_addc_u32 s43, s21, 0
	s_mov_b32 s51, -2
	s_add_u32 s20, s18, 0xfffc0080
	s_addc_u32 s21, s19, -1
	s_add_i32 s52, 0, 0x10000
	s_cmp_eq_u32 s51, 12
	s_cselect_b32 s23, s11, s21
	s_cselect_b32 s22, s36, s20
	v_add_u32_e32 v138, s52, v141
	s_cselect_b32 s21, s9, s43
	s_cselect_b32 s20, s37, s42
	s_add_i32 s56, 0, 0x14000
	ds_read_b128 v[150:153], v138
	ds_read_b128 v[154:157], v138 offset:1024
	ds_read_b128 v[162:165], v138 offset:2048
	ds_read_b128 v[166:169], v138 offset:3072
	v_add_u32_e32 v138, s56, v141
	ds_read_b128 v[170:173], v138
	ds_read_b128 v[184:187], v138 offset:1024
	ds_read_b128 v[188:191], v138 offset:2048
	ds_read_b128 v[192:195], v138 offset:3072
	v_lshl_add_u64 v[158:159], s[18:19], 0, v[134:135]
	s_add_i32 m0, s35, 0xc000
	ds_read_b128 v[208:211], v149
	ds_read_b128 v[214:217], v149 offset:1024
	ds_read_b128 v[218:221], v149 offset:2048
	ds_read_b128 v[222:225], v149 offset:3072
	ds_read_b128 v[226:229], v149 offset:4096
	ds_read_b128 v[230:233], v149 offset:5120
	ds_read_b128 v[234:237], v149 offset:6144
	ds_read_b128 v[238:241], v149 offset:7168
	global_load_lds_dwordx4 v[158:159], off
	v_lshl_add_u64 v[158:159], s[18:19], 0, v[136:137]
	s_add_i32 m0, s35, 0xe000
	s_nop 0
	global_load_lds_dwordx4 v[158:159], off
	s_waitcnt vmcnt(16)
	s_waitcnt lgkmcnt(0)
	s_setprio 1
	s_barrier
	v_mfma_f32_16x16x32_bf16 v[124:127], v[150:153], v[208:211], 0
	v_mfma_f32_16x16x32_bf16 v[116:119], v[162:165], v[208:211], 0
	v_mfma_f32_16x16x32_bf16 v[108:111], v[150:153], v[218:221], 0
	v_mfma_f32_16x16x32_bf16 v[100:103], v[162:165], v[218:221], 0
	v_mfma_f32_16x16x32_bf16 v[92:95], v[150:153], v[226:229], 0
	v_mfma_f32_16x16x32_bf16 v[84:87], v[162:165], v[226:229], 0
	v_mfma_f32_16x16x32_bf16 v[76:79], v[150:153], v[234:237], 0
	v_mfma_f32_16x16x32_bf16 v[68:71], v[162:165], v[234:237], 0
	v_mfma_f32_16x16x32_bf16 v[124:127], v[154:157], v[214:217], v[124:127]
	v_mfma_f32_16x16x32_bf16 v[116:119], v[166:169], v[214:217], v[116:119]
	v_mfma_f32_16x16x32_bf16 v[108:111], v[154:157], v[222:225], v[108:111]
	v_mfma_f32_16x16x32_bf16 v[100:103], v[166:169], v[222:225], v[100:103]
	v_mfma_f32_16x16x32_bf16 v[92:95], v[154:157], v[230:233], v[92:95]
	v_mfma_f32_16x16x32_bf16 v[84:87], v[166:169], v[230:233], v[84:87]
	v_mfma_f32_16x16x32_bf16 v[76:79], v[154:157], v[238:241], v[76:79]
	v_mfma_f32_16x16x32_bf16 v[68:71], v[166:169], v[238:241], v[68:71]
	s_setprio 0
	s_setprio 1
	v_mfma_f32_16x16x32_bf16 v[120:123], v[170:173], v[208:211], 0
	v_mfma_f32_16x16x32_bf16 v[112:115], v[188:191], v[208:211], 0
	v_mfma_f32_16x16x32_bf16 v[104:107], v[170:173], v[218:221], 0
	v_mfma_f32_16x16x32_bf16 v[96:99], v[188:191], v[218:221], 0
	v_mfma_f32_16x16x32_bf16 v[88:91], v[170:173], v[226:229], 0
	v_mfma_f32_16x16x32_bf16 v[80:83], v[188:191], v[226:229], 0
	v_mfma_f32_16x16x32_bf16 v[72:75], v[170:173], v[234:237], 0
	v_mfma_f32_16x16x32_bf16 v[64:67], v[188:191], v[234:237], 0
	v_mfma_f32_16x16x32_bf16 v[120:123], v[184:187], v[214:217], v[120:123]
	v_mfma_f32_16x16x32_bf16 v[112:115], v[192:195], v[214:217], v[112:115]
	v_mfma_f32_16x16x32_bf16 v[104:107], v[184:187], v[222:225], v[104:107]
	v_mfma_f32_16x16x32_bf16 v[96:99], v[192:195], v[222:225], v[96:99]
	v_mfma_f32_16x16x32_bf16 v[88:91], v[184:187], v[230:233], v[88:91]
	v_mfma_f32_16x16x32_bf16 v[80:83], v[192:195], v[230:233], v[80:83]
	v_mfma_f32_16x16x32_bf16 v[72:75], v[184:187], v[238:241], v[72:75]
	v_mfma_f32_16x16x32_bf16 v[64:67], v[192:195], v[238:241], v[64:67]
	s_setprio 0
	s_barrier
	s_add_i32 s52, s52, s34
	v_lshl_add_u64 v[158:159], s[20:21], 0, v[160:161]
	s_mov_b32 m0, s52
	ds_read_b128 v[208:211], v149 offset:16384
	ds_read_b128 v[214:217], v149 offset:17408
	ds_read_b128 v[218:221], v149 offset:18432
	ds_read_b128 v[222:225], v149 offset:19456
	ds_read_b128 v[226:229], v149 offset:20480
	ds_read_b128 v[230:233], v149 offset:21504
	ds_read_b128 v[234:237], v149 offset:22528
	ds_read_b128 v[238:241], v149 offset:23552
	global_load_lds_dwordx4 v[158:159], off
	s_add_i32 m0, s52, 0x2000
	s_add_u32 s52, s20, 0x40000
	v_lshl_add_u64 v[174:175], s[20:21], 0, v[132:133]
	s_addc_u32 s53, s21, 0
	s_add_i32 s56, s56, s34
	global_load_lds_dwordx4 v[174:175], off
	v_lshl_add_u64 v[178:179], s[52:53], 0, v[160:161]
	s_mov_b32 m0, s56
	v_lshl_add_u64 v[180:181], s[22:23], 0, v[130:131]
	global_load_lds_dwordx4 v[178:179], off
	v_lshl_add_u64 v[178:179], s[52:53], 0, v[132:133]
	s_add_i32 m0, s56, 0x2000
	s_nop 0
	global_load_lds_dwordx4 v[178:179], off
	v_lshl_add_u64 v[178:179], s[22:23], 0, v[128:129]
	s_mov_b32 m0, s35
	s_nop 0
	global_load_lds_dwordx4 v[178:179], off
	s_mov_b32 m0, s44
	s_nop 0
	global_load_lds_dwordx4 v[180:181], off
	s_cmp_lt_u32 s47, 2
	s_cbranch_scc1 .Lmy_w8_2
	s_waitcnt vmcnt(16)
	s_branch .Lmy_wj_2

; #define PG8_STAGE(bufoff, gbase, voff) do { _Pragma("unroll") for (int _i = 0; _i < 2; ++_i) \
;         __builtin_amdgcn_global_load_lds((const unsigned*)((const char*)(gbase) + (voff)[_i]), (PG8_LAS unsigned*)(lds + (bufoff) + ldsw + _i * 8192), 16, 0, 0); } while (0)
; #define PG8_LDA(dst, b, h) do { _Pragma("unroll") for (int m = 0; m < 4; ++m) _Pragma("unroll") for (int k = 0; k < 2; ++k) dst[m][k] = *(const PG8_LAS bf16x8*)(lds + PG8_SA(b, h) + aoff + m * 2048 + k * 1024); } while (0)
; #define PG8_LDB(dst, b, h) do { _Pragma("unroll") for (int n = 0; n < 2; ++n) _Pragma("unroll") for (int k = 0; k < 2; ++k) dst[n][k] = *(const PG8_LAS bf16x8*)(lds + PG8_SB(b, h) + boff + n * 2048 + k * 1024); } while (0)
; #define PG8_MMA(ai, bj, At, Bt) do { __builtin_amdgcn_s_setprio(1); _Pragma("unroll") for (int m = 0; m < 4; ++m) _Pragma("unroll") for (int n = 0; n < 2; ++n) _Pragma("unroll") for (int k = 0; k < 2; ++k) \
;         acc[ai][bj][m][n] = __builtin_amdgcn_mfma_f32_16x16x32_bf16(Bt[n][k], At[m][k], acc[ai][bj][m][n], 0, 0, 0); __builtin_amdgcn_s_setprio(0); } while (0)
; #define PG8_WAIT_V(n) asm volatile("s_waitcnt vmcnt(" #n ")" ::: "memory")
; #define PG8_WAIT_L(n) asm volatile("s_waitcnt lgkmcnt(" #n ")" ::: "memory")
; #define PG8_BAR __builtin_amdgcn_s_barrier()
; #define PG8_SCHED __builtin_amdgcn_sched_barrier(0)
; template <class Epi, class Sched, bool ALIGN_EPI = false, bool SP2 = false>
; __device__ __forceinline__ void gemm_phase(PG8_LAS unsigned char* lds, const Gemm g, const Sched& S, const Epi& E, const int tid) {
;     ...
;             PG8_WAIT_V(8); PG8_WAIT_L(0); PG8_BAR; PG8_MMA(1, 0, At, B0); PG8_MMA(1, 1, At, B1); PG8_BAR; PG8_SCHED;
;             PG8_LDB(B0, 1, 0); PG8_LDB(B1, 1, 1); PG8_SCHED; PG8_LDA(At, 1, 0); PG8_STAGE(PG8_SA(0, 1), a2 + hstep, voffA);
;             PG8_WAIT_V(8); PG8_WAIT_L(0); PG8_BAR; PG8_MMA(0, 0, At, B0); PG8_MMA(0, 1, At, B1); PG8_BAR; PG8_SCHED;
.Lmy_wj_2:
	s_waitcnt lgkmcnt(0)
	s_setprio 1
	s_barrier
	v_mfma_f32_16x16x32_bf16 v[60:63], v[150:153], v[208:211], 0
	v_mfma_f32_16x16x32_bf16 v[52:55], v[162:165], v[208:211], 0
	v_mfma_f32_16x16x32_bf16 v[44:47], v[150:153], v[218:221], 0
	v_mfma_f32_16x16x32_bf16 v[36:39], v[162:165], v[218:221], 0
	v_mfma_f32_16x16x32_bf16 v[28:31], v[150:153], v[226:229], 0
	v_mfma_f32_16x16x32_bf16 v[20:23], v[162:165], v[226:229], 0
	v_mfma_f32_16x16x32_bf16 v[12:15], v[150:153], v[234:237], 0
	v_mfma_f32_16x16x32_bf16 v[4:7], v[162:165], v[234:237], 0
	v_mfma_f32_16x16x32_bf16 v[60:63], v[154:157], v[214:217], v[60:63]
	v_mfma_f32_16x16x32_bf16 v[52:55], v[166:169], v[214:217], v[52:55]
	v_mfma_f32_16x16x32_bf16 v[44:47], v[154:157], v[222:225], v[44:47]
	v_mfma_f32_16x16x32_bf16 v[36:39], v[166:169], v[222:225], v[36:39]
	v_mfma_f32_16x16x32_bf16 v[28:31], v[154:157], v[230:233], v[28:31]
	v_mfma_f32_16x16x32_bf16 v[20:23], v[166:169], v[230:233], v[20:23]
	v_mfma_f32_16x16x32_bf16 v[12:15], v[154:157], v[238:241], v[12:15]
	v_mfma_f32_16x16x32_bf16 v[4:7], v[166:169], v[238:241], v[4:7]
	s_setprio 0
	s_setprio 1
	v_mfma_f32_16x16x32_bf16 v[56:59], v[170:173], v[208:211], 0
	v_mfma_f32_16x16x32_bf16 v[48:51], v[188:191], v[208:211], 0
	v_mfma_f32_16x16x32_bf16 v[40:43], v[170:173], v[218:221], 0
	v_mfma_f32_16x16x32_bf16 v[32:35], v[188:191], v[218:221], 0
	v_mfma_f32_16x16x32_bf16 v[24:27], v[170:173], v[226:229], 0
	v_mfma_f32_16x16x32_bf16 v[16:19], v[188:191], v[226:229], 0
	v_mfma_f32_16x16x32_bf16 v[8:11], v[170:173], v[234:237], 0
	v_mfma_f32_16x16x32_bf16 v[0:3], v[188:191], v[234:237], 0
	v_mfma_f32_16x16x32_bf16 v[56:59], v[184:187], v[214:217], v[56:59]
	v_mfma_f32_16x16x32_bf16 v[48:51], v[192:195], v[214:217], v[48:51]
	v_mfma_f32_16x16x32_bf16 v[40:43], v[184:187], v[222:225], v[40:43]
	v_mfma_f32_16x16x32_bf16 v[32:35], v[192:195], v[222:225], v[32:35]
	v_mfma_f32_16x16x32_bf16 v[24:27], v[184:187], v[230:233], v[24:27]
	v_mfma_f32_16x16x32_bf16 v[16:19], v[192:195], v[230:233], v[16:19]
	v_mfma_f32_16x16x32_bf16 v[8:11], v[184:187], v[238:241], v[8:11]
	v_mfma_f32_16x16x32_bf16 v[0:3], v[192:195], v[238:241], v[0:3]
	s_setprio 0
	s_barrier
	s_add_i32 s52, 0, 0x18000
	v_add_u32_e32 v138, s52, v141
	s_add_i32 s53, 0, 0x1c000
	ds_read_b128 v[150:153], v138
	ds_read_b128 v[154:157], v138 offset:1024
	ds_read_b128 v[162:165], v138 offset:2048
	ds_read_b128 v[166:169], v138 offset:3072
	v_add_u32_e32 v138, s53, v141
	ds_read_b128 v[170:173], v138
	ds_read_b128 v[184:187], v138 offset:1024
	ds_read_b128 v[188:191], v138 offset:2048
	ds_read_b128 v[192:195], v138 offset:3072
	s_add_u32 s22, s22, 0x40000
	s_addc_u32 s23, s23, 0
	s_mov_b32 m0, s45
	v_lshl_add_u64 v[196:197], s[22:23], 0, v[128:129]
	ds_read_b128 v[208:211], v149 offset:32768
	ds_read_b128 v[214:217], v149 offset:33792
	ds_read_b128 v[218:221], v149 offset:34816
	ds_read_b128 v[222:225], v149 offset:35840
	ds_read_b128 v[226:229], v149 offset:36864
	ds_read_b128 v[230:233], v149 offset:37888
	ds_read_b128 v[234:237], v149 offset:38912
	ds_read_b128 v[238:241], v149 offset:39936
	global_load_lds_dwordx4 v[196:197], off
	v_lshl_add_u64 v[196:197], s[22:23], 0, v[130:131]
	s_mov_b32 m0, s46
	s_nop 0
	global_load_lds_dwordx4 v[196:197], off
	s_waitcnt vmcnt(8)
	s_waitcnt lgkmcnt(0)
	s_setprio 1
	s_barrier
	v_mfma_f32_16x16x32_bf16 v[124:127], v[150:153], v[208:211], v[124:127]
	v_mfma_f32_16x16x32_bf16 v[116:119], v[162:165], v[208:211], v[116:119]
	v_mfma_f32_16x16x32_bf16 v[108:111], v[150:153], v[218:221], v[108:111]
	v_mfma_f32_16x16x32_bf16 v[100:103], v[162:165], v[218:221], v[100:103]
	v_mfma_f32_16x16x32_bf16 v[92:95], v[150:153], v[226:229], v[92:95]
	v_mfma_f32_16x16x32_bf16 v[84:87], v[162:165], v[226:229], v[84:87]
	v_mfma_f32_16x16x32_bf16 v[76:79], v[150:153], v[234:237], v[76:79]
	v_mfma_f32_16x16x32_bf16 v[68:71], v[162:165], v[234:237], v[68:71]
	v_mfma_f32_16x16x32_bf16 v[124:127], v[154:157], v[214:217], v[124:127]
	v_mfma_f32_16x16x32_bf16 v[116:119], v[166:169], v[214:217], v[116:119]
	v_mfma_f32_16x16x32_bf16 v[108:111], v[154:157], v[222:225], v[108:111]
	v_mfma_f32_16x16x32_bf16 v[100:103], v[166:169], v[222:225], v[100:103]
	v_mfma_f32_16x16x32_bf16 v[92:95], v[154:157], v[230:233], v[92:95]
	v_mfma_f32_16x16x32_bf16 v[84:87], v[166:169], v[230:233], v[84:87]
	v_mfma_f32_16x16x32_bf16 v[76:79], v[154:157], v[238:241], v[76:79]
	v_mfma_f32_16x16x32_bf16 v[68:71], v[166:169], v[238:241], v[68:71]
	s_setprio 0
	s_setprio 1
	v_mfma_f32_16x16x32_bf16 v[120:123], v[170:173], v[208:211], v[120:123]
	v_mfma_f32_16x16x32_bf16 v[112:115], v[188:191], v[208:211], v[112:115]
	v_mfma_f32_16x16x32_bf16 v[104:107], v[170:173], v[218:221], v[104:107]
	v_mfma_f32_16x16x32_bf16 v[96:99], v[188:191], v[218:221], v[96:99]
	v_mfma_f32_16x16x32_bf16 v[88:91], v[170:173], v[226:229], v[88:91]
	v_mfma_f32_16x16x32_bf16 v[80:83], v[188:191], v[226:229], v[80:83]
	v_mfma_f32_16x16x32_bf16 v[72:75], v[170:173], v[234:237], v[72:75]
	v_mfma_f32_16x16x32_bf16 v[64:67], v[188:191], v[234:237], v[64:67]
	v_mfma_f32_16x16x32_bf16 v[120:123], v[184:187], v[214:217], v[120:123]
	v_mfma_f32_16x16x32_bf16 v[112:115], v[192:195], v[214:217], v[112:115]
	v_mfma_f32_16x16x32_bf16 v[104:107], v[184:187], v[222:225], v[104:107]
	v_mfma_f32_16x16x32_bf16 v[96:99], v[192:195], v[222:225], v[96:99]
	v_mfma_f32_16x16x32_bf16 v[88:91], v[184:187], v[230:233], v[88:91]
	v_mfma_f32_16x16x32_bf16 v[80:83], v[192:195], v[230:233], v[80:83]
	v_mfma_f32_16x16x32_bf16 v[72:75], v[184:187], v[238:241], v[72:75]
	v_mfma_f32_16x16x32_bf16 v[64:67], v[192:195], v[238:241], v[64:67]
	s_setprio 0
	s_barrier
; #define PG8_STAGE(bufoff, gbase, voff) do { _Pragma("unroll") for (int _i = 0; _i < 2; ++_i) \
;         __builtin_amdgcn_global_load_lds((const unsigned*)((const char*)(gbase) + (voff)[_i]), (PG8_LAS unsigned*)(lds + (bufoff) + ldsw + _i * 8192), 16, 0, 0); } while (0)
; #define PG8_LDA(dst, b, h) do { _Pragma("unroll") for (int m = 0; m < 4; ++m) _Pragma("unroll") for (int k = 0; k < 2; ++k) dst[m][k] = *(const PG8_LAS bf16x8*)(lds + PG8_SA(b, h) + aoff + m * 2048 + k * 1024); } while (0)
; #define PG8_WAIT_V(n) asm volatile("s_waitcnt vmcnt(" #n ")" ::: "memory")
; #define PG8_WAIT_L(n) asm volatile("s_waitcnt lgkmcnt(" #n ")" ::: "memory")
; #define PG8_BAR __builtin_amdgcn_s_barrier()
; template <class Epi, class Sched, bool ALIGN_EPI = false, bool SP2 = false>
; __device__ __forceinline__ void gemm_phase(PG8_LAS unsigned char* lds, const Gemm g, const Sched& S, const Epi& E, const int tid) {
;     ...
;         for (int t = 0; t < nt; t += 2) {
;             const bool last = (t == nt - 2);
;             const char* a1 = cA + (size_t)(t + 1) * kstep;
;             const char* a2 = last ? nA : cA + (size_t)(t + 2) * kstep; const char* b2 = last ? nB : cB + (size_t)(t + 2) * kstep;
;             const char* a3 = a2 + kstep; const char* b3 = b2 + kstep;
;             if (last && has_next) S.a_ready(nxt);
;             if constexpr (SP2) {
;             PG8_LDB(B0, 0, 0); PG8_LDB(B1, 0, 1); PG8_SCHED; PG8_LDA(At, 0, 0); PG8_STAGE(PG8_SA(1, 1), a1 + hstep, voffA);
;             PG8_WAIT_V(8); PG8_WAIT_L(0); PG8_BAR; PG8_MMA(0, 0, At, B0); PG8_MMA(0, 1, At, B1); PG8_BAR; PG8_SCHED;
;             PG8_LDA(At, 0, 1); PG8_STAGE(PG8_SB(0, 0), b2, voffB); PG8_STAGE(PG8_SB(0, 1), b2 + hstep, voffB); PG8_STAGE(PG8_SA(0, 0), a2, voffA);
;             PG8_WAIT_V(8); PG8_WAIT_L(0); PG8_BAR; PG8_MMA(1, 0, At, B0); PG8_MMA(1, 1, At, B1); PG8_BAR; PG8_SCHED;
;             PG8_LDB(B0, 1, 0); PG8_LDB(B1, 1, 1); PG8_SCHED; PG8_LDA(At, 1, 0); PG8_STAGE(PG8_SA(0, 1), a2 + hstep, voffA);
;             PG8_WAIT_V(8); PG8_WAIT_L(0); PG8_BAR; PG8_MMA(0, 0, At, B0); PG8_MMA(0, 1, At, B1); PG8_BAR; PG8_SCHED;
;             PG8_LDA(At, 1, 1); PG8_STAGE(PG8_SB(1, 0), b3, voffB); PG8_STAGE(PG8_SB(1, 1), b3 + hstep, voffB); PG8_STAGE(PG8_SA(1, 0), a3, voffA);
;             PG8_WAIT_V(8); PG8_WAIT_L(0); PG8_BAR; PG8_MMA(1, 0, At, B0); PG8_MMA(1, 1, At, B1); PG8_BAR; PG8_SCHED;
	s_add_i32 s22, s52, s34
	v_lshl_add_u64 v[158:159], v[158:159], 0, s[28:29]
	s_mov_b32 m0, s22
	ds_read_b128 v[208:211], v149 offset:49152
	ds_read_b128 v[214:217], v149 offset:50176
	ds_read_b128 v[218:221], v149 offset:51200
	ds_read_b128 v[222:225], v149 offset:52224
	ds_read_b128 v[226:229], v149 offset:53248
	ds_read_b128 v[230:233], v149 offset:54272
	ds_read_b128 v[234:237], v149 offset:55296
	ds_read_b128 v[238:241], v149 offset:56320
	global_load_lds_dwordx4 v[158:159], off
	s_add_i32 m0, s22, 0x2000
	s_add_u32 s20, s20, 0x40080
	v_lshl_add_u64 v[158:159], v[174:175], 0, s[28:29]
	s_addc_u32 s21, s21, 0
	s_add_i32 s22, s53, s34
	global_load_lds_dwordx4 v[158:159], off
	v_lshl_add_u64 v[158:159], s[20:21], 0, v[160:161]
	s_mov_b32 m0, s22
	s_nop 0
	global_load_lds_dwordx4 v[158:159], off
	v_lshl_add_u64 v[158:159], s[20:21], 0, v[132:133]
	s_add_i32 m0, s22, 0x2000
	s_nop 0
	global_load_lds_dwordx4 v[158:159], off
	v_lshl_add_u64 v[158:159], v[178:179], 0, s[28:29]
	s_mov_b32 m0, s49
	s_nop 0
	global_load_lds_dwordx4 v[158:159], off
	v_lshl_add_u64 v[158:159], v[180:181], 0, s[28:29]
	s_mov_b32 m0, s50
	s_nop 0
	global_load_lds_dwordx4 v[158:159], off
	s_waitcnt vmcnt(8)
	s_waitcnt lgkmcnt(0)
	s_setprio 1
	s_barrier
	v_mfma_f32_16x16x32_bf16 v[60:63], v[150:153], v[208:211], v[60:63]
	v_mfma_f32_16x16x32_bf16 v[52:55], v[162:165], v[208:211], v[52:55]
	v_mfma_f32_16x16x32_bf16 v[44:47], v[150:153], v[218:221], v[44:47]
	v_mfma_f32_16x16x32_bf16 v[36:39], v[162:165], v[218:221], v[36:39]
	v_mfma_f32_16x16x32_bf16 v[28:31], v[150:153], v[226:229], v[28:31]
	v_mfma_f32_16x16x32_bf16 v[20:23], v[162:165], v[226:229], v[20:23]
	v_mfma_f32_16x16x32_bf16 v[12:15], v[150:153], v[234:237], v[12:15]
	v_mfma_f32_16x16x32_bf16 v[4:7], v[162:165], v[234:237], v[4:7]
	v_mfma_f32_16x16x32_bf16 v[60:63], v[154:157], v[214:217], v[60:63]
	v_mfma_f32_16x16x32_bf16 v[52:55], v[166:169], v[214:217], v[52:55]
	v_mfma_f32_16x16x32_bf16 v[44:47], v[154:157], v[222:225], v[44:47]
	v_mfma_f32_16x16x32_bf16 v[36:39], v[166:169], v[222:225], v[36:39]
	v_mfma_f32_16x16x32_bf16 v[28:31], v[154:157], v[230:233], v[28:31]
	v_mfma_f32_16x16x32_bf16 v[20:23], v[166:169], v[230:233], v[20:23]
	v_mfma_f32_16x16x32_bf16 v[12:15], v[154:157], v[238:241], v[12:15]
	v_mfma_f32_16x16x32_bf16 v[4:7], v[166:169], v[238:241], v[4:7]
	s_setprio 0
	s_setprio 1
	v_mfma_f32_16x16x32_bf16 v[56:59], v[170:173], v[208:211], v[56:59]
	v_mfma_f32_16x16x32_bf16 v[48:51], v[188:191], v[208:211], v[48:51]
	v_mfma_f32_16x16x32_bf16 v[40:43], v[170:173], v[218:221], v[40:43]
	v_mfma_f32_16x16x32_bf16 v[32:35], v[188:191], v[218:221], v[32:35]
	v_mfma_f32_16x16x32_bf16 v[24:27], v[170:173], v[226:229], v[24:27]
	v_mfma_f32_16x16x32_bf16 v[16:19], v[188:191], v[226:229], v[16:19]
	v_mfma_f32_16x16x32_bf16 v[8:11], v[170:173], v[234:237], v[8:11]
	v_mfma_f32_16x16x32_bf16 v[0:3], v[188:191], v[234:237], v[0:3]
	v_mfma_f32_16x16x32_bf16 v[56:59], v[184:187], v[214:217], v[56:59]
	v_mfma_f32_16x16x32_bf16 v[48:51], v[192:195], v[214:217], v[48:51]
	v_mfma_f32_16x16x32_bf16 v[40:43], v[184:187], v[222:225], v[40:43]
	v_mfma_f32_16x16x32_bf16 v[32:35], v[192:195], v[222:225], v[32:35]
	v_mfma_f32_16x16x32_bf16 v[24:27], v[184:187], v[230:233], v[24:27]
	v_mfma_f32_16x16x32_bf16 v[16:19], v[192:195], v[230:233], v[16:19]
	v_mfma_f32_16x16x32_bf16 v[8:11], v[184:187], v[238:241], v[8:11]
	v_mfma_f32_16x16x32_bf16 v[0:3], v[192:195], v[238:241], v[0:3]
	s_setprio 0
	s_barrier
	s_add_i32 s51, s51, 2
	s_add_u32 s18, s18, 0x100
	s_addc_u32 s19, s19, 0
	s_add_u32 s42, s42, 0x100
	s_addc_u32 s43, s43, 0
	s_cmp_gt_u32 s51, 13
	s_cbranch_scc1 .Lmy_kdone_2
.LBB0_517:
	s_add_u32 s20, s18, 0xfffc0080
	s_addc_u32 s21, s19, -1
	s_add_i32 s52, 0, 0x10000
	s_cmp_eq_u32 s51, 12
	s_cselect_b32 s23, s11, s21
	s_cselect_b32 s22, s36, s20
	v_add_u32_e32 v138, s52, v141
	s_cselect_b32 s21, s9, s43
	s_cselect_b32 s20, s37, s42
	s_add_i32 s56, 0, 0x14000
	ds_read_b128 v[150:153], v138
	ds_read_b128 v[154:157], v138 offset:1024
	ds_read_b128 v[162:165], v138 offset:2048
	ds_read_b128 v[166:169], v138 offset:3072
	v_add_u32_e32 v138, s56, v141
	ds_read_b128 v[170:173], v138
	ds_read_b128 v[184:187], v138 offset:1024
	ds_read_b128 v[188:191], v138 offset:2048
	ds_read_b128 v[192:195], v138 offset:3072
	v_lshl_add_u64 v[158:159], s[18:19], 0, v[134:135]
	s_add_i32 m0, s35, 0xc000
	ds_read_b128 v[208:211], v149
	ds_read_b128 v[214:217], v149 offset:1024
	ds_read_b128 v[218:221], v149 offset:2048
	ds_read_b128 v[222:225], v149 offset:3072
	ds_read_b128 v[226:229], v149 offset:4096
	ds_read_b128 v[230:233], v149 offset:5120
	ds_read_b128 v[234:237], v149 offset:6144
	ds_read_b128 v[238:241], v149 offset:7168
	global_load_lds_dwordx4 v[158:159], off
	v_lshl_add_u64 v[158:159], s[18:19], 0, v[136:137]
	s_add_i32 m0, s35, 0xe000
	s_nop 0
	global_load_lds_dwordx4 v[158:159], off
	s_waitcnt vmcnt(8)
	s_waitcnt lgkmcnt(0)
	s_setprio 1
	s_barrier
; #define PG8_STAGE(bufoff, gbase, voff) do { _Pragma("unroll") for (int _i = 0; _i < 2; ++_i) \
;         __builtin_amdgcn_global_load_lds((const unsigned*)((const char*)(gbase) + (voff)[_i]), (PG8_LAS unsigned*)(lds + (bufoff) + ldsw + _i * 8192), 16, 0, 0); } while (0)
; #define PG8_LDA(dst, b, h) do { _Pragma("unroll") for (int m = 0; m < 4; ++m) _Pragma("unroll") for (int k = 0; k < 2; ++k) dst[m][k] = *(const PG8_LAS bf16x8*)(lds + PG8_SA(b, h) + aoff + m * 2048 + k * 1024); } while (0)
; #define PG8_MMA(ai, bj, At, Bt) do { __builtin_amdgcn_s_setprio(1); _Pragma("unroll") for (int m = 0; m < 4; ++m) _Pragma("unroll") for (int n = 0; n < 2; ++n) _Pragma("unroll") for (int k = 0; k < 2; ++k) \
;         acc[ai][bj][m][n] = __builtin_amdgcn_mfma_f32_16x16x32_bf16(Bt[n][k], At[m][k], acc[ai][bj][m][n], 0, 0, 0); __builtin_amdgcn_s_setprio(0); } while (0)
; #define PG8_WAIT_V(n) asm volatile("s_waitcnt vmcnt(" #n ")" ::: "memory")
; #define PG8_WAIT_L(n) asm volatile("s_waitcnt lgkmcnt(" #n ")" ::: "memory")
; #define PG8_BAR __builtin_amdgcn_s_barrier()
; #define PG8_SCHED __builtin_amdgcn_sched_barrier(0)
; template <class Epi, class Sched, bool ALIGN_EPI = false, bool SP2 = false>
; __device__ __forceinline__ void gemm_phase(PG8_LAS unsigned char* lds, const Gemm g, const Sched& S, const Epi& E, const int tid) {
;     ...
;             PG8_WAIT_V(8); PG8_WAIT_L(0); PG8_BAR; PG8_MMA(0, 0, At, B0); PG8_MMA(0, 1, At, B1); PG8_BAR; PG8_SCHED;
;             PG8_LDA(At, 0, 1); PG8_STAGE(PG8_SB(0, 0), b2, voffB); PG8_STAGE(PG8_SB(0, 1), b2 + hstep, voffB); PG8_STAGE(PG8_SA(0, 0), a2, voffA);
;             PG8_WAIT_V(8); PG8_WAIT_L(0); PG8_BAR; PG8_MMA(1, 0, At, B0); PG8_MMA(1, 1, At, B1); PG8_BAR; PG8_SCHED;
	v_mfma_f32_16x16x32_bf16 v[124:127], v[150:153], v[208:211], v[124:127]
	v_mfma_f32_16x16x32_bf16 v[116:119], v[162:165], v[208:211], v[116:119]
	v_mfma_f32_16x16x32_bf16 v[108:111], v[150:153], v[218:221], v[108:111]
	v_mfma_f32_16x16x32_bf16 v[100:103], v[162:165], v[218:221], v[100:103]
	v_mfma_f32_16x16x32_bf16 v[92:95], v[150:153], v[226:229], v[92:95]
	v_mfma_f32_16x16x32_bf16 v[84:87], v[162:165], v[226:229], v[84:87]
	v_mfma_f32_16x16x32_bf16 v[76:79], v[150:153], v[234:237], v[76:79]
	v_mfma_f32_16x16x32_bf16 v[68:71], v[162:165], v[234:237], v[68:71]
	v_mfma_f32_16x16x32_bf16 v[124:127], v[154:157], v[214:217], v[124:127]
	v_mfma_f32_16x16x32_bf16 v[116:119], v[166:169], v[214:217], v[116:119]
	v_mfma_f32_16x16x32_bf16 v[108:111], v[154:157], v[222:225], v[108:111]
	v_mfma_f32_16x16x32_bf16 v[100:103], v[166:169], v[222:225], v[100:103]
	v_mfma_f32_16x16x32_bf16 v[92:95], v[154:157], v[230:233], v[92:95]
	v_mfma_f32_16x16x32_bf16 v[84:87], v[166:169], v[230:233], v[84:87]
	v_mfma_f32_16x16x32_bf16 v[76:79], v[154:157], v[238:241], v[76:79]
	v_mfma_f32_16x16x32_bf16 v[68:71], v[166:169], v[238:241], v[68:71]
	s_setprio 0
	s_setprio 1
	v_mfma_f32_16x16x32_bf16 v[120:123], v[170:173], v[208:211], v[120:123]
	v_mfma_f32_16x16x32_bf16 v[112:115], v[188:191], v[208:211], v[112:115]
	v_mfma_f32_16x16x32_bf16 v[104:107], v[170:173], v[218:221], v[104:107]
	v_mfma_f32_16x16x32_bf16 v[96:99], v[188:191], v[218:221], v[96:99]
	v_mfma_f32_16x16x32_bf16 v[88:91], v[170:173], v[226:229], v[88:91]
	v_mfma_f32_16x16x32_bf16 v[80:83], v[188:191], v[226:229], v[80:83]
	v_mfma_f32_16x16x32_bf16 v[72:75], v[170:173], v[234:237], v[72:75]
	v_mfma_f32_16x16x32_bf16 v[64:67], v[188:191], v[234:237], v[64:67]
	v_mfma_f32_16x16x32_bf16 v[120:123], v[184:187], v[214:217], v[120:123]
	v_mfma_f32_16x16x32_bf16 v[112:115], v[192:195], v[214:217], v[112:115]
	v_mfma_f32_16x16x32_bf16 v[104:107], v[184:187], v[222:225], v[104:107]
	v_mfma_f32_16x16x32_bf16 v[96:99], v[192:195], v[222:225], v[96:99]
	v_mfma_f32_16x16x32_bf16 v[88:91], v[184:187], v[230:233], v[88:91]
	v_mfma_f32_16x16x32_bf16 v[80:83], v[192:195], v[230:233], v[80:83]
	v_mfma_f32_16x16x32_bf16 v[72:75], v[184:187], v[238:241], v[72:75]
	v_mfma_f32_16x16x32_bf16 v[64:67], v[192:195], v[238:241], v[64:67]
	s_setprio 0
	s_barrier
	s_add_i32 s52, s52, s34
	v_lshl_add_u64 v[158:159], s[20:21], 0, v[160:161]
	s_mov_b32 m0, s52
	ds_read_b128 v[208:211], v149 offset:16384
	ds_read_b128 v[214:217], v149 offset:17408
	ds_read_b128 v[218:221], v149 offset:18432
	ds_read_b128 v[222:225], v149 offset:19456
	ds_read_b128 v[226:229], v149 offset:20480
	ds_read_b128 v[230:233], v149 offset:21504
	ds_read_b128 v[234:237], v149 offset:22528
	ds_read_b128 v[238:241], v149 offset:23552
	global_load_lds_dwordx4 v[158:159], off
	s_add_i32 m0, s52, 0x2000
	s_add_u32 s52, s20, 0x40000
	v_lshl_add_u64 v[174:175], s[20:21], 0, v[132:133]
	s_addc_u32 s53, s21, 0
	s_add_i32 s56, s56, s34
	global_load_lds_dwordx4 v[174:175], off
	v_lshl_add_u64 v[178:179], s[52:53], 0, v[160:161]
	s_mov_b32 m0, s56
	v_lshl_add_u64 v[180:181], s[22:23], 0, v[130:131]
	global_load_lds_dwordx4 v[178:179], off
	v_lshl_add_u64 v[178:179], s[52:53], 0, v[132:133]
	s_add_i32 m0, s56, 0x2000
	s_nop 0
	global_load_lds_dwordx4 v[178:179], off
	v_lshl_add_u64 v[178:179], s[22:23], 0, v[128:129]
	s_mov_b32 m0, s35
	s_nop 0
	global_load_lds_dwordx4 v[178:179], off
	s_mov_b32 m0, s44
	s_nop 0
	global_load_lds_dwordx4 v[180:181], off
	s_waitcnt vmcnt(8)
	s_waitcnt lgkmcnt(0)
	s_setprio 1
	s_barrier
	v_mfma_f32_16x16x32_bf16 v[60:63], v[150:153], v[208:211], v[60:63]
	v_mfma_f32_16x16x32_bf16 v[52:55], v[162:165], v[208:211], v[52:55]
	v_mfma_f32_16x16x32_bf16 v[44:47], v[150:153], v[218:221], v[44:47]
	v_mfma_f32_16x16x32_bf16 v[36:39], v[162:165], v[218:221], v[36:39]
	v_mfma_f32_16x16x32_bf16 v[28:31], v[150:153], v[226:229], v[28:31]
	v_mfma_f32_16x16x32_bf16 v[20:23], v[162:165], v[226:229], v[20:23]
	v_mfma_f32_16x16x32_bf16 v[12:15], v[150:153], v[234:237], v[12:15]
	v_mfma_f32_16x16x32_bf16 v[4:7], v[162:165], v[234:237], v[4:7]
	v_mfma_f32_16x16x32_bf16 v[60:63], v[154:157], v[214:217], v[60:63]
	v_mfma_f32_16x16x32_bf16 v[52:55], v[166:169], v[214:217], v[52:55]
	v_mfma_f32_16x16x32_bf16 v[44:47], v[154:157], v[222:225], v[44:47]
	v_mfma_f32_16x16x32_bf16 v[36:39], v[166:169], v[222:225], v[36:39]
	v_mfma_f32_16x16x32_bf16 v[28:31], v[154:157], v[230:233], v[28:31]
	v_mfma_f32_16x16x32_bf16 v[20:23], v[166:169], v[230:233], v[20:23]
	v_mfma_f32_16x16x32_bf16 v[12:15], v[154:157], v[238:241], v[12:15]
	v_mfma_f32_16x16x32_bf16 v[4:7], v[166:169], v[238:241], v[4:7]
	s_setprio 0
	s_setprio 1
	v_mfma_f32_16x16x32_bf16 v[56:59], v[170:173], v[208:211], v[56:59]
	v_mfma_f32_16x16x32_bf16 v[48:51], v[188:191], v[208:211], v[48:51]
	v_mfma_f32_16x16x32_bf16 v[40:43], v[170:173], v[218:221], v[40:43]
	v_mfma_f32_16x16x32_bf16 v[32:35], v[188:191], v[218:221], v[32:35]
	v_mfma_f32_16x16x32_bf16 v[24:27], v[170:173], v[226:229], v[24:27]
	v_mfma_f32_16x16x32_bf16 v[16:19], v[188:191], v[226:229], v[16:19]
	v_mfma_f32_16x16x32_bf16 v[8:11], v[170:173], v[234:237], v[8:11]
	v_mfma_f32_16x16x32_bf16 v[0:3], v[188:191], v[234:237], v[0:3]
	v_mfma_f32_16x16x32_bf16 v[56:59], v[184:187], v[214:217], v[56:59]
	v_mfma_f32_16x16x32_bf16 v[48:51], v[192:195], v[214:217], v[48:51]
	v_mfma_f32_16x16x32_bf16 v[40:43], v[184:187], v[222:225], v[40:43]
	v_mfma_f32_16x16x32_bf16 v[32:35], v[192:195], v[222:225], v[32:35]
	v_mfma_f32_16x16x32_bf16 v[24:27], v[184:187], v[230:233], v[24:27]
	v_mfma_f32_16x16x32_bf16 v[16:19], v[192:195], v[230:233], v[16:19]
	v_mfma_f32_16x16x32_bf16 v[8:11], v[184:187], v[238:241], v[8:11]
	v_mfma_f32_16x16x32_bf16 v[0:3], v[192:195], v[238:241], v[0:3]
	s_setprio 0
	s_barrier
; #define PG8_STAGE(bufoff, gbase, voff) do { _Pragma("unroll") for (int _i = 0; _i < 2; ++_i) \
;         __builtin_amdgcn_global_load_lds((const unsigned*)((const char*)(gbase) + (voff)[_i]), (PG8_LAS unsigned*)(lds + (bufoff) + ldsw + _i * 8192), 16, 0, 0); } while (0)
; #define PG8_LDA(dst, b, h) do { _Pragma("unroll") for (int m = 0; m < 4; ++m) _Pragma("unroll") for (int k = 0; k < 2; ++k) dst[m][k] = *(const PG8_LAS bf16x8*)(lds + PG8_SA(b, h) + aoff + m * 2048 + k * 1024); } while (0)
; #define PG8_LDB(dst, b, h) do { _Pragma("unroll") for (int n = 0; n < 2; ++n) _Pragma("unroll") for (int k = 0; k < 2; ++k) dst[n][k] = *(const PG8_LAS bf16x8*)(lds + PG8_SB(b, h) + boff + n * 2048 + k * 1024); } while (0)
; #define PG8_MMA(ai, bj, At, Bt) do { __builtin_amdgcn_s_setprio(1); _Pragma("unroll") for (int m = 0; m < 4; ++m) _Pragma("unroll") for (int n = 0; n < 2; ++n) _Pragma("unroll") for (int k = 0; k < 2; ++k) \
;         acc[ai][bj][m][n] = __builtin_amdgcn_mfma_f32_16x16x32_bf16(Bt[n][k], At[m][k], acc[ai][bj][m][n], 0, 0, 0); __builtin_amdgcn_s_setprio(0); } while (0)
; #define PG8_WAIT_V(n) asm volatile("s_waitcnt vmcnt(" #n ")" ::: "memory")
; #define PG8_WAIT_L(n) asm volatile("s_waitcnt lgkmcnt(" #n ")" ::: "memory")
; #define PG8_BAR __builtin_amdgcn_s_barrier()
; #define PG8_SCHED __builtin_amdgcn_sched_barrier(0)
; template <class Epi, class Sched, bool ALIGN_EPI = false, bool SP2 = false>
; __device__ __forceinline__ void gemm_phase(PG8_LAS unsigned char* lds, const Gemm g, const Sched& S, const Epi& E, const int tid) {
;     ...
;             PG8_LDB(B0, 1, 0); PG8_LDB(B1, 1, 1); PG8_SCHED; PG8_LDA(At, 1, 0); PG8_STAGE(PG8_SA(0, 1), a2 + hstep, voffA);
;             PG8_WAIT_V(8); PG8_WAIT_L(0); PG8_BAR; PG8_MMA(0, 0, At, B0); PG8_MMA(0, 1, At, B1); PG8_BAR; PG8_SCHED;
	s_add_i32 s52, 0, 0x18000
	v_add_u32_e32 v138, s52, v141
	s_add_i32 s53, 0, 0x1c000
	ds_read_b128 v[150:153], v138
	ds_read_b128 v[154:157], v138 offset:1024
	ds_read_b128 v[162:165], v138 offset:2048
	ds_read_b128 v[166:169], v138 offset:3072
	v_add_u32_e32 v138, s53, v141
	ds_read_b128 v[170:173], v138
	ds_read_b128 v[184:187], v138 offset:1024
	ds_read_b128 v[188:191], v138 offset:2048
	ds_read_b128 v[192:195], v138 offset:3072
	s_add_u32 s22, s22, 0x40000
	s_addc_u32 s23, s23, 0
	s_mov_b32 m0, s45
	v_lshl_add_u64 v[196:197], s[22:23], 0, v[128:129]
	ds_read_b128 v[208:211], v149 offset:32768
	ds_read_b128 v[214:217], v149 offset:33792
	ds_read_b128 v[218:221], v149 offset:34816
	ds_read_b128 v[222:225], v149 offset:35840
	ds_read_b128 v[226:229], v149 offset:36864
	ds_read_b128 v[230:233], v149 offset:37888
	ds_read_b128 v[234:237], v149 offset:38912
	ds_read_b128 v[238:241], v149 offset:39936
	global_load_lds_dwordx4 v[196:197], off
	v_lshl_add_u64 v[196:197], s[22:23], 0, v[130:131]
	s_mov_b32 m0, s46
	s_nop 0
	global_load_lds_dwordx4 v[196:197], off
	s_waitcnt vmcnt(8)
	s_waitcnt lgkmcnt(0)
	s_setprio 1
	s_barrier
	v_mfma_f32_16x16x32_bf16 v[124:127], v[150:153], v[208:211], v[124:127]
	v_mfma_f32_16x16x32_bf16 v[116:119], v[162:165], v[208:211], v[116:119]
	v_mfma_f32_16x16x32_bf16 v[108:111], v[150:153], v[218:221], v[108:111]
	v_mfma_f32_16x16x32_bf16 v[100:103], v[162:165], v[218:221], v[100:103]
	v_mfma_f32_16x16x32_bf16 v[92:95], v[150:153], v[226:229], v[92:95]
	v_mfma_f32_16x16x32_bf16 v[84:87], v[162:165], v[226:229], v[84:87]
	v_mfma_f32_16x16x32_bf16 v[76:79], v[150:153], v[234:237], v[76:79]
	v_mfma_f32_16x16x32_bf16 v[68:71], v[162:165], v[234:237], v[68:71]
	v_mfma_f32_16x16x32_bf16 v[124:127], v[154:157], v[214:217], v[124:127]
	v_mfma_f32_16x16x32_bf16 v[116:119], v[166:169], v[214:217], v[116:119]
	v_mfma_f32_16x16x32_bf16 v[108:111], v[154:157], v[222:225], v[108:111]
	v_mfma_f32_16x16x32_bf16 v[100:103], v[166:169], v[222:225], v[100:103]
	v_mfma_f32_16x16x32_bf16 v[92:95], v[154:157], v[230:233], v[92:95]
	v_mfma_f32_16x16x32_bf16 v[84:87], v[166:169], v[230:233], v[84:87]
	v_mfma_f32_16x16x32_bf16 v[76:79], v[154:157], v[238:241], v[76:79]
	v_mfma_f32_16x16x32_bf16 v[68:71], v[166:169], v[238:241], v[68:71]
	s_setprio 0
	s_setprio 1
	v_mfma_f32_16x16x32_bf16 v[120:123], v[170:173], v[208:211], v[120:123]
	v_mfma_f32_16x16x32_bf16 v[112:115], v[188:191], v[208:211], v[112:115]
	v_mfma_f32_16x16x32_bf16 v[104:107], v[170:173], v[218:221], v[104:107]
	v_mfma_f32_16x16x32_bf16 v[96:99], v[188:191], v[218:221], v[96:99]
	v_mfma_f32_16x16x32_bf16 v[88:91], v[170:173], v[226:229], v[88:91]
	v_mfma_f32_16x16x32_bf16 v[80:83], v[188:191], v[226:229], v[80:83]
	v_mfma_f32_16x16x32_bf16 v[72:75], v[170:173], v[234:237], v[72:75]
	v_mfma_f32_16x16x32_bf16 v[64:67], v[188:191], v[234:237], v[64:67]
	v_mfma_f32_16x16x32_bf16 v[120:123], v[184:187], v[214:217], v[120:123]
	v_mfma_f32_16x16x32_bf16 v[112:115], v[192:195], v[214:217], v[112:115]
	v_mfma_f32_16x16x32_bf16 v[104:107], v[184:187], v[222:225], v[104:107]
	v_mfma_f32_16x16x32_bf16 v[96:99], v[192:195], v[222:225], v[96:99]
	v_mfma_f32_16x16x32_bf16 v[88:91], v[184:187], v[230:233], v[88:91]
	v_mfma_f32_16x16x32_bf16 v[80:83], v[192:195], v[230:233], v[80:83]
	v_mfma_f32_16x16x32_bf16 v[72:75], v[184:187], v[238:241], v[72:75]
	v_mfma_f32_16x16x32_bf16 v[64:67], v[192:195], v[238:241], v[64:67]
	s_setprio 0
	s_barrier
; #define PG8_STAGE(bufoff, gbase, voff) do { _Pragma("unroll") for (int _i = 0; _i < 2; ++_i) \
;         __builtin_amdgcn_global_load_lds((const unsigned*)((const char*)(gbase) + (voff)[_i]), (PG8_LAS unsigned*)(lds + (bufoff) + ldsw + _i * 8192), 16, 0, 0); } while (0)
; #define PG8_LDA(dst, b, h) do { _Pragma("unroll") for (int m = 0; m < 4; ++m) _Pragma("unroll") for (int k = 0; k < 2; ++k) dst[m][k] = *(const PG8_LAS bf16x8*)(lds + PG8_SA(b, h) + aoff + m * 2048 + k * 1024); } while (0)
; #define PG8_MMA(ai, bj, At, Bt) do { __builtin_amdgcn_s_setprio(1); _Pragma("unroll") for (int m = 0; m < 4; ++m) _Pragma("unroll") for (int n = 0; n < 2; ++n) _Pragma("unroll") for (int k = 0; k < 2; ++k) \
;         acc[ai][bj][m][n] = __builtin_amdgcn_mfma_f32_16x16x32_bf16(Bt[n][k], At[m][k], acc[ai][bj][m][n], 0, 0, 0); __builtin_amdgcn_s_setprio(0); } while (0)
; #define PG8_WAIT_V(n) asm volatile("s_waitcnt vmcnt(" #n ")" ::: "memory")
; #define PG8_WAIT_L(n) asm volatile("s_waitcnt lgkmcnt(" #n ")" ::: "memory")
; #define PG8_BAR __builtin_amdgcn_s_barrier()
; #define PG8_SCHED __builtin_amdgcn_sched_barrier(0)
; template <class Epi, class Sched, bool ALIGN_EPI = false, bool SP2 = false>
; __device__ __forceinline__ void gemm_phase(PG8_LAS unsigned char* lds, const Gemm g, const Sched& S, const Epi& E, const int tid) {
;     ...
;             PG8_LDA(At, 1, 1); PG8_STAGE(PG8_SB(1, 0), b3, voffB); PG8_STAGE(PG8_SB(1, 1), b3 + hstep, voffB); PG8_STAGE(PG8_SA(1, 0), a3, voffA);
;             PG8_WAIT_V(8); PG8_WAIT_L(0); PG8_BAR; PG8_MMA(1, 0, At, B0); PG8_MMA(1, 1, At, B1); PG8_BAR; PG8_SCHED;
	s_add_i32 s22, s52, s34
	v_lshl_add_u64 v[158:159], v[158:159], 0, s[28:29]
	s_mov_b32 m0, s22
	ds_read_b128 v[208:211], v149 offset:49152
	ds_read_b128 v[214:217], v149 offset:50176
	ds_read_b128 v[218:221], v149 offset:51200
	ds_read_b128 v[222:225], v149 offset:52224
	ds_read_b128 v[226:229], v149 offset:53248
	ds_read_b128 v[230:233], v149 offset:54272
	ds_read_b128 v[234:237], v149 offset:55296
	ds_read_b128 v[238:241], v149 offset:56320
	global_load_lds_dwordx4 v[158:159], off
	s_add_i32 m0, s22, 0x2000
	s_add_u32 s20, s20, 0x40080
	v_lshl_add_u64 v[158:159], v[174:175], 0, s[28:29]
	s_addc_u32 s21, s21, 0
	s_add_i32 s22, s53, s34
	global_load_lds_dwordx4 v[158:159], off
	v_lshl_add_u64 v[158:159], s[20:21], 0, v[160:161]
	s_mov_b32 m0, s22
	s_nop 0
	global_load_lds_dwordx4 v[158:159], off
	v_lshl_add_u64 v[158:159], s[20:21], 0, v[132:133]
	s_add_i32 m0, s22, 0x2000
	s_nop 0
	global_load_lds_dwordx4 v[158:159], off
	v_lshl_add_u64 v[158:159], v[178:179], 0, s[28:29]
	s_mov_b32 m0, s49
	s_nop 0
	global_load_lds_dwordx4 v[158:159], off
	v_lshl_add_u64 v[158:159], v[180:181], 0, s[28:29]
	s_mov_b32 m0, s50
	s_nop 0
	global_load_lds_dwordx4 v[158:159], off
	s_waitcnt vmcnt(8)
	s_waitcnt lgkmcnt(0)
	s_setprio 1
	s_barrier
	v_mfma_f32_16x16x32_bf16 v[60:63], v[150:153], v[208:211], v[60:63]
	v_mfma_f32_16x16x32_bf16 v[52:55], v[162:165], v[208:211], v[52:55]
	v_mfma_f32_16x16x32_bf16 v[44:47], v[150:153], v[218:221], v[44:47]
	v_mfma_f32_16x16x32_bf16 v[36:39], v[162:165], v[218:221], v[36:39]
	v_mfma_f32_16x16x32_bf16 v[28:31], v[150:153], v[226:229], v[28:31]
	v_mfma_f32_16x16x32_bf16 v[20:23], v[162:165], v[226:229], v[20:23]
	v_mfma_f32_16x16x32_bf16 v[12:15], v[150:153], v[234:237], v[12:15]
	v_mfma_f32_16x16x32_bf16 v[4:7], v[162:165], v[234:237], v[4:7]
	v_mfma_f32_16x16x32_bf16 v[60:63], v[154:157], v[214:217], v[60:63]
	v_mfma_f32_16x16x32_bf16 v[52:55], v[166:169], v[214:217], v[52:55]
	v_mfma_f32_16x16x32_bf16 v[44:47], v[154:157], v[222:225], v[44:47]
	v_mfma_f32_16x16x32_bf16 v[36:39], v[166:169], v[222:225], v[36:39]
	v_mfma_f32_16x16x32_bf16 v[28:31], v[154:157], v[230:233], v[28:31]
	v_mfma_f32_16x16x32_bf16 v[20:23], v[166:169], v[230:233], v[20:23]
	v_mfma_f32_16x16x32_bf16 v[12:15], v[154:157], v[238:241], v[12:15]
	v_mfma_f32_16x16x32_bf16 v[4:7], v[166:169], v[238:241], v[4:7]
	s_setprio 0
	s_setprio 1
	v_mfma_f32_16x16x32_bf16 v[56:59], v[170:173], v[208:211], v[56:59]
	v_mfma_f32_16x16x32_bf16 v[48:51], v[188:191], v[208:211], v[48:51]
	v_mfma_f32_16x16x32_bf16 v[40:43], v[170:173], v[218:221], v[40:43]
	v_mfma_f32_16x16x32_bf16 v[32:35], v[188:191], v[218:221], v[32:35]
	v_mfma_f32_16x16x32_bf16 v[24:27], v[170:173], v[226:229], v[24:27]
	v_mfma_f32_16x16x32_bf16 v[16:19], v[188:191], v[226:229], v[16:19]
	v_mfma_f32_16x16x32_bf16 v[8:11], v[170:173], v[234:237], v[8:11]
	v_mfma_f32_16x16x32_bf16 v[0:3], v[188:191], v[234:237], v[0:3]
	v_mfma_f32_16x16x32_bf16 v[56:59], v[184:187], v[214:217], v[56:59]
	v_mfma_f32_16x16x32_bf16 v[48:51], v[192:195], v[214:217], v[48:51]
	v_mfma_f32_16x16x32_bf16 v[40:43], v[184:187], v[222:225], v[40:43]
	v_mfma_f32_16x16x32_bf16 v[32:35], v[192:195], v[222:225], v[32:35]
	v_mfma_f32_16x16x32_bf16 v[24:27], v[184:187], v[230:233], v[24:27]
	v_mfma_f32_16x16x32_bf16 v[16:19], v[192:195], v[230:233], v[16:19]
	v_mfma_f32_16x16x32_bf16 v[8:11], v[184:187], v[238:241], v[8:11]
	v_mfma_f32_16x16x32_bf16 v[0:3], v[192:195], v[238:241], v[0:3]
	s_setprio 0
	s_barrier
	s_add_i32 s51, s51, 2
	s_add_u32 s18, s18, 0x100
	s_addc_u32 s19, s19, 0
	s_add_u32 s42, s42, 0x100
	s_addc_u32 s43, s43, 0
	s_cmp_gt_u32 s51, 13
	s_cbranch_scc0 .LBB0_517

; #define PG8_STAGE(bufoff, gbase, voff) do { _Pragma("unroll") for (int _i = 0; _i < 2; ++_i) \
;         __builtin_amdgcn_global_load_lds((const unsigned*)((const char*)(gbase) + (voff)[_i]), (PG8_LAS unsigned*)(lds + (bufoff) + ldsw + _i * 8192), 16, 0, 0); } while (0)
; #define PG8_LDA(dst, b, h) do { _Pragma("unroll") for (int m = 0; m < 4; ++m) _Pragma("unroll") for (int k = 0; k < 2; ++k) dst[m][k] = *(const PG8_LAS bf16x8*)(lds + PG8_SA(b, h) + aoff + m * 2048 + k * 1024); } while (0)
; #define PG8_LDB(dst, b, h) do { _Pragma("unroll") for (int n = 0; n < 2; ++n) _Pragma("unroll") for (int k = 0; k < 2; ++k) dst[n][k] = *(const PG8_LAS bf16x8*)(lds + PG8_SB(b, h) + boff + n * 2048 + k * 1024); } while (0)
; #define PG8_WAIT_V(n) asm volatile("s_waitcnt vmcnt(" #n ")" ::: "memory")
; #define PG8_WAIT_L(n) asm volatile("s_waitcnt lgkmcnt(" #n ")" ::: "memory")
; #define PG8_BAR __builtin_amdgcn_s_barrier()
; #define PG8_SCHED __builtin_amdgcn_sched_barrier(0)
; template <class Epi, class Sched, bool ALIGN_EPI = false, bool SP2 = false>
; __device__ __forceinline__ void gemm_phase(PG8_LAS unsigned char* lds, const Gemm g, const Sched& S, const Epi& E, const int tid) {
;     ...
;         const bool has_next = S.next(ui + 1, nxt);
;         const char* nA = has_next ? (const char*)g.A + (size_t)nxt.pm * tstep : cA; const char* nB = has_next ? (const char*)g.Bt + (size_t)nxt.pn * tstep : cB;
;         for (int t = 0; t < nt; t += 2) {
;             const bool last = (t == nt - 2);
;             const char* a1 = cA + (size_t)(t + 1) * kstep;
;             const char* a2 = last ? nA : cA + (size_t)(t + 2) * kstep; const char* b2 = last ? nB : cB + (size_t)(t + 2) * kstep;
;             const char* a3 = a2 + kstep; const char* b3 = b2 + kstep;
;             if (last && has_next) S.a_ready(nxt);
;             if constexpr (SP2) {
;             PG8_LDB(B0, 0, 0); PG8_LDB(B1, 0, 1); PG8_SCHED; PG8_LDA(At, 0, 0); PG8_STAGE(PG8_SA(1, 1), a1 + hstep, voffA);
;             PG8_WAIT_V(8); PG8_WAIT_L(0); PG8_BAR; PG8_MMA(0, 0, At, B0); PG8_MMA(0, 1, At, B1); PG8_BAR; PG8_SCHED;
;             PG8_LDA(At, 0, 1); PG8_STAGE(PG8_SB(0, 0), b2, voffB); PG8_STAGE(PG8_SB(0, 1), b2 + hstep, voffB); PG8_STAGE(PG8_SA(0, 0), a2, voffA);
;             PG8_WAIT_V(8); PG8_WAIT_L(0); PG8_BAR; PG8_MMA(1, 0, At, B0); PG8_MMA(1, 1, At, B1); PG8_BAR; PG8_SCHED;
.LBB0_620:
	s_add_u32 s44, s50, 0x80
	s_addc_u32 s45, s51, 0
	s_add_u32 s37, s48, 0x100
	s_addc_u32 s50, s49, 0
	s_mov_b32 s48, 0
	s_add_i32 s51, s48, 2
	s_add_u32 vcc_lo, s44, 0x80
	s_addc_u32 s49, s45, 0
	s_cmp_eq_u32 s82, s48
	s_cselect_b32 s49, s35, s49
	s_cselect_b32 s48, s34, vcc_lo
	v_add_u32_e32 v156, s59, v174
	s_cselect_b32 vcc_hi, s47, s50
	s_cselect_b32 vcc_lo, s46, s37
	s_add_i32 s90, 0, 0x14000
	s_waitcnt lgkmcnt(0)
	ds_read_b128 v[144:147], v156
	ds_read_b128 v[148:151], v156 offset:1024
	ds_read_b128 v[152:155], v156 offset:2048
	ds_read_b128 v[184:187], v156 offset:3072
	v_add_u32_e32 v156, s90, v174
	ds_read_b128 v[188:191], v156
	ds_read_b128 v[192:195], v156 offset:1024
	ds_read_b128 v[214:217], v156 offset:2048
	ds_read_b128 v[218:221], v156 offset:3072
	v_lshl_add_u64 v[156:157], s[44:45], 0, v[140:141]
	s_add_i32 m0, s66, 0xc000
	ds_read_b128 v[222:225], v175
	ds_read_b128 v[226:229], v175 offset:1024
	ds_read_b128 v[230:233], v175 offset:2048
	ds_read_b128 v[234:237], v175 offset:3072
	ds_read_b128 v[238:241], v175 offset:4096
	ds_read_b128 v[242:245], v175 offset:5120
	ds_read_b128 v[246:249], v175 offset:6144
	ds_read_b128 v[208:211], v175 offset:7168
	global_load_lds_dwordx4 v[156:157], off
	v_lshl_add_u64 v[156:157], s[44:45], 0, v[142:143]
	s_add_i32 m0, s66, 0xe000
	s_nop 0
	global_load_lds_dwordx4 v[156:157], off
	s_waitcnt vmcnt(8)
	s_waitcnt lgkmcnt(0)
	s_setprio 1
	s_barrier
	v_mfma_f32_16x16x32_bf16 v[124:127], v[144:147], v[222:225], 0
	v_mfma_f32_16x16x32_bf16 v[120:123], v[152:155], v[222:225], 0
	v_mfma_f32_16x16x32_bf16 v[108:111], v[144:147], v[230:233], 0
	v_mfma_f32_16x16x32_bf16 v[104:107], v[152:155], v[230:233], 0
	v_mfma_f32_16x16x32_bf16 v[92:95], v[144:147], v[238:241], 0
	v_mfma_f32_16x16x32_bf16 v[88:91], v[152:155], v[238:241], 0
	v_mfma_f32_16x16x32_bf16 v[76:79], v[144:147], v[246:249], 0
	v_mfma_f32_16x16x32_bf16 v[72:75], v[152:155], v[246:249], 0
	v_mfma_f32_16x16x32_bf16 v[124:127], v[148:151], v[226:229], v[124:127]
	v_mfma_f32_16x16x32_bf16 v[120:123], v[184:187], v[226:229], v[120:123]
	v_mfma_f32_16x16x32_bf16 v[108:111], v[148:151], v[234:237], v[108:111]
	v_mfma_f32_16x16x32_bf16 v[104:107], v[184:187], v[234:237], v[104:107]
	v_mfma_f32_16x16x32_bf16 v[92:95], v[148:151], v[242:245], v[92:95]
	v_mfma_f32_16x16x32_bf16 v[88:91], v[184:187], v[242:245], v[88:91]
	v_mfma_f32_16x16x32_bf16 v[76:79], v[148:151], v[208:211], v[76:79]
	v_mfma_f32_16x16x32_bf16 v[72:75], v[184:187], v[208:211], v[72:75]
	s_setprio 0
	s_setprio 1
	v_mfma_f32_16x16x32_bf16 v[116:119], v[188:191], v[222:225], 0
	v_mfma_f32_16x16x32_bf16 v[112:115], v[214:217], v[222:225], 0
	v_mfma_f32_16x16x32_bf16 v[100:103], v[188:191], v[230:233], 0
	v_mfma_f32_16x16x32_bf16 v[96:99], v[214:217], v[230:233], 0
	v_mfma_f32_16x16x32_bf16 v[84:87], v[188:191], v[238:241], 0
	v_mfma_f32_16x16x32_bf16 v[80:83], v[214:217], v[238:241], 0
	v_mfma_f32_16x16x32_bf16 v[68:71], v[188:191], v[246:249], 0
	v_mfma_f32_16x16x32_bf16 v[64:67], v[214:217], v[246:249], 0
	v_mfma_f32_16x16x32_bf16 v[116:119], v[192:195], v[226:229], v[116:119]
	v_mfma_f32_16x16x32_bf16 v[112:115], v[218:221], v[226:229], v[112:115]
	v_mfma_f32_16x16x32_bf16 v[100:103], v[192:195], v[234:237], v[100:103]
	v_mfma_f32_16x16x32_bf16 v[96:99], v[218:221], v[234:237], v[96:99]
	v_mfma_f32_16x16x32_bf16 v[84:87], v[192:195], v[242:245], v[84:87]
	v_mfma_f32_16x16x32_bf16 v[80:83], v[218:221], v[242:245], v[80:83]
	v_mfma_f32_16x16x32_bf16 v[68:71], v[192:195], v[208:211], v[68:71]
	v_mfma_f32_16x16x32_bf16 v[64:67], v[218:221], v[208:211], v[64:67]
	s_setprio 0
	s_barrier
	s_add_i32 s91, s59, s65
	v_lshl_add_u64 v[156:157], vcc, 0, v[160:161]
	s_mov_b32 m0, s91
	ds_read_b128 v[208:211], v175 offset:16384
	ds_read_b128 v[222:225], v175 offset:17408
	ds_read_b128 v[226:229], v175 offset:18432
	ds_read_b128 v[230:233], v175 offset:19456
	ds_read_b128 v[234:237], v175 offset:20480
	ds_read_b128 v[238:241], v175 offset:21504
	ds_read_b128 v[242:245], v175 offset:22528
	ds_read_b128 v[246:249], v175 offset:23552
	global_load_lds_dwordx4 v[156:157], off
	s_add_i32 m0, s91, 0x2000
	v_lshl_add_u64 v[250:251], vcc, 0, v[136:137]
	s_add_u32 vcc_lo, vcc_lo, s94
	s_addc_u32 vcc_hi, vcc_hi, 0
	s_add_i32 s90, s90, s65
	global_load_lds_dwordx4 v[250:251], off
	v_lshl_add_u64 v[178:179], vcc, 0, v[160:161]
	s_mov_b32 m0, s90
	v_lshl_add_u64 v[180:181], vcc, 0, v[136:137]
	global_load_lds_dwordx4 v[178:179], off
	s_add_i32 m0, s90, 0x2000
	v_lshl_add_u64 v[204:205], s[48:49], 0, v[132:133]
	global_load_lds_dwordx4 v[180:181], off
	s_mov_b32 m0, s66
	v_lshl_add_u64 v[196:197], s[48:49], 0, v[134:135]
	global_load_lds_dwordx4 v[204:205], off
	s_mov_b32 m0, s67
	s_nop 0
	global_load_lds_dwordx4 v[196:197], off
	s_waitcnt vmcnt(8)
	s_waitcnt lgkmcnt(0)
	s_setprio 1
	s_barrier
; #define PG8_STAGE(bufoff, gbase, voff) do { _Pragma("unroll") for (int _i = 0; _i < 2; ++_i) \
;         __builtin_amdgcn_global_load_lds((const unsigned*)((const char*)(gbase) + (voff)[_i]), (PG8_LAS unsigned*)(lds + (bufoff) + ldsw + _i * 8192), 16, 0, 0); } while (0)
; #define PG8_LDA(dst, b, h) do { _Pragma("unroll") for (int m = 0; m < 4; ++m) _Pragma("unroll") for (int k = 0; k < 2; ++k) dst[m][k] = *(const PG8_LAS bf16x8*)(lds + PG8_SA(b, h) + aoff + m * 2048 + k * 1024); } while (0)
; #define PG8_LDB(dst, b, h) do { _Pragma("unroll") for (int n = 0; n < 2; ++n) _Pragma("unroll") for (int k = 0; k < 2; ++k) dst[n][k] = *(const PG8_LAS bf16x8*)(lds + PG8_SB(b, h) + boff + n * 2048 + k * 1024); } while (0)
; #define PG8_MMA(ai, bj, At, Bt) do { __builtin_amdgcn_s_setprio(1); _Pragma("unroll") for (int m = 0; m < 4; ++m) _Pragma("unroll") for (int n = 0; n < 2; ++n) _Pragma("unroll") for (int k = 0; k < 2; ++k) \
;         acc[ai][bj][m][n] = __builtin_amdgcn_mfma_f32_16x16x32_bf16(Bt[n][k], At[m][k], acc[ai][bj][m][n], 0, 0, 0); __builtin_amdgcn_s_setprio(0); } while (0)
; #define PG8_WAIT_V(n) asm volatile("s_waitcnt vmcnt(" #n ")" ::: "memory")
; #define PG8_WAIT_L(n) asm volatile("s_waitcnt lgkmcnt(" #n ")" ::: "memory")
; #define PG8_BAR __builtin_amdgcn_s_barrier()
; #define PG8_SCHED __builtin_amdgcn_sched_barrier(0)
; template <class Epi, class Sched, bool ALIGN_EPI = false, bool SP2 = false>
; __device__ __forceinline__ void gemm_phase(PG8_LAS unsigned char* lds, const Gemm g, const Sched& S, const Epi& E, const int tid) {
;     ...
;             PG8_WAIT_V(8); PG8_WAIT_L(0); PG8_BAR; PG8_MMA(1, 0, At, B0); PG8_MMA(1, 1, At, B1); PG8_BAR; PG8_SCHED;
;             PG8_LDB(B0, 1, 0); PG8_LDB(B1, 1, 1); PG8_SCHED; PG8_LDA(At, 1, 0); PG8_STAGE(PG8_SA(0, 1), a2 + hstep, voffA);
;             PG8_WAIT_V(8); PG8_WAIT_L(0); PG8_BAR; PG8_MMA(0, 0, At, B0); PG8_MMA(0, 1, At, B1); PG8_BAR; PG8_SCHED;
	v_mfma_f32_16x16x32_bf16 v[60:63], v[144:147], v[208:211], 0
	v_mfma_f32_16x16x32_bf16 v[56:59], v[152:155], v[208:211], 0
	v_mfma_f32_16x16x32_bf16 v[44:47], v[144:147], v[226:229], 0
	v_mfma_f32_16x16x32_bf16 v[40:43], v[152:155], v[226:229], 0
	v_mfma_f32_16x16x32_bf16 v[28:31], v[144:147], v[234:237], 0
	v_mfma_f32_16x16x32_bf16 v[24:27], v[152:155], v[234:237], 0
	v_mfma_f32_16x16x32_bf16 v[12:15], v[144:147], v[242:245], 0
	v_mfma_f32_16x16x32_bf16 v[8:11], v[152:155], v[242:245], 0
	v_mfma_f32_16x16x32_bf16 v[60:63], v[148:151], v[222:225], v[60:63]
	v_mfma_f32_16x16x32_bf16 v[56:59], v[184:187], v[222:225], v[56:59]
	v_mfma_f32_16x16x32_bf16 v[44:47], v[148:151], v[230:233], v[44:47]
	v_mfma_f32_16x16x32_bf16 v[40:43], v[184:187], v[230:233], v[40:43]
	v_mfma_f32_16x16x32_bf16 v[28:31], v[148:151], v[238:241], v[28:31]
	v_mfma_f32_16x16x32_bf16 v[24:27], v[184:187], v[238:241], v[24:27]
	v_mfma_f32_16x16x32_bf16 v[12:15], v[148:151], v[246:249], v[12:15]
	v_mfma_f32_16x16x32_bf16 v[8:11], v[184:187], v[246:249], v[8:11]
	s_setprio 0
	s_setprio 1
	v_mfma_f32_16x16x32_bf16 v[52:55], v[188:191], v[208:211], 0
	v_mfma_f32_16x16x32_bf16 v[48:51], v[214:217], v[208:211], 0
	v_mfma_f32_16x16x32_bf16 v[36:39], v[188:191], v[226:229], 0
	v_mfma_f32_16x16x32_bf16 v[32:35], v[214:217], v[226:229], 0
	v_mfma_f32_16x16x32_bf16 v[20:23], v[188:191], v[234:237], 0
	v_mfma_f32_16x16x32_bf16 v[16:19], v[214:217], v[234:237], 0
	v_mfma_f32_16x16x32_bf16 v[4:7], v[188:191], v[242:245], 0
	v_mfma_f32_16x16x32_bf16 v[0:3], v[214:217], v[242:245], 0
	v_mfma_f32_16x16x32_bf16 v[52:55], v[192:195], v[222:225], v[52:55]
	v_mfma_f32_16x16x32_bf16 v[48:51], v[218:221], v[222:225], v[48:51]
	v_mfma_f32_16x16x32_bf16 v[36:39], v[192:195], v[230:233], v[36:39]
	v_mfma_f32_16x16x32_bf16 v[32:35], v[218:221], v[230:233], v[32:35]
	v_mfma_f32_16x16x32_bf16 v[20:23], v[192:195], v[238:241], v[20:23]
	v_mfma_f32_16x16x32_bf16 v[16:19], v[218:221], v[238:241], v[16:19]
	v_mfma_f32_16x16x32_bf16 v[4:7], v[192:195], v[246:249], v[4:7]
	v_mfma_f32_16x16x32_bf16 v[0:3], v[218:221], v[246:249], v[0:3]
	s_setprio 0
	s_barrier
	s_add_i32 s90, 0, 0x18000
	v_add_u32_e32 v183, s90, v174
	s_add_i32 s91, 0, 0x1c000
	ds_read_b128 v[144:147], v183
	ds_read_b128 v[148:151], v183 offset:1024
	ds_read_b128 v[152:155], v183 offset:2048
	ds_read_b128 v[184:187], v183 offset:3072
	v_add_u32_e32 v183, s91, v174
	ds_read_b128 v[188:191], v183
	ds_read_b128 v[192:195], v183 offset:1024
	ds_read_b128 v[208:211], v183 offset:2048
	ds_read_b128 v[214:217], v183 offset:3072
	s_add_u32 s48, s48, s94
	s_addc_u32 s49, s49, 0
	s_mov_b32 m0, s68
	v_lshl_add_u64 v[198:199], s[48:49], 0, v[132:133]
	ds_read_b128 v[218:221], v175 offset:32768
	ds_read_b128 v[222:225], v175 offset:33792
	ds_read_b128 v[226:229], v175 offset:34816
	ds_read_b128 v[230:233], v175 offset:35840
	ds_read_b128 v[234:237], v175 offset:36864
	ds_read_b128 v[238:241], v175 offset:37888
	ds_read_b128 v[242:245], v175 offset:38912
	ds_read_b128 v[246:249], v175 offset:39936
	global_load_lds_dwordx4 v[198:199], off
	v_lshl_add_u64 v[198:199], s[48:49], 0, v[134:135]
	s_mov_b32 m0, s69
	s_nop 0
	global_load_lds_dwordx4 v[198:199], off
	s_waitcnt vmcnt(8)
	s_waitcnt lgkmcnt(0)
	s_setprio 1
	s_barrier
	v_mfma_f32_16x16x32_bf16 v[124:127], v[144:147], v[218:221], v[124:127]
	v_mfma_f32_16x16x32_bf16 v[120:123], v[152:155], v[218:221], v[120:123]
	v_mfma_f32_16x16x32_bf16 v[108:111], v[144:147], v[226:229], v[108:111]
	v_mfma_f32_16x16x32_bf16 v[104:107], v[152:155], v[226:229], v[104:107]
	v_mfma_f32_16x16x32_bf16 v[92:95], v[144:147], v[234:237], v[92:95]
	v_mfma_f32_16x16x32_bf16 v[88:91], v[152:155], v[234:237], v[88:91]
	v_mfma_f32_16x16x32_bf16 v[76:79], v[144:147], v[242:245], v[76:79]
	v_mfma_f32_16x16x32_bf16 v[72:75], v[152:155], v[242:245], v[72:75]
	v_mfma_f32_16x16x32_bf16 v[124:127], v[148:151], v[222:225], v[124:127]
	v_mfma_f32_16x16x32_bf16 v[120:123], v[184:187], v[222:225], v[120:123]
	v_mfma_f32_16x16x32_bf16 v[108:111], v[148:151], v[230:233], v[108:111]
	v_mfma_f32_16x16x32_bf16 v[104:107], v[184:187], v[230:233], v[104:107]
	v_mfma_f32_16x16x32_bf16 v[92:95], v[148:151], v[238:241], v[92:95]
	v_mfma_f32_16x16x32_bf16 v[88:91], v[184:187], v[238:241], v[88:91]
	v_mfma_f32_16x16x32_bf16 v[76:79], v[148:151], v[246:249], v[76:79]
	v_mfma_f32_16x16x32_bf16 v[72:75], v[184:187], v[246:249], v[72:75]
	s_setprio 0
	s_setprio 1
	v_mfma_f32_16x16x32_bf16 v[116:119], v[188:191], v[218:221], v[116:119]
	v_mfma_f32_16x16x32_bf16 v[112:115], v[208:211], v[218:221], v[112:115]
	v_mfma_f32_16x16x32_bf16 v[100:103], v[188:191], v[226:229], v[100:103]
	v_mfma_f32_16x16x32_bf16 v[96:99], v[208:211], v[226:229], v[96:99]
	v_mfma_f32_16x16x32_bf16 v[84:87], v[188:191], v[234:237], v[84:87]
	v_mfma_f32_16x16x32_bf16 v[80:83], v[208:211], v[234:237], v[80:83]
	v_mfma_f32_16x16x32_bf16 v[68:71], v[188:191], v[242:245], v[68:71]
	v_mfma_f32_16x16x32_bf16 v[64:67], v[208:211], v[242:245], v[64:67]
	v_mfma_f32_16x16x32_bf16 v[116:119], v[192:195], v[222:225], v[116:119]
	v_mfma_f32_16x16x32_bf16 v[112:115], v[214:217], v[222:225], v[112:115]
	v_mfma_f32_16x16x32_bf16 v[100:103], v[192:195], v[230:233], v[100:103]
	v_mfma_f32_16x16x32_bf16 v[96:99], v[214:217], v[230:233], v[96:99]
	v_mfma_f32_16x16x32_bf16 v[84:87], v[192:195], v[238:241], v[84:87]
	v_mfma_f32_16x16x32_bf16 v[80:83], v[214:217], v[238:241], v[80:83]
	v_mfma_f32_16x16x32_bf16 v[68:71], v[192:195], v[246:249], v[68:71]
	v_mfma_f32_16x16x32_bf16 v[64:67], v[214:217], v[246:249], v[64:67]
	s_setprio 0
	s_barrier
; #define PG8_STAGE(bufoff, gbase, voff) do { _Pragma("unroll") for (int _i = 0; _i < 2; ++_i) \
;         __builtin_amdgcn_global_load_lds((const unsigned*)((const char*)(gbase) + (voff)[_i]), (PG8_LAS unsigned*)(lds + (bufoff) + ldsw + _i * 8192), 16, 0, 0); } while (0)
; #define PG8_LDA(dst, b, h) do { _Pragma("unroll") for (int m = 0; m < 4; ++m) _Pragma("unroll") for (int k = 0; k < 2; ++k) dst[m][k] = *(const PG8_LAS bf16x8*)(lds + PG8_SA(b, h) + aoff + m * 2048 + k * 1024); } while (0)
; #define PG8_WAIT_V(n) asm volatile("s_waitcnt vmcnt(" #n ")" ::: "memory")
; #define PG8_WAIT_L(n) asm volatile("s_waitcnt lgkmcnt(" #n ")" ::: "memory")
; #define PG8_BAR __builtin_amdgcn_s_barrier()
; template <class Epi, class Sched, bool ALIGN_EPI = false, bool SP2 = false>
; __device__ __forceinline__ void gemm_phase(PG8_LAS unsigned char* lds, const Gemm g, const Sched& S, const Epi& E, const int tid) {
;     ...
;         for (int t = 0; t < nt; t += 2) {
;             const bool last = (t == nt - 2);
;             const char* a1 = cA + (size_t)(t + 1) * kstep;
;             const char* a2 = last ? nA : cA + (size_t)(t + 2) * kstep; const char* b2 = last ? nB : cB + (size_t)(t + 2) * kstep;
;             const char* a3 = a2 + kstep; const char* b3 = b2 + kstep;
;             if (last && has_next) S.a_ready(nxt);
;             if constexpr (SP2) {
;             PG8_LDB(B0, 0, 0); PG8_LDB(B1, 0, 1); PG8_SCHED; PG8_LDA(At, 0, 0); PG8_STAGE(PG8_SA(1, 1), a1 + hstep, voffA);
;             PG8_WAIT_V(8); PG8_WAIT_L(0); PG8_BAR; PG8_MMA(0, 0, At, B0); PG8_MMA(0, 1, At, B1); PG8_BAR; PG8_SCHED;
;             PG8_LDA(At, 0, 1); PG8_STAGE(PG8_SB(0, 0), b2, voffB); PG8_STAGE(PG8_SB(0, 1), b2 + hstep, voffB); PG8_STAGE(PG8_SA(0, 0), a2, voffA);
;             PG8_WAIT_V(8); PG8_WAIT_L(0); PG8_BAR; PG8_MMA(1, 0, At, B0); PG8_MMA(1, 1, At, B1); PG8_BAR; PG8_SCHED;
;             PG8_LDB(B0, 1, 0); PG8_LDB(B1, 1, 1); PG8_SCHED; PG8_LDA(At, 1, 0); PG8_STAGE(PG8_SA(0, 1), a2 + hstep, voffA);
;             PG8_WAIT_V(8); PG8_WAIT_L(0); PG8_BAR; PG8_MMA(0, 0, At, B0); PG8_MMA(0, 1, At, B1); PG8_BAR; PG8_SCHED;
;             PG8_LDA(At, 1, 1); PG8_STAGE(PG8_SB(1, 0), b3, voffB); PG8_STAGE(PG8_SB(1, 1), b3 + hstep, voffB); PG8_STAGE(PG8_SA(1, 0), a3, voffA);
;             PG8_WAIT_V(8); PG8_WAIT_L(0); PG8_BAR; PG8_MMA(1, 0, At, B0); PG8_MMA(1, 1, At, B1); PG8_BAR; PG8_SCHED;
	s_add_i32 s48, s90, s65
	v_lshl_add_u64 v[156:157], v[156:157], 0, s[28:29]
	s_mov_b32 m0, s48
	ds_read_b128 v[218:221], v175 offset:49152
	ds_read_b128 v[222:225], v175 offset:50176
	ds_read_b128 v[226:229], v175 offset:51200
	ds_read_b128 v[230:233], v175 offset:52224
	ds_read_b128 v[234:237], v175 offset:53248
	ds_read_b128 v[238:241], v175 offset:54272
	ds_read_b128 v[242:245], v175 offset:55296
	ds_read_b128 v[246:249], v175 offset:56320
	global_load_lds_dwordx4 v[156:157], off
	v_lshl_add_u64 v[156:157], v[250:251], 0, s[28:29]
	s_add_i32 m0, s48, 0x2000
	s_add_i32 s48, s91, s65
	global_load_lds_dwordx4 v[156:157], off
	v_lshl_add_u64 v[156:157], v[178:179], 0, s[28:29]
	s_mov_b32 m0, s48
	s_nop 0
	global_load_lds_dwordx4 v[156:157], off
	v_lshl_add_u64 v[156:157], v[180:181], 0, s[28:29]
	s_add_i32 m0, s48, 0x2000
	s_nop 0
	global_load_lds_dwordx4 v[156:157], off
	v_lshl_add_u64 v[156:157], v[204:205], 0, s[28:29]
	s_mov_b32 m0, s70
	s_nop 0
	global_load_lds_dwordx4 v[156:157], off
	v_lshl_add_u64 v[156:157], v[196:197], 0, s[28:29]
	s_mov_b32 m0, s71
	s_nop 0
	global_load_lds_dwordx4 v[156:157], off
	s_waitcnt vmcnt(8)
	s_waitcnt lgkmcnt(0)
	s_setprio 1
	s_barrier
	v_mfma_f32_16x16x32_bf16 v[60:63], v[144:147], v[218:221], v[60:63]
	v_mfma_f32_16x16x32_bf16 v[56:59], v[152:155], v[218:221], v[56:59]
	v_mfma_f32_16x16x32_bf16 v[44:47], v[144:147], v[226:229], v[44:47]
	v_mfma_f32_16x16x32_bf16 v[40:43], v[152:155], v[226:229], v[40:43]
	v_mfma_f32_16x16x32_bf16 v[28:31], v[144:147], v[234:237], v[28:31]
	v_mfma_f32_16x16x32_bf16 v[24:27], v[152:155], v[234:237], v[24:27]
	v_mfma_f32_16x16x32_bf16 v[12:15], v[144:147], v[242:245], v[12:15]
	v_mfma_f32_16x16x32_bf16 v[8:11], v[152:155], v[242:245], v[8:11]
	v_mfma_f32_16x16x32_bf16 v[60:63], v[148:151], v[222:225], v[60:63]
	v_mfma_f32_16x16x32_bf16 v[56:59], v[184:187], v[222:225], v[56:59]
	v_mfma_f32_16x16x32_bf16 v[44:47], v[148:151], v[230:233], v[44:47]
	v_mfma_f32_16x16x32_bf16 v[40:43], v[184:187], v[230:233], v[40:43]
	v_mfma_f32_16x16x32_bf16 v[28:31], v[148:151], v[238:241], v[28:31]
	v_mfma_f32_16x16x32_bf16 v[24:27], v[184:187], v[238:241], v[24:27]
	v_mfma_f32_16x16x32_bf16 v[12:15], v[148:151], v[246:249], v[12:15]
	v_mfma_f32_16x16x32_bf16 v[8:11], v[184:187], v[246:249], v[8:11]
	s_setprio 0
	s_setprio 1
	v_mfma_f32_16x16x32_bf16 v[52:55], v[188:191], v[218:221], v[52:55]
	v_mfma_f32_16x16x32_bf16 v[48:51], v[208:211], v[218:221], v[48:51]
	v_mfma_f32_16x16x32_bf16 v[36:39], v[188:191], v[226:229], v[36:39]
	v_mfma_f32_16x16x32_bf16 v[32:35], v[208:211], v[226:229], v[32:35]
	v_mfma_f32_16x16x32_bf16 v[20:23], v[188:191], v[234:237], v[20:23]
	v_mfma_f32_16x16x32_bf16 v[16:19], v[208:211], v[234:237], v[16:19]
	v_mfma_f32_16x16x32_bf16 v[4:7], v[188:191], v[242:245], v[4:7]
	v_mfma_f32_16x16x32_bf16 v[0:3], v[208:211], v[242:245], v[0:3]
	v_mfma_f32_16x16x32_bf16 v[52:55], v[192:195], v[222:225], v[52:55]
	v_mfma_f32_16x16x32_bf16 v[48:51], v[214:217], v[222:225], v[48:51]
	v_mfma_f32_16x16x32_bf16 v[36:39], v[192:195], v[230:233], v[36:39]
	v_mfma_f32_16x16x32_bf16 v[32:35], v[214:217], v[230:233], v[32:35]
	v_mfma_f32_16x16x32_bf16 v[20:23], v[192:195], v[238:241], v[20:23]
	v_mfma_f32_16x16x32_bf16 v[16:19], v[214:217], v[238:241], v[16:19]
	v_mfma_f32_16x16x32_bf16 v[4:7], v[192:195], v[246:249], v[4:7]
	v_mfma_f32_16x16x32_bf16 v[0:3], v[214:217], v[246:249], v[0:3]
	s_setprio 0
	s_barrier
	s_add_u32 s44, s44, 0x100
	s_addc_u32 s45, s45, 0
	s_add_u32 s37, s37, 0x100
	s_addc_u32 s50, s50, 0
	s_cmp_ge_u32 s51, s80
	s_mov_b32 s48, s51
	s_cbranch_scc1 .Lmy_kdone_3
.LBB0_621:
	s_add_i32 s51, s48, 2
	s_add_u32 vcc_lo, s44, 0x80
	s_addc_u32 s49, s45, 0
	s_cmp_eq_u32 s82, s48
	s_cselect_b32 s49, s35, s49
	s_cselect_b32 s48, s34, vcc_lo
	v_add_u32_e32 v156, s59, v174
	s_cselect_b32 vcc_hi, s47, s50
	s_cselect_b32 vcc_lo, s46, s37
	s_add_i32 s90, 0, 0x14000
	s_waitcnt lgkmcnt(0)
	ds_read_b128 v[144:147], v156
	ds_read_b128 v[148:151], v156 offset:1024
	ds_read_b128 v[152:155], v156 offset:2048
	ds_read_b128 v[184:187], v156 offset:3072
	v_add_u32_e32 v156, s90, v174
	ds_read_b128 v[188:191], v156
	ds_read_b128 v[192:195], v156 offset:1024
	ds_read_b128 v[214:217], v156 offset:2048
	ds_read_b128 v[218:221], v156 offset:3072
	v_lshl_add_u64 v[156:157], s[44:45], 0, v[140:141]
	s_add_i32 m0, s66, 0xc000
	ds_read_b128 v[222:225], v175
	ds_read_b128 v[226:229], v175 offset:1024
	ds_read_b128 v[230:233], v175 offset:2048
	ds_read_b128 v[234:237], v175 offset:3072
	ds_read_b128 v[238:241], v175 offset:4096
	ds_read_b128 v[242:245], v175 offset:5120
	ds_read_b128 v[246:249], v175 offset:6144
	ds_read_b128 v[208:211], v175 offset:7168
	global_load_lds_dwordx4 v[156:157], off
	v_lshl_add_u64 v[156:157], s[44:45], 0, v[142:143]
	s_add_i32 m0, s66, 0xe000
	s_nop 0
	global_load_lds_dwordx4 v[156:157], off
	s_waitcnt vmcnt(8)
	s_waitcnt lgkmcnt(0)
	s_setprio 1
	s_barrier
; #define PG8_STAGE(bufoff, gbase, voff) do { _Pragma("unroll") for (int _i = 0; _i < 2; ++_i) \
;         __builtin_amdgcn_global_load_lds((const unsigned*)((const char*)(gbase) + (voff)[_i]), (PG8_LAS unsigned*)(lds + (bufoff) + ldsw + _i * 8192), 16, 0, 0); } while (0)
; #define PG8_LDA(dst, b, h) do { _Pragma("unroll") for (int m = 0; m < 4; ++m) _Pragma("unroll") for (int k = 0; k < 2; ++k) dst[m][k] = *(const PG8_LAS bf16x8*)(lds + PG8_SA(b, h) + aoff + m * 2048 + k * 1024); } while (0)
; #define PG8_MMA(ai, bj, At, Bt) do { __builtin_amdgcn_s_setprio(1); _Pragma("unroll") for (int m = 0; m < 4; ++m) _Pragma("unroll") for (int n = 0; n < 2; ++n) _Pragma("unroll") for (int k = 0; k < 2; ++k) \
;         acc[ai][bj][m][n] = __builtin_amdgcn_mfma_f32_16x16x32_bf16(Bt[n][k], At[m][k], acc[ai][bj][m][n], 0, 0, 0); __builtin_amdgcn_s_setprio(0); } while (0)
; #define PG8_WAIT_V(n) asm volatile("s_waitcnt vmcnt(" #n ")" ::: "memory")
; #define PG8_WAIT_L(n) asm volatile("s_waitcnt lgkmcnt(" #n ")" ::: "memory")
; #define PG8_BAR __builtin_amdgcn_s_barrier()
; #define PG8_SCHED __builtin_amdgcn_sched_barrier(0)
; template <class Epi, class Sched, bool ALIGN_EPI = false, bool SP2 = false>
; __device__ __forceinline__ void gemm_phase(PG8_LAS unsigned char* lds, const Gemm g, const Sched& S, const Epi& E, const int tid) {
;     ...
;             PG8_WAIT_V(8); PG8_WAIT_L(0); PG8_BAR; PG8_MMA(0, 0, At, B0); PG8_MMA(0, 1, At, B1); PG8_BAR; PG8_SCHED;
;             PG8_LDA(At, 0, 1); PG8_STAGE(PG8_SB(0, 0), b2, voffB); PG8_STAGE(PG8_SB(0, 1), b2 + hstep, voffB); PG8_STAGE(PG8_SA(0, 0), a2, voffA);
;             PG8_WAIT_V(8); PG8_WAIT_L(0); PG8_BAR; PG8_MMA(1, 0, At, B0); PG8_MMA(1, 1, At, B1); PG8_BAR; PG8_SCHED;
	v_mfma_f32_16x16x32_bf16 v[124:127], v[144:147], v[222:225], v[124:127]
	v_mfma_f32_16x16x32_bf16 v[120:123], v[152:155], v[222:225], v[120:123]
	v_mfma_f32_16x16x32_bf16 v[108:111], v[144:147], v[230:233], v[108:111]
	v_mfma_f32_16x16x32_bf16 v[104:107], v[152:155], v[230:233], v[104:107]
	v_mfma_f32_16x16x32_bf16 v[92:95], v[144:147], v[238:241], v[92:95]
	v_mfma_f32_16x16x32_bf16 v[88:91], v[152:155], v[238:241], v[88:91]
	v_mfma_f32_16x16x32_bf16 v[76:79], v[144:147], v[246:249], v[76:79]
	v_mfma_f32_16x16x32_bf16 v[72:75], v[152:155], v[246:249], v[72:75]
	v_mfma_f32_16x16x32_bf16 v[124:127], v[148:151], v[226:229], v[124:127]
	v_mfma_f32_16x16x32_bf16 v[120:123], v[184:187], v[226:229], v[120:123]
	v_mfma_f32_16x16x32_bf16 v[108:111], v[148:151], v[234:237], v[108:111]
	v_mfma_f32_16x16x32_bf16 v[104:107], v[184:187], v[234:237], v[104:107]
	v_mfma_f32_16x16x32_bf16 v[92:95], v[148:151], v[242:245], v[92:95]
	v_mfma_f32_16x16x32_bf16 v[88:91], v[184:187], v[242:245], v[88:91]
	v_mfma_f32_16x16x32_bf16 v[76:79], v[148:151], v[208:211], v[76:79]
	v_mfma_f32_16x16x32_bf16 v[72:75], v[184:187], v[208:211], v[72:75]
	s_setprio 0
	s_setprio 1
	v_mfma_f32_16x16x32_bf16 v[116:119], v[188:191], v[222:225], v[116:119]
	v_mfma_f32_16x16x32_bf16 v[112:115], v[214:217], v[222:225], v[112:115]
	v_mfma_f32_16x16x32_bf16 v[100:103], v[188:191], v[230:233], v[100:103]
	v_mfma_f32_16x16x32_bf16 v[96:99], v[214:217], v[230:233], v[96:99]
	v_mfma_f32_16x16x32_bf16 v[84:87], v[188:191], v[238:241], v[84:87]
	v_mfma_f32_16x16x32_bf16 v[80:83], v[214:217], v[238:241], v[80:83]
	v_mfma_f32_16x16x32_bf16 v[68:71], v[188:191], v[246:249], v[68:71]
	v_mfma_f32_16x16x32_bf16 v[64:67], v[214:217], v[246:249], v[64:67]
	v_mfma_f32_16x16x32_bf16 v[116:119], v[192:195], v[226:229], v[116:119]
	v_mfma_f32_16x16x32_bf16 v[112:115], v[218:221], v[226:229], v[112:115]
	v_mfma_f32_16x16x32_bf16 v[100:103], v[192:195], v[234:237], v[100:103]
	v_mfma_f32_16x16x32_bf16 v[96:99], v[218:221], v[234:237], v[96:99]
	v_mfma_f32_16x16x32_bf16 v[84:87], v[192:195], v[242:245], v[84:87]
	v_mfma_f32_16x16x32_bf16 v[80:83], v[218:221], v[242:245], v[80:83]
	v_mfma_f32_16x16x32_bf16 v[68:71], v[192:195], v[208:211], v[68:71]
	v_mfma_f32_16x16x32_bf16 v[64:67], v[218:221], v[208:211], v[64:67]
	s_setprio 0
	s_barrier
	s_add_i32 s91, s59, s65
	v_lshl_add_u64 v[156:157], vcc, 0, v[160:161]
	s_mov_b32 m0, s91
	ds_read_b128 v[208:211], v175 offset:16384
	ds_read_b128 v[222:225], v175 offset:17408
	ds_read_b128 v[226:229], v175 offset:18432
	ds_read_b128 v[230:233], v175 offset:19456
	ds_read_b128 v[234:237], v175 offset:20480
	ds_read_b128 v[238:241], v175 offset:21504
	ds_read_b128 v[242:245], v175 offset:22528
	ds_read_b128 v[246:249], v175 offset:23552
	global_load_lds_dwordx4 v[156:157], off
	s_add_i32 m0, s91, 0x2000
	v_lshl_add_u64 v[250:251], vcc, 0, v[136:137]
	s_add_u32 vcc_lo, vcc_lo, s94
	s_addc_u32 vcc_hi, vcc_hi, 0
	s_add_i32 s90, s90, s65
	global_load_lds_dwordx4 v[250:251], off
	v_lshl_add_u64 v[178:179], vcc, 0, v[160:161]
	s_mov_b32 m0, s90
	v_lshl_add_u64 v[180:181], vcc, 0, v[136:137]
	global_load_lds_dwordx4 v[178:179], off
	s_add_i32 m0, s90, 0x2000
	v_lshl_add_u64 v[204:205], s[48:49], 0, v[132:133]
	global_load_lds_dwordx4 v[180:181], off
	s_mov_b32 m0, s66
	v_lshl_add_u64 v[196:197], s[48:49], 0, v[134:135]
	global_load_lds_dwordx4 v[204:205], off
	s_mov_b32 m0, s67
	s_nop 0
	global_load_lds_dwordx4 v[196:197], off
	s_waitcnt vmcnt(8)
	s_waitcnt lgkmcnt(0)
	s_setprio 1
	s_barrier
	v_mfma_f32_16x16x32_bf16 v[60:63], v[144:147], v[208:211], v[60:63]
	v_mfma_f32_16x16x32_bf16 v[56:59], v[152:155], v[208:211], v[56:59]
	v_mfma_f32_16x16x32_bf16 v[44:47], v[144:147], v[226:229], v[44:47]
	v_mfma_f32_16x16x32_bf16 v[40:43], v[152:155], v[226:229], v[40:43]
	v_mfma_f32_16x16x32_bf16 v[28:31], v[144:147], v[234:237], v[28:31]
	v_mfma_f32_16x16x32_bf16 v[24:27], v[152:155], v[234:237], v[24:27]
	v_mfma_f32_16x16x32_bf16 v[12:15], v[144:147], v[242:245], v[12:15]
	v_mfma_f32_16x16x32_bf16 v[8:11], v[152:155], v[242:245], v[8:11]
	v_mfma_f32_16x16x32_bf16 v[60:63], v[148:151], v[222:225], v[60:63]
	v_mfma_f32_16x16x32_bf16 v[56:59], v[184:187], v[222:225], v[56:59]
	v_mfma_f32_16x16x32_bf16 v[44:47], v[148:151], v[230:233], v[44:47]
	v_mfma_f32_16x16x32_bf16 v[40:43], v[184:187], v[230:233], v[40:43]
	v_mfma_f32_16x16x32_bf16 v[28:31], v[148:151], v[238:241], v[28:31]
	v_mfma_f32_16x16x32_bf16 v[24:27], v[184:187], v[238:241], v[24:27]
	v_mfma_f32_16x16x32_bf16 v[12:15], v[148:151], v[246:249], v[12:15]
	v_mfma_f32_16x16x32_bf16 v[8:11], v[184:187], v[246:249], v[8:11]
	s_setprio 0
	s_setprio 1
	v_mfma_f32_16x16x32_bf16 v[52:55], v[188:191], v[208:211], v[52:55]
	v_mfma_f32_16x16x32_bf16 v[48:51], v[214:217], v[208:211], v[48:51]
	v_mfma_f32_16x16x32_bf16 v[36:39], v[188:191], v[226:229], v[36:39]
	v_mfma_f32_16x16x32_bf16 v[32:35], v[214:217], v[226:229], v[32:35]
	v_mfma_f32_16x16x32_bf16 v[20:23], v[188:191], v[234:237], v[20:23]
	v_mfma_f32_16x16x32_bf16 v[16:19], v[214:217], v[234:237], v[16:19]
	v_mfma_f32_16x16x32_bf16 v[4:7], v[188:191], v[242:245], v[4:7]
	v_mfma_f32_16x16x32_bf16 v[0:3], v[214:217], v[242:245], v[0:3]
	v_mfma_f32_16x16x32_bf16 v[52:55], v[192:195], v[222:225], v[52:55]
	v_mfma_f32_16x16x32_bf16 v[48:51], v[218:221], v[222:225], v[48:51]
	v_mfma_f32_16x16x32_bf16 v[36:39], v[192:195], v[230:233], v[36:39]
	v_mfma_f32_16x16x32_bf16 v[32:35], v[218:221], v[230:233], v[32:35]
	v_mfma_f32_16x16x32_bf16 v[20:23], v[192:195], v[238:241], v[20:23]
	v_mfma_f32_16x16x32_bf16 v[16:19], v[218:221], v[238:241], v[16:19]
	v_mfma_f32_16x16x32_bf16 v[4:7], v[192:195], v[246:249], v[4:7]
	v_mfma_f32_16x16x32_bf16 v[0:3], v[218:221], v[246:249], v[0:3]
	s_setprio 0
	s_barrier
; #define PG8_STAGE(bufoff, gbase, voff) do { _Pragma("unroll") for (int _i = 0; _i < 2; ++_i) \
;         __builtin_amdgcn_global_load_lds((const unsigned*)((const char*)(gbase) + (voff)[_i]), (PG8_LAS unsigned*)(lds + (bufoff) + ldsw + _i * 8192), 16, 0, 0); } while (0)
; #define PG8_LDA(dst, b, h) do { _Pragma("unroll") for (int m = 0; m < 4; ++m) _Pragma("unroll") for (int k = 0; k < 2; ++k) dst[m][k] = *(const PG8_LAS bf16x8*)(lds + PG8_SA(b, h) + aoff + m * 2048 + k * 1024); } while (0)
; #define PG8_LDB(dst, b, h) do { _Pragma("unroll") for (int n = 0; n < 2; ++n) _Pragma("unroll") for (int k = 0; k < 2; ++k) dst[n][k] = *(const PG8_LAS bf16x8*)(lds + PG8_SB(b, h) + boff + n * 2048 + k * 1024); } while (0)
; #define PG8_MMA(ai, bj, At, Bt) do { __builtin_amdgcn_s_setprio(1); _Pragma("unroll") for (int m = 0; m < 4; ++m) _Pragma("unroll") for (int n = 0; n < 2; ++n) _Pragma("unroll") for (int k = 0; k < 2; ++k) \
;         acc[ai][bj][m][n] = __builtin_amdgcn_mfma_f32_16x16x32_bf16(Bt[n][k], At[m][k], acc[ai][bj][m][n], 0, 0, 0); __builtin_amdgcn_s_setprio(0); } while (0)
; #define PG8_WAIT_V(n) asm volatile("s_waitcnt vmcnt(" #n ")" ::: "memory")
; #define PG8_WAIT_L(n) asm volatile("s_waitcnt lgkmcnt(" #n ")" ::: "memory")
; #define PG8_BAR __builtin_amdgcn_s_barrier()
; #define PG8_SCHED __builtin_amdgcn_sched_barrier(0)
; template <class Epi, class Sched, bool ALIGN_EPI = false, bool SP2 = false>
; __device__ __forceinline__ void gemm_phase(PG8_LAS unsigned char* lds, const Gemm g, const Sched& S, const Epi& E, const int tid) {
;     ...
;             PG8_LDB(B0, 1, 0); PG8_LDB(B1, 1, 1); PG8_SCHED; PG8_LDA(At, 1, 0); PG8_STAGE(PG8_SA(0, 1), a2 + hstep, voffA);
;             PG8_WAIT_V(8); PG8_WAIT_L(0); PG8_BAR; PG8_MMA(0, 0, At, B0); PG8_MMA(0, 1, At, B1); PG8_BAR; PG8_SCHED;
	s_add_i32 s90, 0, 0x18000
	v_add_u32_e32 v183, s90, v174
	s_add_i32 s91, 0, 0x1c000
	ds_read_b128 v[144:147], v183
	ds_read_b128 v[148:151], v183 offset:1024
	ds_read_b128 v[152:155], v183 offset:2048
	ds_read_b128 v[184:187], v183 offset:3072
	v_add_u32_e32 v183, s91, v174
	ds_read_b128 v[188:191], v183
	ds_read_b128 v[192:195], v183 offset:1024
	ds_read_b128 v[208:211], v183 offset:2048
	ds_read_b128 v[214:217], v183 offset:3072
	s_add_u32 s48, s48, s94
	s_addc_u32 s49, s49, 0
	s_mov_b32 m0, s68
	v_lshl_add_u64 v[198:199], s[48:49], 0, v[132:133]
	ds_read_b128 v[218:221], v175 offset:32768
	ds_read_b128 v[222:225], v175 offset:33792
	ds_read_b128 v[226:229], v175 offset:34816
	ds_read_b128 v[230:233], v175 offset:35840
	ds_read_b128 v[234:237], v175 offset:36864
	ds_read_b128 v[238:241], v175 offset:37888
	ds_read_b128 v[242:245], v175 offset:38912
	ds_read_b128 v[246:249], v175 offset:39936
	global_load_lds_dwordx4 v[198:199], off
	v_lshl_add_u64 v[198:199], s[48:49], 0, v[134:135]
	s_mov_b32 m0, s69
	s_nop 0
	global_load_lds_dwordx4 v[198:199], off
	s_waitcnt vmcnt(8)
	s_waitcnt lgkmcnt(0)
	s_setprio 1
	s_barrier
	v_mfma_f32_16x16x32_bf16 v[124:127], v[144:147], v[218:221], v[124:127]
	v_mfma_f32_16x16x32_bf16 v[120:123], v[152:155], v[218:221], v[120:123]
	v_mfma_f32_16x16x32_bf16 v[108:111], v[144:147], v[226:229], v[108:111]
	v_mfma_f32_16x16x32_bf16 v[104:107], v[152:155], v[226:229], v[104:107]
	v_mfma_f32_16x16x32_bf16 v[92:95], v[144:147], v[234:237], v[92:95]
	v_mfma_f32_16x16x32_bf16 v[88:91], v[152:155], v[234:237], v[88:91]
	v_mfma_f32_16x16x32_bf16 v[76:79], v[144:147], v[242:245], v[76:79]
	v_mfma_f32_16x16x32_bf16 v[72:75], v[152:155], v[242:245], v[72:75]
	v_mfma_f32_16x16x32_bf16 v[124:127], v[148:151], v[222:225], v[124:127]
	v_mfma_f32_16x16x32_bf16 v[120:123], v[184:187], v[222:225], v[120:123]
	v_mfma_f32_16x16x32_bf16 v[108:111], v[148:151], v[230:233], v[108:111]
	v_mfma_f32_16x16x32_bf16 v[104:107], v[184:187], v[230:233], v[104:107]
	v_mfma_f32_16x16x32_bf16 v[92:95], v[148:151], v[238:241], v[92:95]
	v_mfma_f32_16x16x32_bf16 v[88:91], v[184:187], v[238:241], v[88:91]
	v_mfma_f32_16x16x32_bf16 v[76:79], v[148:151], v[246:249], v[76:79]
	v_mfma_f32_16x16x32_bf16 v[72:75], v[184:187], v[246:249], v[72:75]
	s_setprio 0
	s_setprio 1
	v_mfma_f32_16x16x32_bf16 v[116:119], v[188:191], v[218:221], v[116:119]
	v_mfma_f32_16x16x32_bf16 v[112:115], v[208:211], v[218:221], v[112:115]
	v_mfma_f32_16x16x32_bf16 v[100:103], v[188:191], v[226:229], v[100:103]
	v_mfma_f32_16x16x32_bf16 v[96:99], v[208:211], v[226:229], v[96:99]
	v_mfma_f32_16x16x32_bf16 v[84:87], v[188:191], v[234:237], v[84:87]
	v_mfma_f32_16x16x32_bf16 v[80:83], v[208:211], v[234:237], v[80:83]
	v_mfma_f32_16x16x32_bf16 v[68:71], v[188:191], v[242:245], v[68:71]
	v_mfma_f32_16x16x32_bf16 v[64:67], v[208:211], v[242:245], v[64:67]
	v_mfma_f32_16x16x32_bf16 v[116:119], v[192:195], v[222:225], v[116:119]
	v_mfma_f32_16x16x32_bf16 v[112:115], v[214:217], v[222:225], v[112:115]
	v_mfma_f32_16x16x32_bf16 v[100:103], v[192:195], v[230:233], v[100:103]
	v_mfma_f32_16x16x32_bf16 v[96:99], v[214:217], v[230:233], v[96:99]
	v_mfma_f32_16x16x32_bf16 v[84:87], v[192:195], v[238:241], v[84:87]
	v_mfma_f32_16x16x32_bf16 v[80:83], v[214:217], v[238:241], v[80:83]
	v_mfma_f32_16x16x32_bf16 v[68:71], v[192:195], v[246:249], v[68:71]
	v_mfma_f32_16x16x32_bf16 v[64:67], v[214:217], v[246:249], v[64:67]
	s_setprio 0
	s_barrier
; #define PG8_STAGE(bufoff, gbase, voff) do { _Pragma("unroll") for (int _i = 0; _i < 2; ++_i) \
;         __builtin_amdgcn_global_load_lds((const unsigned*)((const char*)(gbase) + (voff)[_i]), (PG8_LAS unsigned*)(lds + (bufoff) + ldsw + _i * 8192), 16, 0, 0); } while (0)
; #define PG8_LDA(dst, b, h) do { _Pragma("unroll") for (int m = 0; m < 4; ++m) _Pragma("unroll") for (int k = 0; k < 2; ++k) dst[m][k] = *(const PG8_LAS bf16x8*)(lds + PG8_SA(b, h) + aoff + m * 2048 + k * 1024); } while (0)
; #define PG8_MMA(ai, bj, At, Bt) do { __builtin_amdgcn_s_setprio(1); _Pragma("unroll") for (int m = 0; m < 4; ++m) _Pragma("unroll") for (int n = 0; n < 2; ++n) _Pragma("unroll") for (int k = 0; k < 2; ++k) \
;         acc[ai][bj][m][n] = __builtin_amdgcn_mfma_f32_16x16x32_bf16(Bt[n][k], At[m][k], acc[ai][bj][m][n], 0, 0, 0); __builtin_amdgcn_s_setprio(0); } while (0)
; #define PG8_WAIT_V(n) asm volatile("s_waitcnt vmcnt(" #n ")" ::: "memory")
; #define PG8_WAIT_L(n) asm volatile("s_waitcnt lgkmcnt(" #n ")" ::: "memory")
; #define PG8_BAR __builtin_amdgcn_s_barrier()
; #define PG8_SCHED __builtin_amdgcn_sched_barrier(0)
; template <class Epi, class Sched, bool ALIGN_EPI = false, bool SP2 = false>
; __device__ __forceinline__ void gemm_phase(PG8_LAS unsigned char* lds, const Gemm g, const Sched& S, const Epi& E, const int tid) {
;     ...
;             PG8_LDA(At, 1, 1); PG8_STAGE(PG8_SB(1, 0), b3, voffB); PG8_STAGE(PG8_SB(1, 1), b3 + hstep, voffB); PG8_STAGE(PG8_SA(1, 0), a3, voffA);
;             PG8_WAIT_V(8); PG8_WAIT_L(0); PG8_BAR; PG8_MMA(1, 0, At, B0); PG8_MMA(1, 1, At, B1); PG8_BAR; PG8_SCHED;
	s_add_i32 s48, s90, s65
	v_lshl_add_u64 v[156:157], v[156:157], 0, s[28:29]
	s_mov_b32 m0, s48
	ds_read_b128 v[218:221], v175 offset:49152
	ds_read_b128 v[222:225], v175 offset:50176
	ds_read_b128 v[226:229], v175 offset:51200
	ds_read_b128 v[230:233], v175 offset:52224
	ds_read_b128 v[234:237], v175 offset:53248
	ds_read_b128 v[238:241], v175 offset:54272
	ds_read_b128 v[242:245], v175 offset:55296
	ds_read_b128 v[246:249], v175 offset:56320
	global_load_lds_dwordx4 v[156:157], off
	v_lshl_add_u64 v[156:157], v[250:251], 0, s[28:29]
	s_add_i32 m0, s48, 0x2000
	s_add_i32 s48, s91, s65
	global_load_lds_dwordx4 v[156:157], off
	v_lshl_add_u64 v[156:157], v[178:179], 0, s[28:29]
	s_mov_b32 m0, s48
	s_nop 0
	global_load_lds_dwordx4 v[156:157], off
	v_lshl_add_u64 v[156:157], v[180:181], 0, s[28:29]
	s_add_i32 m0, s48, 0x2000
	s_nop 0
	global_load_lds_dwordx4 v[156:157], off
	v_lshl_add_u64 v[156:157], v[204:205], 0, s[28:29]
	s_mov_b32 m0, s70
	s_nop 0
	global_load_lds_dwordx4 v[156:157], off
	v_lshl_add_u64 v[156:157], v[196:197], 0, s[28:29]
	s_mov_b32 m0, s71
	s_nop 0
	global_load_lds_dwordx4 v[156:157], off
	s_waitcnt vmcnt(8)
	s_waitcnt lgkmcnt(0)
	s_setprio 1
	s_barrier
	v_mfma_f32_16x16x32_bf16 v[60:63], v[144:147], v[218:221], v[60:63]
	v_mfma_f32_16x16x32_bf16 v[56:59], v[152:155], v[218:221], v[56:59]
	v_mfma_f32_16x16x32_bf16 v[44:47], v[144:147], v[226:229], v[44:47]
	v_mfma_f32_16x16x32_bf16 v[40:43], v[152:155], v[226:229], v[40:43]
	v_mfma_f32_16x16x32_bf16 v[28:31], v[144:147], v[234:237], v[28:31]
	v_mfma_f32_16x16x32_bf16 v[24:27], v[152:155], v[234:237], v[24:27]
	v_mfma_f32_16x16x32_bf16 v[12:15], v[144:147], v[242:245], v[12:15]
	v_mfma_f32_16x16x32_bf16 v[8:11], v[152:155], v[242:245], v[8:11]
	v_mfma_f32_16x16x32_bf16 v[60:63], v[148:151], v[222:225], v[60:63]
	v_mfma_f32_16x16x32_bf16 v[56:59], v[184:187], v[222:225], v[56:59]
	v_mfma_f32_16x16x32_bf16 v[44:47], v[148:151], v[230:233], v[44:47]
	v_mfma_f32_16x16x32_bf16 v[40:43], v[184:187], v[230:233], v[40:43]
	v_mfma_f32_16x16x32_bf16 v[28:31], v[148:151], v[238:241], v[28:31]
	v_mfma_f32_16x16x32_bf16 v[24:27], v[184:187], v[238:241], v[24:27]
	v_mfma_f32_16x16x32_bf16 v[12:15], v[148:151], v[246:249], v[12:15]
	v_mfma_f32_16x16x32_bf16 v[8:11], v[184:187], v[246:249], v[8:11]
	s_setprio 0
	s_setprio 1
	v_mfma_f32_16x16x32_bf16 v[52:55], v[188:191], v[218:221], v[52:55]
	v_mfma_f32_16x16x32_bf16 v[48:51], v[208:211], v[218:221], v[48:51]
	v_mfma_f32_16x16x32_bf16 v[36:39], v[188:191], v[226:229], v[36:39]
	v_mfma_f32_16x16x32_bf16 v[32:35], v[208:211], v[226:229], v[32:35]
	v_mfma_f32_16x16x32_bf16 v[20:23], v[188:191], v[234:237], v[20:23]
	v_mfma_f32_16x16x32_bf16 v[16:19], v[208:211], v[234:237], v[16:19]
	v_mfma_f32_16x16x32_bf16 v[4:7], v[188:191], v[242:245], v[4:7]
	v_mfma_f32_16x16x32_bf16 v[0:3], v[208:211], v[242:245], v[0:3]
	v_mfma_f32_16x16x32_bf16 v[52:55], v[192:195], v[222:225], v[52:55]
	v_mfma_f32_16x16x32_bf16 v[48:51], v[214:217], v[222:225], v[48:51]
	v_mfma_f32_16x16x32_bf16 v[36:39], v[192:195], v[230:233], v[36:39]
	v_mfma_f32_16x16x32_bf16 v[32:35], v[214:217], v[230:233], v[32:35]
	v_mfma_f32_16x16x32_bf16 v[20:23], v[192:195], v[238:241], v[20:23]
	v_mfma_f32_16x16x32_bf16 v[16:19], v[214:217], v[238:241], v[16:19]
	v_mfma_f32_16x16x32_bf16 v[4:7], v[192:195], v[246:249], v[4:7]
	v_mfma_f32_16x16x32_bf16 v[0:3], v[214:217], v[246:249], v[0:3]
	s_setprio 0
	s_barrier
	s_add_u32 s44, s44, 0x100
	s_addc_u32 s45, s45, 0
	s_add_u32 s37, s37, 0x100
	s_addc_u32 s50, s50, 0
	s_cmp_ge_u32 s51, s80
	s_mov_b32 s48, s51
	s_cbranch_scc0 .LBB0_621
